# v11: v3 + removed the 24 back-to-back 's_setprio 0; s_setprio 1' pairs in the middle of the 32-MFMA blocks of the six GEMM K-loops
# baseline (speedup 1.0000x reference)
.LBB0_419:
	s_add_u32 s8, s0, 0xfffc0080
	s_addc_u32 s9, s1, -1
	s_add_i32 s58, 0, 0x10000
	s_cmp_eq_u32 s55, 12
	s_cselect_b32 s11, s34, s9
	s_cselect_b32 s10, s35, s8
	v_add_u32_e32 v140, s58, v143
	s_cselect_b32 s9, s36, s51
	s_cselect_b32 s8, s37, s49
	s_add_i32 s60, 0, 0x14000
	ds_read_b128 v[146:149], v140
	ds_read_b128 v[150:153], v140 offset:1024
	ds_read_b128 v[154:157], v140 offset:2048
	ds_read_b128 v[158:161], v140 offset:3072
	v_add_u32_e32 v140, s60, v143
	ds_read_b128 v[162:165], v140
	ds_read_b128 v[166:169], v140 offset:1024
	ds_read_b128 v[170:173], v140 offset:2048
	ds_read_b128 v[174:177], v140 offset:3072
	v_lshl_add_u64 v[140:141], s[0:1], 0, v[138:139]
	s_add_i32 m0, s17, 0xc000
	ds_read_b128 v[178:181], v145
	ds_read_b128 v[182:185], v145 offset:1024
	ds_read_b128 v[200:203], v145 offset:2048
	ds_read_b128 v[204:207], v145 offset:3072
	ds_read_b128 v[208:211], v145 offset:4096
	ds_read_b128 v[212:215], v145 offset:5120
	ds_read_b128 v[216:219], v145 offset:6144
	ds_read_b128 v[226:229], v145 offset:7168
	global_load_lds_dwordx4 v[140:141], off
	v_lshl_add_u64 v[140:141], s[0:1], 0, v[136:137]
	s_add_i32 m0, s17, 0xe000
	s_nop 0
	global_load_lds_dwordx4 v[140:141], off
	s_waitcnt vmcnt(8)
	s_waitcnt lgkmcnt(0)
	s_barrier
	s_setprio 1
	s_waitcnt lgkmcnt(0)
	v_mfma_f32_16x16x32_bf16 v[126:129], v[146:149], v[178:181], v[126:129]
	v_mfma_f32_16x16x32_bf16 v[118:121], v[154:157], v[178:181], v[118:121]
	v_mfma_f32_16x16x32_bf16 v[110:113], v[146:149], v[200:203], v[110:113]
	v_mfma_f32_16x16x32_bf16 v[102:105], v[154:157], v[200:203], v[102:105]
	v_mfma_f32_16x16x32_bf16 v[94:97], v[146:149], v[208:211], v[94:97]
	v_mfma_f32_16x16x32_bf16 v[86:89], v[154:157], v[208:211], v[86:89]
	v_mfma_f32_16x16x32_bf16 v[78:81], v[146:149], v[216:219], v[78:81]
	v_mfma_f32_16x16x32_bf16 v[70:73], v[154:157], v[216:219], v[70:73]
	v_mfma_f32_16x16x32_bf16 v[126:129], v[150:153], v[182:185], v[126:129]
	v_mfma_f32_16x16x32_bf16 v[118:121], v[158:161], v[182:185], v[118:121]
	v_mfma_f32_16x16x32_bf16 v[110:113], v[150:153], v[204:207], v[110:113]
	v_mfma_f32_16x16x32_bf16 v[102:105], v[158:161], v[204:207], v[102:105]
	v_mfma_f32_16x16x32_bf16 v[94:97], v[150:153], v[212:215], v[94:97]
	v_mfma_f32_16x16x32_bf16 v[86:89], v[158:161], v[212:215], v[86:89]
	v_mfma_f32_16x16x32_bf16 v[78:81], v[150:153], v[226:229], v[78:81]
	v_mfma_f32_16x16x32_bf16 v[70:73], v[158:161], v[226:229], v[70:73]
	v_mfma_f32_16x16x32_bf16 v[122:125], v[162:165], v[178:181], v[122:125]
	v_mfma_f32_16x16x32_bf16 v[114:117], v[170:173], v[178:181], v[114:117]
	v_mfma_f32_16x16x32_bf16 v[106:109], v[162:165], v[200:203], v[106:109]
	v_mfma_f32_16x16x32_bf16 v[98:101], v[170:173], v[200:203], v[98:101]
	v_mfma_f32_16x16x32_bf16 v[90:93], v[162:165], v[208:211], v[90:93]
	v_mfma_f32_16x16x32_bf16 v[82:85], v[170:173], v[208:211], v[82:85]
	v_mfma_f32_16x16x32_bf16 v[74:77], v[162:165], v[216:219], v[74:77]
	v_mfma_f32_16x16x32_bf16 v[66:69], v[170:173], v[216:219], v[66:69]
	v_mfma_f32_16x16x32_bf16 v[122:125], v[166:169], v[182:185], v[122:125]
	v_mfma_f32_16x16x32_bf16 v[114:117], v[174:177], v[182:185], v[114:117]
	v_mfma_f32_16x16x32_bf16 v[106:109], v[166:169], v[204:207], v[106:109]
	v_mfma_f32_16x16x32_bf16 v[98:101], v[174:177], v[204:207], v[98:101]
	v_mfma_f32_16x16x32_bf16 v[90:93], v[166:169], v[212:215], v[90:93]
	v_mfma_f32_16x16x32_bf16 v[82:85], v[174:177], v[212:215], v[82:85]
	v_mfma_f32_16x16x32_bf16 v[74:77], v[166:169], v[226:229], v[74:77]
	v_mfma_f32_16x16x32_bf16 v[66:69], v[174:177], v[226:229], v[66:69]
	s_setprio 0
	s_barrier
	s_add_i32 s58, s58, s16
	v_lshl_add_u64 v[140:141], s[8:9], 0, v[188:189]
	s_mov_b32 m0, s58
	ds_read_b128 v[178:181], v145 offset:16384
	ds_read_b128 v[182:185], v145 offset:17408
	ds_read_b128 v[200:203], v145 offset:18432
	ds_read_b128 v[204:207], v145 offset:19456
	ds_read_b128 v[208:211], v145 offset:20480
	ds_read_b128 v[212:215], v145 offset:21504
	ds_read_b128 v[216:219], v145 offset:22528
	ds_read_b128 v[226:229], v145 offset:23552
	global_load_lds_dwordx4 v[140:141], off
	s_add_i32 m0, s58, 0x2000
	s_add_u32 s58, s8, 0x40000
	v_lshl_add_u64 v[230:231], s[8:9], 0, v[130:131]
	s_addc_u32 s59, s9, 0
	s_add_i32 s60, s60, s16
	global_load_lds_dwordx4 v[230:231], off
	v_lshl_add_u64 v[232:233], s[58:59], 0, v[188:189]
	s_mov_b32 m0, s60
	v_lshl_add_u64 v[234:235], s[10:11], 0, v[132:133]
	global_load_lds_dwordx4 v[232:233], off
	v_lshl_add_u64 v[232:233], s[58:59], 0, v[130:131]
	s_add_i32 m0, s60, 0x2000
	s_nop 0
	global_load_lds_dwordx4 v[232:233], off
	v_lshl_add_u64 v[232:233], s[10:11], 0, v[134:135]
	s_mov_b32 m0, s17
	s_nop 0
	global_load_lds_dwordx4 v[232:233], off
	s_mov_b32 m0, s18
	s_nop 0
	global_load_lds_dwordx4 v[234:235], off
	s_waitcnt vmcnt(8)
	s_waitcnt lgkmcnt(0)
	s_barrier
	s_setprio 1
	s_waitcnt lgkmcnt(0)
	v_mfma_f32_16x16x32_bf16 v[62:65], v[146:149], v[178:181], v[62:65]
	v_mfma_f32_16x16x32_bf16 v[54:57], v[154:157], v[178:181], v[54:57]
	v_mfma_f32_16x16x32_bf16 v[46:49], v[146:149], v[200:203], v[46:49]
	v_mfma_f32_16x16x32_bf16 v[38:41], v[154:157], v[200:203], v[38:41]
	v_mfma_f32_16x16x32_bf16 v[30:33], v[146:149], v[208:211], v[30:33]
	v_mfma_f32_16x16x32_bf16 v[22:25], v[154:157], v[208:211], v[22:25]
	v_mfma_f32_16x16x32_bf16 v[14:17], v[146:149], v[216:219], v[14:17]
	v_mfma_f32_16x16x32_bf16 v[6:9], v[154:157], v[216:219], v[6:9]
	v_mfma_f32_16x16x32_bf16 v[62:65], v[150:153], v[182:185], v[62:65]
	v_mfma_f32_16x16x32_bf16 v[54:57], v[158:161], v[182:185], v[54:57]
	v_mfma_f32_16x16x32_bf16 v[46:49], v[150:153], v[204:207], v[46:49]
	v_mfma_f32_16x16x32_bf16 v[38:41], v[158:161], v[204:207], v[38:41]
	v_mfma_f32_16x16x32_bf16 v[30:33], v[150:153], v[212:215], v[30:33]
	v_mfma_f32_16x16x32_bf16 v[22:25], v[158:161], v[212:215], v[22:25]
	v_mfma_f32_16x16x32_bf16 v[14:17], v[150:153], v[226:229], v[14:17]
	v_mfma_f32_16x16x32_bf16 v[6:9], v[158:161], v[226:229], v[6:9]
	v_mfma_f32_16x16x32_bf16 v[58:61], v[162:165], v[178:181], v[58:61]
	v_mfma_f32_16x16x32_bf16 v[50:53], v[170:173], v[178:181], v[50:53]
	v_mfma_f32_16x16x32_bf16 v[42:45], v[162:165], v[200:203], v[42:45]
	v_mfma_f32_16x16x32_bf16 v[34:37], v[170:173], v[200:203], v[34:37]
	v_mfma_f32_16x16x32_bf16 v[26:29], v[162:165], v[208:211], v[26:29]
	v_mfma_f32_16x16x32_bf16 v[18:21], v[170:173], v[208:211], v[18:21]
	v_mfma_f32_16x16x32_bf16 v[10:13], v[162:165], v[216:219], v[10:13]
	v_mfma_f32_16x16x32_bf16 v[2:5], v[170:173], v[216:219], v[2:5]
	v_mfma_f32_16x16x32_bf16 v[58:61], v[166:169], v[182:185], v[58:61]
	v_mfma_f32_16x16x32_bf16 v[50:53], v[174:177], v[182:185], v[50:53]
	v_mfma_f32_16x16x32_bf16 v[42:45], v[166:169], v[204:207], v[42:45]
	v_mfma_f32_16x16x32_bf16 v[34:37], v[174:177], v[204:207], v[34:37]
	v_mfma_f32_16x16x32_bf16 v[26:29], v[166:169], v[212:215], v[26:29]
	v_mfma_f32_16x16x32_bf16 v[18:21], v[174:177], v[212:215], v[18:21]
	v_mfma_f32_16x16x32_bf16 v[10:13], v[166:169], v[226:229], v[10:13]
	v_mfma_f32_16x16x32_bf16 v[2:5], v[174:177], v[226:229], v[2:5]
	s_setprio 0
	s_barrier
	s_add_i32 s58, 0, 0x18000
	s_add_i32 s59, 0, 0x1c000
	v_add_u32_e32 v158, s58, v143
	v_add_u32_e32 v174, s59, v143
	ds_read_b128 v[146:149], v158
	ds_read_b128 v[150:153], v158 offset:1024
	ds_read_b128 v[154:157], v158 offset:2048
	ds_read_b128 v[158:161], v158 offset:3072
	ds_read_b128 v[162:165], v174
	ds_read_b128 v[166:169], v174 offset:1024
	ds_read_b128 v[170:173], v174 offset:2048
	ds_read_b128 v[174:177], v174 offset:3072
	s_add_u32 s10, s10, 0x40000
	s_addc_u32 s11, s11, 0
	s_mov_b32 m0, s19
	v_lshl_add_u64 v[236:237], s[10:11], 0, v[134:135]
	ds_read_b128 v[178:181], v145 offset:32768
	ds_read_b128 v[182:185], v145 offset:33792
	ds_read_b128 v[200:203], v145 offset:34816
	ds_read_b128 v[204:207], v145 offset:35840
	ds_read_b128 v[208:211], v145 offset:36864
	ds_read_b128 v[212:215], v145 offset:37888
	ds_read_b128 v[216:219], v145 offset:38912
	ds_read_b128 v[226:229], v145 offset:39936
	global_load_lds_dwordx4 v[236:237], off
	v_lshl_add_u64 v[236:237], s[10:11], 0, v[132:133]
	s_mov_b32 m0, s20
	s_nop 0
	global_load_lds_dwordx4 v[236:237], off
	s_waitcnt vmcnt(8)
	s_waitcnt lgkmcnt(0)
	s_barrier
	s_setprio 1
	s_waitcnt lgkmcnt(0)
	v_mfma_f32_16x16x32_bf16 v[126:129], v[146:149], v[178:181], v[126:129]
	v_mfma_f32_16x16x32_bf16 v[118:121], v[154:157], v[178:181], v[118:121]
	v_mfma_f32_16x16x32_bf16 v[110:113], v[146:149], v[200:203], v[110:113]
	v_mfma_f32_16x16x32_bf16 v[102:105], v[154:157], v[200:203], v[102:105]
	v_mfma_f32_16x16x32_bf16 v[94:97], v[146:149], v[208:211], v[94:97]
	v_mfma_f32_16x16x32_bf16 v[86:89], v[154:157], v[208:211], v[86:89]
	v_mfma_f32_16x16x32_bf16 v[78:81], v[146:149], v[216:219], v[78:81]
	v_mfma_f32_16x16x32_bf16 v[70:73], v[154:157], v[216:219], v[70:73]
	v_mfma_f32_16x16x32_bf16 v[126:129], v[150:153], v[182:185], v[126:129]
	v_mfma_f32_16x16x32_bf16 v[118:121], v[158:161], v[182:185], v[118:121]
	v_mfma_f32_16x16x32_bf16 v[110:113], v[150:153], v[204:207], v[110:113]
	v_mfma_f32_16x16x32_bf16 v[102:105], v[158:161], v[204:207], v[102:105]
	v_mfma_f32_16x16x32_bf16 v[94:97], v[150:153], v[212:215], v[94:97]
	v_mfma_f32_16x16x32_bf16 v[86:89], v[158:161], v[212:215], v[86:89]
	v_mfma_f32_16x16x32_bf16 v[78:81], v[150:153], v[226:229], v[78:81]
	v_mfma_f32_16x16x32_bf16 v[70:73], v[158:161], v[226:229], v[70:73]
	v_mfma_f32_16x16x32_bf16 v[122:125], v[162:165], v[178:181], v[122:125]
	v_mfma_f32_16x16x32_bf16 v[114:117], v[170:173], v[178:181], v[114:117]
	v_mfma_f32_16x16x32_bf16 v[106:109], v[162:165], v[200:203], v[106:109]
	v_mfma_f32_16x16x32_bf16 v[98:101], v[170:173], v[200:203], v[98:101]
	v_mfma_f32_16x16x32_bf16 v[90:93], v[162:165], v[208:211], v[90:93]
	v_mfma_f32_16x16x32_bf16 v[82:85], v[170:173], v[208:211], v[82:85]
	v_mfma_f32_16x16x32_bf16 v[74:77], v[162:165], v[216:219], v[74:77]
	v_mfma_f32_16x16x32_bf16 v[66:69], v[170:173], v[216:219], v[66:69]
	v_mfma_f32_16x16x32_bf16 v[122:125], v[166:169], v[182:185], v[122:125]
	v_mfma_f32_16x16x32_bf16 v[114:117], v[174:177], v[182:185], v[114:117]
	v_mfma_f32_16x16x32_bf16 v[106:109], v[166:169], v[204:207], v[106:109]
	v_mfma_f32_16x16x32_bf16 v[98:101], v[174:177], v[204:207], v[98:101]
	v_mfma_f32_16x16x32_bf16 v[90:93], v[166:169], v[212:215], v[90:93]
	v_mfma_f32_16x16x32_bf16 v[82:85], v[174:177], v[212:215], v[82:85]
	v_mfma_f32_16x16x32_bf16 v[74:77], v[166:169], v[226:229], v[74:77]
	v_mfma_f32_16x16x32_bf16 v[66:69], v[174:177], v[226:229], v[66:69]
	s_setprio 0
	s_barrier
	s_add_i32 s10, s58, s16
	v_lshl_add_u64 v[140:141], v[140:141], 0, s[4:5]
	s_mov_b32 m0, s10
	ds_read_b128 v[178:181], v145 offset:49152
	ds_read_b128 v[182:185], v145 offset:50176
	ds_read_b128 v[200:203], v145 offset:51200
	ds_read_b128 v[204:207], v145 offset:52224
	ds_read_b128 v[208:211], v145 offset:53248
	ds_read_b128 v[212:215], v145 offset:54272
	ds_read_b128 v[216:219], v145 offset:55296
	ds_read_b128 v[226:229], v145 offset:56320
	global_load_lds_dwordx4 v[140:141], off
	s_add_i32 m0, s10, 0x2000
	s_add_u32 s8, s8, 0x40080
	v_lshl_add_u64 v[140:141], v[230:231], 0, s[4:5]
	s_addc_u32 s9, s9, 0
	s_add_i32 s10, s59, s16
	global_load_lds_dwordx4 v[140:141], off
	v_lshl_add_u64 v[140:141], s[8:9], 0, v[188:189]
	s_mov_b32 m0, s10
	s_nop 0
	global_load_lds_dwordx4 v[140:141], off
	v_lshl_add_u64 v[140:141], s[8:9], 0, v[130:131]
	s_add_i32 m0, s10, 0x2000
	s_nop 0
	global_load_lds_dwordx4 v[140:141], off
	v_lshl_add_u64 v[140:141], v[232:233], 0, s[4:5]
	s_mov_b32 m0, s21
	s_nop 0
	global_load_lds_dwordx4 v[140:141], off
	v_lshl_add_u64 v[140:141], v[234:235], 0, s[4:5]
	s_mov_b32 m0, s24
	s_nop 0
	global_load_lds_dwordx4 v[140:141], off
	s_waitcnt vmcnt(8)
	s_waitcnt lgkmcnt(0)
	s_barrier
	s_setprio 1
	s_waitcnt lgkmcnt(0)
	v_mfma_f32_16x16x32_bf16 v[62:65], v[146:149], v[178:181], v[62:65]
	v_mfma_f32_16x16x32_bf16 v[54:57], v[154:157], v[178:181], v[54:57]
	v_mfma_f32_16x16x32_bf16 v[46:49], v[146:149], v[200:203], v[46:49]
	v_mfma_f32_16x16x32_bf16 v[38:41], v[154:157], v[200:203], v[38:41]
	v_mfma_f32_16x16x32_bf16 v[30:33], v[146:149], v[208:211], v[30:33]
	v_mfma_f32_16x16x32_bf16 v[22:25], v[154:157], v[208:211], v[22:25]
	v_mfma_f32_16x16x32_bf16 v[14:17], v[146:149], v[216:219], v[14:17]
	v_mfma_f32_16x16x32_bf16 v[6:9], v[154:157], v[216:219], v[6:9]
	v_mfma_f32_16x16x32_bf16 v[62:65], v[150:153], v[182:185], v[62:65]
	v_mfma_f32_16x16x32_bf16 v[54:57], v[158:161], v[182:185], v[54:57]
	v_mfma_f32_16x16x32_bf16 v[46:49], v[150:153], v[204:207], v[46:49]
	v_mfma_f32_16x16x32_bf16 v[38:41], v[158:161], v[204:207], v[38:41]
	v_mfma_f32_16x16x32_bf16 v[30:33], v[150:153], v[212:215], v[30:33]
	v_mfma_f32_16x16x32_bf16 v[22:25], v[158:161], v[212:215], v[22:25]
	v_mfma_f32_16x16x32_bf16 v[14:17], v[150:153], v[226:229], v[14:17]
	v_mfma_f32_16x16x32_bf16 v[6:9], v[158:161], v[226:229], v[6:9]
	v_mfma_f32_16x16x32_bf16 v[58:61], v[162:165], v[178:181], v[58:61]
	v_mfma_f32_16x16x32_bf16 v[50:53], v[170:173], v[178:181], v[50:53]
	v_mfma_f32_16x16x32_bf16 v[42:45], v[162:165], v[200:203], v[42:45]
	v_mfma_f32_16x16x32_bf16 v[34:37], v[170:173], v[200:203], v[34:37]
	v_mfma_f32_16x16x32_bf16 v[26:29], v[162:165], v[208:211], v[26:29]
	v_mfma_f32_16x16x32_bf16 v[18:21], v[170:173], v[208:211], v[18:21]
	v_mfma_f32_16x16x32_bf16 v[10:13], v[162:165], v[216:219], v[10:13]
	v_mfma_f32_16x16x32_bf16 v[2:5], v[170:173], v[216:219], v[2:5]
	v_mfma_f32_16x16x32_bf16 v[58:61], v[166:169], v[182:185], v[58:61]
	v_mfma_f32_16x16x32_bf16 v[50:53], v[174:177], v[182:185], v[50:53]
	v_mfma_f32_16x16x32_bf16 v[42:45], v[166:169], v[204:207], v[42:45]
	v_mfma_f32_16x16x32_bf16 v[34:37], v[174:177], v[204:207], v[34:37]
	v_mfma_f32_16x16x32_bf16 v[26:29], v[166:169], v[212:215], v[26:29]
	v_mfma_f32_16x16x32_bf16 v[18:21], v[174:177], v[212:215], v[18:21]
	v_mfma_f32_16x16x32_bf16 v[10:13], v[166:169], v[226:229], v[10:13]
	v_mfma_f32_16x16x32_bf16 v[2:5], v[174:177], v[226:229], v[2:5]
	s_setprio 0
	s_barrier
	s_add_i32 s55, s55, 2
	s_add_u32 s49, s49, 0x100
	s_addc_u32 s51, s51, 0
	s_add_u32 s0, s0, 0x100
	s_addc_u32 s1, s1, 0
	s_cmp_gt_u32 s55, 13
	s_cbranch_scc0 .LBB0_419
	s_and_b64 vcc, exec, s[44:45]
	s_cbranch_vccz .LBB0_422
	s_barrier

.LBB0_528:
	s_add_u32 s10, s70, s8
	s_addc_u32 s11, s71, s9
	s_add_u32 s10, s10, 0x100
	s_addc_u32 s11, s11, 0
	s_add_u32 s83, s80, s8
	s_addc_u32 s84, s81, s9
	s_add_i32 s85, 0, 0x10000
	s_cmpk_eq_i32 s8, 0x1500
	s_cselect_b32 s13, s1, s11
	s_cselect_b32 s12, s0, s10
	s_cselect_b32 s11, s45, s84
	s_cselect_b32 s10, s44, s83
	s_add_i32 s83, 0, 0x14000
	v_add_u32_e32 v154, s85, v140
	v_add_u32_e32 v172, s83, v140
	ds_read_b128 v[142:145], v154
	ds_read_b128 v[146:149], v154 offset:1024
	ds_read_b128 v[150:153], v154 offset:2048
	ds_read_b128 v[154:157], v154 offset:3072
	ds_read_b128 v[158:161], v172
	ds_read_b128 v[162:165], v172 offset:1024
	ds_read_b128 v[168:171], v172 offset:2048
	ds_read_b128 v[172:175], v172 offset:3072
	v_lshl_add_u64 v[184:185], v[138:139], 0, s[8:9]
	s_add_i32 m0, s36, 0xc000
	ds_read_b128 v[176:179], v141
	ds_read_b128 v[180:183], v141 offset:1024
	ds_read_b128 v[202:205], v141 offset:2048
	ds_read_b128 v[206:209], v141 offset:3072
	ds_read_b128 v[210:213], v141 offset:4096
	ds_read_b128 v[216:219], v141 offset:5120
	ds_read_b128 v[226:229], v141 offset:6144
	ds_read_b128 v[230:233], v141 offset:7168
	global_load_lds_dwordx4 v[184:185], off
	v_lshl_add_u64 v[184:185], v[136:137], 0, s[8:9]
	s_add_i32 m0, s36, 0xe000
	s_nop 0
	global_load_lds_dwordx4 v[184:185], off
	s_waitcnt vmcnt(8)
	s_waitcnt lgkmcnt(0)
	s_barrier
	s_setprio 1
	s_waitcnt lgkmcnt(0)
	v_mfma_f32_16x16x32_bf16 v[66:69], v[142:145], v[176:179], v[66:69]
	v_mfma_f32_16x16x32_bf16 v[34:37], v[150:153], v[176:179], v[34:37]
	v_mfma_f32_16x16x32_bf16 v[78:81], v[142:145], v[202:205], v[78:81]
	v_mfma_f32_16x16x32_bf16 v[46:49], v[150:153], v[202:205], v[46:49]
	v_mfma_f32_16x16x32_bf16 v[106:109], v[142:145], v[210:213], v[106:109]
	v_mfma_f32_16x16x32_bf16 v[62:65], v[150:153], v[210:213], v[62:65]
	v_mfma_f32_16x16x32_bf16 v[118:121], v[142:145], v[226:229], v[118:121]
	v_mfma_f32_16x16x32_bf16 v[74:77], v[150:153], v[226:229], v[74:77]
	v_mfma_f32_16x16x32_bf16 v[66:69], v[146:149], v[180:183], v[66:69]
	v_mfma_f32_16x16x32_bf16 v[34:37], v[154:157], v[180:183], v[34:37]
	v_mfma_f32_16x16x32_bf16 v[78:81], v[146:149], v[206:209], v[78:81]
	v_mfma_f32_16x16x32_bf16 v[46:49], v[154:157], v[206:209], v[46:49]
	v_mfma_f32_16x16x32_bf16 v[106:109], v[146:149], v[216:219], v[106:109]
	v_mfma_f32_16x16x32_bf16 v[62:65], v[154:157], v[216:219], v[62:65]
	v_mfma_f32_16x16x32_bf16 v[118:121], v[146:149], v[230:233], v[118:121]
	v_mfma_f32_16x16x32_bf16 v[74:77], v[154:157], v[230:233], v[74:77]
	v_mfma_f32_16x16x32_bf16 v[14:17], v[158:161], v[176:179], v[14:17]
	v_mfma_f32_16x16x32_bf16 v[2:5], v[168:171], v[176:179], v[2:5]
	v_mfma_f32_16x16x32_bf16 v[22:25], v[158:161], v[202:205], v[22:25]
	v_mfma_f32_16x16x32_bf16 v[6:9], v[168:171], v[202:205], v[6:9]
	v_mfma_f32_16x16x32_bf16 v[30:33], v[158:161], v[210:213], v[30:33]
	v_mfma_f32_16x16x32_bf16 v[10:13], v[168:171], v[210:213], v[10:13]
	v_mfma_f32_16x16x32_bf16 v[42:45], v[158:161], v[226:229], v[42:45]
	v_mfma_f32_16x16x32_bf16 v[18:21], v[168:171], v[226:229], v[18:21]
	v_mfma_f32_16x16x32_bf16 v[14:17], v[162:165], v[180:183], v[14:17]
	v_mfma_f32_16x16x32_bf16 v[2:5], v[172:175], v[180:183], v[2:5]
	v_mfma_f32_16x16x32_bf16 v[22:25], v[162:165], v[206:209], v[22:25]
	v_mfma_f32_16x16x32_bf16 v[6:9], v[172:175], v[206:209], v[6:9]
	v_mfma_f32_16x16x32_bf16 v[30:33], v[162:165], v[216:219], v[30:33]
	v_mfma_f32_16x16x32_bf16 v[10:13], v[172:175], v[216:219], v[10:13]
	v_mfma_f32_16x16x32_bf16 v[42:45], v[162:165], v[230:233], v[42:45]
	v_mfma_f32_16x16x32_bf16 v[18:21], v[172:175], v[230:233], v[18:21]
	s_setprio 0
	s_barrier
	s_add_i32 s84, s85, s24
	v_lshl_add_u64 v[184:185], s[10:11], 0, v[188:189]
	s_mov_b32 m0, s84
	ds_read_b128 v[176:179], v141 offset:16384
	ds_read_b128 v[180:183], v141 offset:17408
	ds_read_b128 v[202:205], v141 offset:18432
	ds_read_b128 v[206:209], v141 offset:19456
	ds_read_b128 v[210:213], v141 offset:20480
	ds_read_b128 v[216:219], v141 offset:21504
	ds_read_b128 v[226:229], v141 offset:22528
	ds_read_b128 v[230:233], v141 offset:23552
	global_load_lds_dwordx4 v[184:185], off
	s_add_i32 m0, s84, 0x2000
	s_add_u32 s84, s10, 0xb0000
	v_lshl_add_u64 v[234:235], s[10:11], 0, v[130:131]
	s_addc_u32 s85, s11, 0
	s_add_i32 s83, s83, s24
	global_load_lds_dwordx4 v[234:235], off
	v_lshl_add_u64 v[236:237], s[84:85], 0, v[188:189]
	s_mov_b32 m0, s83
	v_lshl_add_u64 v[238:239], s[12:13], 0, v[130:131]
	global_load_lds_dwordx4 v[236:237], off
	v_lshl_add_u64 v[236:237], s[84:85], 0, v[130:131]
	s_add_i32 m0, s83, 0x2000
	s_nop 0
	global_load_lds_dwordx4 v[236:237], off
	v_lshl_add_u64 v[236:237], s[12:13], 0, v[188:189]
	s_mov_b32 m0, s36
	s_nop 0
	global_load_lds_dwordx4 v[236:237], off
	s_mov_b32 m0, s37
	s_nop 0
	global_load_lds_dwordx4 v[238:239], off
	s_waitcnt vmcnt(8)
	s_waitcnt lgkmcnt(0)
	s_barrier
	s_setprio 1
	s_waitcnt lgkmcnt(0)
	v_mfma_f32_16x16x32_bf16 v[126:129], v[142:145], v[176:179], v[126:129]
	v_mfma_f32_16x16x32_bf16 v[98:101], v[150:153], v[176:179], v[98:101]
	v_mfma_f32_16x16x32_bf16 v[122:125], v[142:145], v[202:205], v[122:125]
	v_mfma_f32_16x16x32_bf16 v[114:117], v[150:153], v[202:205], v[114:117]
	v_mfma_f32_16x16x32_bf16 v[110:113], v[142:145], v[210:213], v[110:113]
	v_mfma_f32_16x16x32_bf16 v[102:105], v[150:153], v[210:213], v[102:105]
	v_mfma_f32_16x16x32_bf16 v[94:97], v[142:145], v[226:229], v[94:97]
	v_mfma_f32_16x16x32_bf16 v[90:93], v[150:153], v[226:229], v[90:93]
	v_mfma_f32_16x16x32_bf16 v[126:129], v[146:149], v[180:183], v[126:129]
	v_mfma_f32_16x16x32_bf16 v[98:101], v[154:157], v[180:183], v[98:101]
	v_mfma_f32_16x16x32_bf16 v[122:125], v[146:149], v[206:209], v[122:125]
	v_mfma_f32_16x16x32_bf16 v[114:117], v[154:157], v[206:209], v[114:117]
	v_mfma_f32_16x16x32_bf16 v[110:113], v[146:149], v[216:219], v[110:113]
	v_mfma_f32_16x16x32_bf16 v[102:105], v[154:157], v[216:219], v[102:105]
	v_mfma_f32_16x16x32_bf16 v[94:97], v[146:149], v[230:233], v[94:97]
	v_mfma_f32_16x16x32_bf16 v[90:93], v[154:157], v[230:233], v[90:93]
	v_mfma_f32_16x16x32_bf16 v[58:61], v[158:161], v[176:179], v[58:61]
	v_mfma_f32_16x16x32_bf16 v[26:29], v[168:171], v[176:179], v[26:29]
	v_mfma_f32_16x16x32_bf16 v[70:73], v[158:161], v[202:205], v[70:73]
	v_mfma_f32_16x16x32_bf16 v[38:41], v[168:171], v[202:205], v[38:41]
	v_mfma_f32_16x16x32_bf16 v[86:89], v[158:161], v[210:213], v[86:89]
	v_mfma_f32_16x16x32_bf16 v[54:57], v[168:171], v[210:213], v[54:57]
	v_mfma_f32_16x16x32_bf16 v[82:85], v[158:161], v[226:229], v[82:85]
	v_mfma_f32_16x16x32_bf16 v[50:53], v[168:171], v[226:229], v[50:53]
	v_mfma_f32_16x16x32_bf16 v[58:61], v[162:165], v[180:183], v[58:61]
	v_mfma_f32_16x16x32_bf16 v[26:29], v[172:175], v[180:183], v[26:29]
	v_mfma_f32_16x16x32_bf16 v[70:73], v[162:165], v[206:209], v[70:73]
	v_mfma_f32_16x16x32_bf16 v[38:41], v[172:175], v[206:209], v[38:41]
	v_mfma_f32_16x16x32_bf16 v[86:89], v[162:165], v[216:219], v[86:89]
	v_mfma_f32_16x16x32_bf16 v[54:57], v[172:175], v[216:219], v[54:57]
	v_mfma_f32_16x16x32_bf16 v[82:85], v[162:165], v[230:233], v[82:85]
	v_mfma_f32_16x16x32_bf16 v[50:53], v[172:175], v[230:233], v[50:53]
	s_setprio 0
	s_barrier
	s_add_i32 s83, 0, 0x18000
	s_add_i32 s84, 0, 0x1c000
	v_add_u32_e32 v154, s83, v140
	v_add_u32_e32 v172, s84, v140
	ds_read_b128 v[142:145], v154
	ds_read_b128 v[146:149], v154 offset:1024
	ds_read_b128 v[150:153], v154 offset:2048
	ds_read_b128 v[154:157], v154 offset:3072
	ds_read_b128 v[158:161], v172
	ds_read_b128 v[162:165], v172 offset:1024
	ds_read_b128 v[168:171], v172 offset:2048
	ds_read_b128 v[172:175], v172 offset:3072
	s_add_u32 s12, s12, 0xb0000
	s_addc_u32 s13, s13, 0
	s_mov_b32 m0, s54
	v_lshl_add_u64 v[240:241], s[12:13], 0, v[188:189]
	ds_read_b128 v[176:179], v141 offset:32768
	ds_read_b128 v[180:183], v141 offset:33792
	ds_read_b128 v[202:205], v141 offset:34816
	ds_read_b128 v[206:209], v141 offset:35840
	ds_read_b128 v[210:213], v141 offset:36864
	ds_read_b128 v[216:219], v141 offset:37888
	ds_read_b128 v[226:229], v141 offset:38912
	ds_read_b128 v[230:233], v141 offset:39936
	global_load_lds_dwordx4 v[240:241], off
	v_lshl_add_u64 v[240:241], s[12:13], 0, v[130:131]
	s_mov_b32 m0, s55
	s_nop 0
	global_load_lds_dwordx4 v[240:241], off
	s_waitcnt vmcnt(8)
	s_waitcnt lgkmcnt(0)
	s_barrier
	s_setprio 1
	s_waitcnt lgkmcnt(0)
	v_mfma_f32_16x16x32_bf16 v[66:69], v[142:145], v[176:179], v[66:69]
	v_mfma_f32_16x16x32_bf16 v[34:37], v[150:153], v[176:179], v[34:37]
	v_mfma_f32_16x16x32_bf16 v[78:81], v[142:145], v[202:205], v[78:81]
	v_mfma_f32_16x16x32_bf16 v[46:49], v[150:153], v[202:205], v[46:49]
	v_mfma_f32_16x16x32_bf16 v[106:109], v[142:145], v[210:213], v[106:109]
	v_mfma_f32_16x16x32_bf16 v[62:65], v[150:153], v[210:213], v[62:65]
	v_mfma_f32_16x16x32_bf16 v[118:121], v[142:145], v[226:229], v[118:121]
	v_mfma_f32_16x16x32_bf16 v[74:77], v[150:153], v[226:229], v[74:77]
	v_mfma_f32_16x16x32_bf16 v[66:69], v[146:149], v[180:183], v[66:69]
	v_mfma_f32_16x16x32_bf16 v[34:37], v[154:157], v[180:183], v[34:37]
	v_mfma_f32_16x16x32_bf16 v[78:81], v[146:149], v[206:209], v[78:81]
	v_mfma_f32_16x16x32_bf16 v[46:49], v[154:157], v[206:209], v[46:49]
	v_mfma_f32_16x16x32_bf16 v[106:109], v[146:149], v[216:219], v[106:109]
	v_mfma_f32_16x16x32_bf16 v[62:65], v[154:157], v[216:219], v[62:65]
	v_mfma_f32_16x16x32_bf16 v[118:121], v[146:149], v[230:233], v[118:121]
	v_mfma_f32_16x16x32_bf16 v[74:77], v[154:157], v[230:233], v[74:77]
	v_mfma_f32_16x16x32_bf16 v[14:17], v[158:161], v[176:179], v[14:17]
	v_mfma_f32_16x16x32_bf16 v[2:5], v[168:171], v[176:179], v[2:5]
	v_mfma_f32_16x16x32_bf16 v[22:25], v[158:161], v[202:205], v[22:25]
	v_mfma_f32_16x16x32_bf16 v[6:9], v[168:171], v[202:205], v[6:9]
	v_mfma_f32_16x16x32_bf16 v[30:33], v[158:161], v[210:213], v[30:33]
	v_mfma_f32_16x16x32_bf16 v[10:13], v[168:171], v[210:213], v[10:13]
	v_mfma_f32_16x16x32_bf16 v[42:45], v[158:161], v[226:229], v[42:45]
	v_mfma_f32_16x16x32_bf16 v[18:21], v[168:171], v[226:229], v[18:21]
	v_mfma_f32_16x16x32_bf16 v[14:17], v[162:165], v[180:183], v[14:17]
	v_mfma_f32_16x16x32_bf16 v[2:5], v[172:175], v[180:183], v[2:5]
	v_mfma_f32_16x16x32_bf16 v[22:25], v[162:165], v[206:209], v[22:25]
	v_mfma_f32_16x16x32_bf16 v[6:9], v[172:175], v[206:209], v[6:9]
	v_mfma_f32_16x16x32_bf16 v[30:33], v[162:165], v[216:219], v[30:33]
	v_mfma_f32_16x16x32_bf16 v[10:13], v[172:175], v[216:219], v[10:13]
	v_mfma_f32_16x16x32_bf16 v[42:45], v[162:165], v[230:233], v[42:45]
	v_mfma_f32_16x16x32_bf16 v[18:21], v[172:175], v[230:233], v[18:21]
	s_setprio 0
	s_barrier
	s_add_i32 s12, s83, s24
	v_lshl_add_u64 v[184:185], v[184:185], 0, s[4:5]
	s_mov_b32 m0, s12
	ds_read_b128 v[176:179], v141 offset:49152
	ds_read_b128 v[180:183], v141 offset:50176
	ds_read_b128 v[202:205], v141 offset:51200
	ds_read_b128 v[206:209], v141 offset:52224
	ds_read_b128 v[210:213], v141 offset:53248
	ds_read_b128 v[216:219], v141 offset:54272
	ds_read_b128 v[226:229], v141 offset:55296
	ds_read_b128 v[230:233], v141 offset:56320
	global_load_lds_dwordx4 v[184:185], off
	s_add_i32 m0, s12, 0x2000
	s_add_u32 s10, s10, 0xb0080
	v_lshl_add_u64 v[184:185], v[234:235], 0, s[4:5]
	s_addc_u32 s11, s11, 0
	s_add_i32 s12, s84, s24
	global_load_lds_dwordx4 v[184:185], off
	v_lshl_add_u64 v[184:185], s[10:11], 0, v[188:189]
	s_mov_b32 m0, s12
	s_nop 0
	global_load_lds_dwordx4 v[184:185], off
	v_lshl_add_u64 v[184:185], s[10:11], 0, v[130:131]
	s_add_i32 m0, s12, 0x2000
	s_nop 0
	global_load_lds_dwordx4 v[184:185], off
	v_lshl_add_u64 v[184:185], v[236:237], 0, s[4:5]
	s_mov_b32 m0, s61
	s_nop 0
	global_load_lds_dwordx4 v[184:185], off
	v_lshl_add_u64 v[184:185], v[238:239], 0, s[4:5]
	s_mov_b32 m0, s63
	s_nop 0
	global_load_lds_dwordx4 v[184:185], off
	s_waitcnt vmcnt(8)
	s_waitcnt lgkmcnt(0)
	s_barrier
	s_setprio 1
	s_waitcnt lgkmcnt(0)
	v_mfma_f32_16x16x32_bf16 v[126:129], v[142:145], v[176:179], v[126:129]
	v_mfma_f32_16x16x32_bf16 v[98:101], v[150:153], v[176:179], v[98:101]
	v_mfma_f32_16x16x32_bf16 v[122:125], v[142:145], v[202:205], v[122:125]
	v_mfma_f32_16x16x32_bf16 v[114:117], v[150:153], v[202:205], v[114:117]
	v_mfma_f32_16x16x32_bf16 v[110:113], v[142:145], v[210:213], v[110:113]
	v_mfma_f32_16x16x32_bf16 v[102:105], v[150:153], v[210:213], v[102:105]
	v_mfma_f32_16x16x32_bf16 v[94:97], v[142:145], v[226:229], v[94:97]
	v_mfma_f32_16x16x32_bf16 v[90:93], v[150:153], v[226:229], v[90:93]
	v_mfma_f32_16x16x32_bf16 v[126:129], v[146:149], v[180:183], v[126:129]
	v_mfma_f32_16x16x32_bf16 v[98:101], v[154:157], v[180:183], v[98:101]
	v_mfma_f32_16x16x32_bf16 v[122:125], v[146:149], v[206:209], v[122:125]
	v_mfma_f32_16x16x32_bf16 v[114:117], v[154:157], v[206:209], v[114:117]
	v_mfma_f32_16x16x32_bf16 v[110:113], v[146:149], v[216:219], v[110:113]
	v_mfma_f32_16x16x32_bf16 v[102:105], v[154:157], v[216:219], v[102:105]
	v_mfma_f32_16x16x32_bf16 v[94:97], v[146:149], v[230:233], v[94:97]
	v_mfma_f32_16x16x32_bf16 v[90:93], v[154:157], v[230:233], v[90:93]
	v_mfma_f32_16x16x32_bf16 v[58:61], v[158:161], v[176:179], v[58:61]
	v_mfma_f32_16x16x32_bf16 v[26:29], v[168:171], v[176:179], v[26:29]
	v_mfma_f32_16x16x32_bf16 v[70:73], v[158:161], v[202:205], v[70:73]
	v_mfma_f32_16x16x32_bf16 v[38:41], v[168:171], v[202:205], v[38:41]
	v_mfma_f32_16x16x32_bf16 v[86:89], v[158:161], v[210:213], v[86:89]
	v_mfma_f32_16x16x32_bf16 v[54:57], v[168:171], v[210:213], v[54:57]
	v_mfma_f32_16x16x32_bf16 v[82:85], v[158:161], v[226:229], v[82:85]
	v_mfma_f32_16x16x32_bf16 v[50:53], v[168:171], v[226:229], v[50:53]
	v_mfma_f32_16x16x32_bf16 v[58:61], v[162:165], v[180:183], v[58:61]
	v_mfma_f32_16x16x32_bf16 v[26:29], v[172:175], v[180:183], v[26:29]
	v_mfma_f32_16x16x32_bf16 v[70:73], v[162:165], v[206:209], v[70:73]
	v_mfma_f32_16x16x32_bf16 v[38:41], v[172:175], v[206:209], v[38:41]
	v_mfma_f32_16x16x32_bf16 v[86:89], v[162:165], v[216:219], v[86:89]
	v_mfma_f32_16x16x32_bf16 v[54:57], v[172:175], v[216:219], v[54:57]
	v_mfma_f32_16x16x32_bf16 v[82:85], v[162:165], v[230:233], v[82:85]
	v_mfma_f32_16x16x32_bf16 v[50:53], v[172:175], v[230:233], v[50:53]
	s_setprio 0
	s_barrier
	s_add_i32 s82, s82, 2
	s_add_u32 s8, s8, 0x100
	s_addc_u32 s9, s9, 0
	s_cmp_gt_u32 s82, 41
	s_cbranch_scc0 .LBB0_528
	s_add_u32 s8, s80, 0xffffff00
	s_addc_u32 s9, s81, -1
	s_and_b64 vcc, exec, s[42:43]
	s_cbranch_vccnz .LBB0_531
	v_mov_b32_e32 v50, 0
	s_mov_b32 s60, s77
	s_mov_b32 s19, s78
	s_mov_b64 s[70:71], s[0:1]
	s_mov_b32 s68, s79
	v_mov_b32_e32 v51, v50
	v_mov_b32_e32 v52, v50
	v_mov_b32_e32 v53, v50
	v_mov_b32_e32 v82, v50
	v_mov_b32_e32 v83, v50
	v_mov_b32_e32 v84, v50
	v_mov_b32_e32 v85, v50
	v_mov_b32_e32 v54, v50
	v_mov_b32_e32 v55, v50
	v_mov_b32_e32 v56, v50
	v_mov_b32_e32 v57, v50
	v_mov_b32_e32 v86, v50
	v_mov_b32_e32 v87, v50
	v_mov_b32_e32 v88, v50
	v_mov_b32_e32 v89, v50
	v_mov_b32_e32 v38, v50
	v_mov_b32_e32 v39, v50
	v_mov_b32_e32 v40, v50
	v_mov_b32_e32 v41, v50
	v_mov_b32_e32 v70, v50
	v_mov_b32_e32 v71, v50
	v_mov_b32_e32 v72, v50
	v_mov_b32_e32 v73, v50
	v_mov_b32_e32 v26, v50
	v_mov_b32_e32 v27, v50
	v_mov_b32_e32 v28, v50
	v_mov_b32_e32 v29, v50
	v_mov_b32_e32 v58, v50
	v_mov_b32_e32 v59, v50
	v_mov_b32_e32 v60, v50
	v_mov_b32_e32 v61, v50
	v_mov_b32_e32 v90, v50
	v_mov_b32_e32 v91, v50
	v_mov_b32_e32 v92, v50
	v_mov_b32_e32 v93, v50
	v_mov_b32_e32 v94, v50
	v_mov_b32_e32 v95, v50
	v_mov_b32_e32 v96, v50
	v_mov_b32_e32 v97, v50
	v_mov_b32_e32 v102, v50
	v_mov_b32_e32 v103, v50
	v_mov_b32_e32 v104, v50
	v_mov_b32_e32 v105, v50
	v_mov_b32_e32 v110, v50
	v_mov_b32_e32 v111, v50
	v_mov_b32_e32 v112, v50
	v_mov_b32_e32 v113, v50
	v_mov_b32_e32 v114, v50
	v_mov_b32_e32 v115, v50
	v_mov_b32_e32 v116, v50
	v_mov_b32_e32 v117, v50
	v_mov_b32_e32 v122, v50
	v_mov_b32_e32 v123, v50
	v_mov_b32_e32 v124, v50
	v_mov_b32_e32 v125, v50
	v_mov_b32_e32 v98, v50
	v_mov_b32_e32 v99, v50
	v_mov_b32_e32 v100, v50
	v_mov_b32_e32 v101, v50
	v_mov_b32_e32 v126, v50
	v_mov_b32_e32 v127, v50
	v_mov_b32_e32 v128, v50
	v_mov_b32_e32 v129, v50
	v_mov_b32_e32 v18, v50
	v_mov_b32_e32 v19, v50
	v_mov_b32_e32 v20, v50
	v_mov_b32_e32 v21, v50
	v_mov_b32_e32 v42, v50
	v_mov_b32_e32 v43, v50
	v_mov_b32_e32 v44, v50
	v_mov_b32_e32 v45, v50
	v_mov_b32_e32 v10, v50
	v_mov_b32_e32 v11, v50
	v_mov_b32_e32 v12, v50
	v_mov_b32_e32 v13, v50
	v_mov_b32_e32 v30, v50
	v_mov_b32_e32 v31, v50
	v_mov_b32_e32 v32, v50
	v_mov_b32_e32 v33, v50
	v_mov_b32_e32 v6, v50
	v_mov_b32_e32 v7, v50
	v_mov_b32_e32 v8, v50
	v_mov_b32_e32 v9, v50
	v_mov_b32_e32 v22, v50
	v_mov_b32_e32 v23, v50
	v_mov_b32_e32 v24, v50
	v_mov_b32_e32 v25, v50
	v_mov_b32_e32 v2, v50
	v_mov_b32_e32 v3, v50
	v_mov_b32_e32 v4, v50
	v_mov_b32_e32 v5, v50
	v_mov_b32_e32 v14, v50
	v_mov_b32_e32 v15, v50
	v_mov_b32_e32 v16, v50
	v_mov_b32_e32 v17, v50
	v_mov_b32_e32 v74, v50
	v_mov_b32_e32 v75, v50
	v_mov_b32_e32 v76, v50
	v_mov_b32_e32 v77, v50
	v_mov_b32_e32 v118, v50
	v_mov_b32_e32 v119, v50
	v_mov_b32_e32 v120, v50
	v_mov_b32_e32 v121, v50
	v_mov_b32_e32 v62, v50
	v_mov_b32_e32 v63, v50
	v_mov_b32_e32 v64, v50
	v_mov_b32_e32 v65, v50
	v_mov_b32_e32 v106, v50
	v_mov_b32_e32 v107, v50
	v_mov_b32_e32 v108, v50
	v_mov_b32_e32 v109, v50
	v_mov_b32_e32 v46, v50
	v_mov_b32_e32 v47, v50
	v_mov_b32_e32 v48, v50
	v_mov_b32_e32 v49, v50
	v_mov_b32_e32 v78, v50
	v_mov_b32_e32 v79, v50
	v_mov_b32_e32 v80, v50
	v_mov_b32_e32 v81, v50
	v_mov_b32_e32 v34, v50
	v_mov_b32_e32 v35, v50
	v_mov_b32_e32 v36, v50
	v_mov_b32_e32 v37, v50
	v_mov_b32_e32 v66, v50
	v_mov_b32_e32 v67, v50
	v_mov_b32_e32 v68, v50
	v_mov_b32_e32 v69, v50
	s_branch .LBB0_532

.LBB0_796:
	s_add_u32 s8, s0, 0xfffc0080
	s_addc_u32 s9, s1, -1
	s_add_i32 s57, 0, 0x10000
	s_cmp_eq_u32 s55, 12
	s_cselect_b32 s11, s36, s9
	s_cselect_b32 s10, s37, s8
	s_cselect_b32 s9, s42, s54
	s_cselect_b32 s8, s43, s53
	s_add_i32 s64, 0, 0x14000
	v_add_u32_e32 v160, s57, v157
	v_add_u32_e32 v176, s64, v157
	ds_read_b128 v[144:147], v160
	ds_read_b128 v[148:151], v160 offset:1024
	ds_read_b128 v[152:155], v160 offset:2048
	ds_read_b128 v[160:163], v160 offset:3072
	ds_read_b128 v[164:167], v176
	ds_read_b128 v[168:171], v176 offset:1024
	ds_read_b128 v[172:175], v176 offset:2048
	ds_read_b128 v[176:179], v176 offset:3072
	v_lshl_add_u64 v[184:185], s[0:1], 0, v[142:143]
	s_add_i32 m0, s17, 0xc000
	ds_read_b128 v[180:183], v159
	ds_read_b128 v[200:203], v159 offset:1024
	ds_read_b128 v[204:207], v159 offset:2048
	ds_read_b128 v[208:211], v159 offset:3072
	ds_read_b128 v[212:215], v159 offset:4096
	ds_read_b128 v[216:219], v159 offset:5120
	ds_read_b128 v[226:229], v159 offset:6144
	ds_read_b128 v[230:233], v159 offset:7168
	global_load_lds_dwordx4 v[184:185], off
	v_lshl_add_u64 v[184:185], s[0:1], 0, v[140:141]
	s_add_i32 m0, s17, 0xe000
	s_nop 0
	global_load_lds_dwordx4 v[184:185], off
	s_waitcnt vmcnt(8)
	s_waitcnt lgkmcnt(0)
	s_barrier
	s_setprio 1
	s_waitcnt lgkmcnt(0)
	v_mfma_f32_16x16x32_bf16 v[126:129], v[144:147], v[180:183], v[126:129]
	v_mfma_f32_16x16x32_bf16 v[122:125], v[152:155], v[180:183], v[122:125]
	v_mfma_f32_16x16x32_bf16 v[110:113], v[144:147], v[204:207], v[110:113]
	v_mfma_f32_16x16x32_bf16 v[106:109], v[152:155], v[204:207], v[106:109]
	v_mfma_f32_16x16x32_bf16 v[94:97], v[144:147], v[212:215], v[94:97]
	v_mfma_f32_16x16x32_bf16 v[90:93], v[152:155], v[212:215], v[90:93]
	v_mfma_f32_16x16x32_bf16 v[78:81], v[144:147], v[226:229], v[78:81]
	v_mfma_f32_16x16x32_bf16 v[74:77], v[152:155], v[226:229], v[74:77]
	v_mfma_f32_16x16x32_bf16 v[126:129], v[148:151], v[200:203], v[126:129]
	v_mfma_f32_16x16x32_bf16 v[122:125], v[160:163], v[200:203], v[122:125]
	v_mfma_f32_16x16x32_bf16 v[110:113], v[148:151], v[208:211], v[110:113]
	v_mfma_f32_16x16x32_bf16 v[106:109], v[160:163], v[208:211], v[106:109]
	v_mfma_f32_16x16x32_bf16 v[94:97], v[148:151], v[216:219], v[94:97]
	v_mfma_f32_16x16x32_bf16 v[90:93], v[160:163], v[216:219], v[90:93]
	v_mfma_f32_16x16x32_bf16 v[78:81], v[148:151], v[230:233], v[78:81]
	v_mfma_f32_16x16x32_bf16 v[74:77], v[160:163], v[230:233], v[74:77]
	v_mfma_f32_16x16x32_bf16 v[118:121], v[164:167], v[180:183], v[118:121]
	v_mfma_f32_16x16x32_bf16 v[114:117], v[172:175], v[180:183], v[114:117]
	v_mfma_f32_16x16x32_bf16 v[102:105], v[164:167], v[204:207], v[102:105]
	v_mfma_f32_16x16x32_bf16 v[98:101], v[172:175], v[204:207], v[98:101]
	v_mfma_f32_16x16x32_bf16 v[86:89], v[164:167], v[212:215], v[86:89]
	v_mfma_f32_16x16x32_bf16 v[82:85], v[172:175], v[212:215], v[82:85]
	v_mfma_f32_16x16x32_bf16 v[70:73], v[164:167], v[226:229], v[70:73]
	v_mfma_f32_16x16x32_bf16 v[66:69], v[172:175], v[226:229], v[66:69]
	v_mfma_f32_16x16x32_bf16 v[118:121], v[168:171], v[200:203], v[118:121]
	v_mfma_f32_16x16x32_bf16 v[114:117], v[176:179], v[200:203], v[114:117]
	v_mfma_f32_16x16x32_bf16 v[102:105], v[168:171], v[208:211], v[102:105]
	v_mfma_f32_16x16x32_bf16 v[98:101], v[176:179], v[208:211], v[98:101]
	v_mfma_f32_16x16x32_bf16 v[86:89], v[168:171], v[216:219], v[86:89]
	v_mfma_f32_16x16x32_bf16 v[82:85], v[176:179], v[216:219], v[82:85]
	v_mfma_f32_16x16x32_bf16 v[70:73], v[168:171], v[230:233], v[70:73]
	v_mfma_f32_16x16x32_bf16 v[66:69], v[176:179], v[230:233], v[66:69]
	s_setprio 0
	s_barrier
	s_add_i32 s57, s57, s16
	v_lshl_add_u64 v[184:185], s[8:9], 0, v[134:135]
	s_mov_b32 m0, s57
	ds_read_b128 v[180:183], v159 offset:16384
	ds_read_b128 v[200:203], v159 offset:17408
	ds_read_b128 v[204:207], v159 offset:18432
	ds_read_b128 v[208:211], v159 offset:19456
	ds_read_b128 v[212:215], v159 offset:20480
	ds_read_b128 v[216:219], v159 offset:21504
	ds_read_b128 v[226:229], v159 offset:22528
	ds_read_b128 v[230:233], v159 offset:23552
	global_load_lds_dwordx4 v[184:185], off
	s_add_i32 m0, s57, 0x2000
	s_add_u32 s62, s8, 0x40000
	v_lshl_add_u64 v[234:235], s[8:9], 0, v[130:131]
	s_addc_u32 s63, s9, 0
	s_add_i32 s57, s64, s16
	global_load_lds_dwordx4 v[234:235], off
	v_lshl_add_u64 v[236:237], s[62:63], 0, v[134:135]
	s_mov_b32 m0, s57
	v_lshl_add_u64 v[238:239], s[10:11], 0, v[132:133]
	global_load_lds_dwordx4 v[236:237], off
	v_lshl_add_u64 v[236:237], s[62:63], 0, v[130:131]
	s_add_i32 m0, s57, 0x2000
	s_nop 0
	global_load_lds_dwordx4 v[236:237], off
	v_lshl_add_u64 v[236:237], s[10:11], 0, v[136:137]
	s_mov_b32 m0, s17
	s_nop 0
	global_load_lds_dwordx4 v[236:237], off
	s_mov_b32 m0, s18
	s_nop 0
	global_load_lds_dwordx4 v[238:239], off
	s_waitcnt vmcnt(8)
	s_waitcnt lgkmcnt(0)
	s_barrier
	s_setprio 1
	s_waitcnt lgkmcnt(0)
	v_mfma_f32_16x16x32_bf16 v[62:65], v[144:147], v[180:183], v[62:65]
	v_mfma_f32_16x16x32_bf16 v[58:61], v[152:155], v[180:183], v[58:61]
	v_mfma_f32_16x16x32_bf16 v[46:49], v[144:147], v[204:207], v[46:49]
	v_mfma_f32_16x16x32_bf16 v[42:45], v[152:155], v[204:207], v[42:45]
	v_mfma_f32_16x16x32_bf16 v[30:33], v[144:147], v[212:215], v[30:33]
	v_mfma_f32_16x16x32_bf16 v[26:29], v[152:155], v[212:215], v[26:29]
	v_mfma_f32_16x16x32_bf16 v[14:17], v[144:147], v[226:229], v[14:17]
	v_mfma_f32_16x16x32_bf16 v[10:13], v[152:155], v[226:229], v[10:13]
	v_mfma_f32_16x16x32_bf16 v[62:65], v[148:151], v[200:203], v[62:65]
	v_mfma_f32_16x16x32_bf16 v[58:61], v[160:163], v[200:203], v[58:61]
	v_mfma_f32_16x16x32_bf16 v[46:49], v[148:151], v[208:211], v[46:49]
	v_mfma_f32_16x16x32_bf16 v[42:45], v[160:163], v[208:211], v[42:45]
	v_mfma_f32_16x16x32_bf16 v[30:33], v[148:151], v[216:219], v[30:33]
	v_mfma_f32_16x16x32_bf16 v[26:29], v[160:163], v[216:219], v[26:29]
	v_mfma_f32_16x16x32_bf16 v[14:17], v[148:151], v[230:233], v[14:17]
	v_mfma_f32_16x16x32_bf16 v[10:13], v[160:163], v[230:233], v[10:13]
	v_mfma_f32_16x16x32_bf16 v[54:57], v[164:167], v[180:183], v[54:57]
	v_mfma_f32_16x16x32_bf16 v[50:53], v[172:175], v[180:183], v[50:53]
	v_mfma_f32_16x16x32_bf16 v[38:41], v[164:167], v[204:207], v[38:41]
	v_mfma_f32_16x16x32_bf16 v[34:37], v[172:175], v[204:207], v[34:37]
	v_mfma_f32_16x16x32_bf16 v[22:25], v[164:167], v[212:215], v[22:25]
	v_mfma_f32_16x16x32_bf16 v[18:21], v[172:175], v[212:215], v[18:21]
	v_mfma_f32_16x16x32_bf16 v[6:9], v[164:167], v[226:229], v[6:9]
	v_mfma_f32_16x16x32_bf16 v[2:5], v[172:175], v[226:229], v[2:5]
	v_mfma_f32_16x16x32_bf16 v[54:57], v[168:171], v[200:203], v[54:57]
	v_mfma_f32_16x16x32_bf16 v[50:53], v[176:179], v[200:203], v[50:53]
	v_mfma_f32_16x16x32_bf16 v[38:41], v[168:171], v[208:211], v[38:41]
	v_mfma_f32_16x16x32_bf16 v[34:37], v[176:179], v[208:211], v[34:37]
	v_mfma_f32_16x16x32_bf16 v[22:25], v[168:171], v[216:219], v[22:25]
	v_mfma_f32_16x16x32_bf16 v[18:21], v[176:179], v[216:219], v[18:21]
	v_mfma_f32_16x16x32_bf16 v[6:9], v[168:171], v[230:233], v[6:9]
	v_mfma_f32_16x16x32_bf16 v[2:5], v[176:179], v[230:233], v[2:5]
	s_setprio 0
	s_barrier
	s_add_i32 s57, 0, 0x18000
	s_add_i32 s62, 0, 0x1c000
	v_add_u32_e32 v160, s57, v157
	v_add_u32_e32 v176, s62, v157
	ds_read_b128 v[144:147], v160
	ds_read_b128 v[148:151], v160 offset:1024
	ds_read_b128 v[152:155], v160 offset:2048
	ds_read_b128 v[160:163], v160 offset:3072
	ds_read_b128 v[164:167], v176
	ds_read_b128 v[168:171], v176 offset:1024
	ds_read_b128 v[172:175], v176 offset:2048
	ds_read_b128 v[176:179], v176 offset:3072
	s_add_u32 s10, s10, 0x40000
	s_addc_u32 s11, s11, 0
	s_mov_b32 m0, s19
	v_lshl_add_u64 v[240:241], s[10:11], 0, v[136:137]
	ds_read_b128 v[180:183], v159 offset:32768
	ds_read_b128 v[200:203], v159 offset:33792
	ds_read_b128 v[204:207], v159 offset:34816
	ds_read_b128 v[208:211], v159 offset:35840
	ds_read_b128 v[212:215], v159 offset:36864
	ds_read_b128 v[216:219], v159 offset:37888
	ds_read_b128 v[226:229], v159 offset:38912
	ds_read_b128 v[230:233], v159 offset:39936
	global_load_lds_dwordx4 v[240:241], off
	v_lshl_add_u64 v[240:241], s[10:11], 0, v[132:133]
	s_mov_b32 m0, s20
	s_nop 0
	global_load_lds_dwordx4 v[240:241], off
	s_waitcnt vmcnt(8)
	s_waitcnt lgkmcnt(0)
	s_barrier
	s_setprio 1
	s_waitcnt lgkmcnt(0)
	v_mfma_f32_16x16x32_bf16 v[126:129], v[144:147], v[180:183], v[126:129]
	v_mfma_f32_16x16x32_bf16 v[122:125], v[152:155], v[180:183], v[122:125]
	v_mfma_f32_16x16x32_bf16 v[110:113], v[144:147], v[204:207], v[110:113]
	v_mfma_f32_16x16x32_bf16 v[106:109], v[152:155], v[204:207], v[106:109]
	v_mfma_f32_16x16x32_bf16 v[94:97], v[144:147], v[212:215], v[94:97]
	v_mfma_f32_16x16x32_bf16 v[90:93], v[152:155], v[212:215], v[90:93]
	v_mfma_f32_16x16x32_bf16 v[78:81], v[144:147], v[226:229], v[78:81]
	v_mfma_f32_16x16x32_bf16 v[74:77], v[152:155], v[226:229], v[74:77]
	v_mfma_f32_16x16x32_bf16 v[126:129], v[148:151], v[200:203], v[126:129]
	v_mfma_f32_16x16x32_bf16 v[122:125], v[160:163], v[200:203], v[122:125]
	v_mfma_f32_16x16x32_bf16 v[110:113], v[148:151], v[208:211], v[110:113]
	v_mfma_f32_16x16x32_bf16 v[106:109], v[160:163], v[208:211], v[106:109]
	v_mfma_f32_16x16x32_bf16 v[94:97], v[148:151], v[216:219], v[94:97]
	v_mfma_f32_16x16x32_bf16 v[90:93], v[160:163], v[216:219], v[90:93]
	v_mfma_f32_16x16x32_bf16 v[78:81], v[148:151], v[230:233], v[78:81]
	v_mfma_f32_16x16x32_bf16 v[74:77], v[160:163], v[230:233], v[74:77]
	v_mfma_f32_16x16x32_bf16 v[118:121], v[164:167], v[180:183], v[118:121]
	v_mfma_f32_16x16x32_bf16 v[114:117], v[172:175], v[180:183], v[114:117]
	v_mfma_f32_16x16x32_bf16 v[102:105], v[164:167], v[204:207], v[102:105]
	v_mfma_f32_16x16x32_bf16 v[98:101], v[172:175], v[204:207], v[98:101]
	v_mfma_f32_16x16x32_bf16 v[86:89], v[164:167], v[212:215], v[86:89]
	v_mfma_f32_16x16x32_bf16 v[82:85], v[172:175], v[212:215], v[82:85]
	v_mfma_f32_16x16x32_bf16 v[70:73], v[164:167], v[226:229], v[70:73]
	v_mfma_f32_16x16x32_bf16 v[66:69], v[172:175], v[226:229], v[66:69]
	v_mfma_f32_16x16x32_bf16 v[118:121], v[168:171], v[200:203], v[118:121]
	v_mfma_f32_16x16x32_bf16 v[114:117], v[176:179], v[200:203], v[114:117]
	v_mfma_f32_16x16x32_bf16 v[102:105], v[168:171], v[208:211], v[102:105]
	v_mfma_f32_16x16x32_bf16 v[98:101], v[176:179], v[208:211], v[98:101]
	v_mfma_f32_16x16x32_bf16 v[86:89], v[168:171], v[216:219], v[86:89]
	v_mfma_f32_16x16x32_bf16 v[82:85], v[176:179], v[216:219], v[82:85]
	v_mfma_f32_16x16x32_bf16 v[70:73], v[168:171], v[230:233], v[70:73]
	v_mfma_f32_16x16x32_bf16 v[66:69], v[176:179], v[230:233], v[66:69]
	s_setprio 0
	s_barrier
	s_add_i32 s10, s57, s16
	v_lshl_add_u64 v[184:185], v[184:185], 0, s[4:5]
	s_mov_b32 m0, s10
	ds_read_b128 v[180:183], v159 offset:49152
	ds_read_b128 v[200:203], v159 offset:50176
	ds_read_b128 v[204:207], v159 offset:51200
	ds_read_b128 v[208:211], v159 offset:52224
	ds_read_b128 v[212:215], v159 offset:53248
	ds_read_b128 v[216:219], v159 offset:54272
	ds_read_b128 v[226:229], v159 offset:55296
	ds_read_b128 v[230:233], v159 offset:56320
	global_load_lds_dwordx4 v[184:185], off
	s_add_i32 m0, s10, 0x2000
	s_add_u32 s8, s8, 0x40080
	v_lshl_add_u64 v[184:185], v[234:235], 0, s[4:5]
	s_addc_u32 s9, s9, 0
	s_add_i32 s10, s62, s16
	global_load_lds_dwordx4 v[184:185], off
	v_lshl_add_u64 v[184:185], s[8:9], 0, v[134:135]
	s_mov_b32 m0, s10
	s_nop 0
	global_load_lds_dwordx4 v[184:185], off
	v_lshl_add_u64 v[184:185], s[8:9], 0, v[130:131]
	s_add_i32 m0, s10, 0x2000
	s_nop 0
	global_load_lds_dwordx4 v[184:185], off
	v_lshl_add_u64 v[184:185], v[236:237], 0, s[4:5]
	s_mov_b32 m0, s25
	s_nop 0
	global_load_lds_dwordx4 v[184:185], off
	v_lshl_add_u64 v[184:185], v[238:239], 0, s[4:5]
	s_mov_b32 m0, s28
	s_nop 0
	global_load_lds_dwordx4 v[184:185], off
	s_waitcnt vmcnt(8)
	s_waitcnt lgkmcnt(0)
	s_barrier
	s_setprio 1
	s_waitcnt lgkmcnt(0)
	v_mfma_f32_16x16x32_bf16 v[62:65], v[144:147], v[180:183], v[62:65]
	v_mfma_f32_16x16x32_bf16 v[58:61], v[152:155], v[180:183], v[58:61]
	v_mfma_f32_16x16x32_bf16 v[46:49], v[144:147], v[204:207], v[46:49]
	v_mfma_f32_16x16x32_bf16 v[42:45], v[152:155], v[204:207], v[42:45]
	v_mfma_f32_16x16x32_bf16 v[30:33], v[144:147], v[212:215], v[30:33]
	v_mfma_f32_16x16x32_bf16 v[26:29], v[152:155], v[212:215], v[26:29]
	v_mfma_f32_16x16x32_bf16 v[14:17], v[144:147], v[226:229], v[14:17]
	v_mfma_f32_16x16x32_bf16 v[10:13], v[152:155], v[226:229], v[10:13]
	v_mfma_f32_16x16x32_bf16 v[62:65], v[148:151], v[200:203], v[62:65]
	v_mfma_f32_16x16x32_bf16 v[58:61], v[160:163], v[200:203], v[58:61]
	v_mfma_f32_16x16x32_bf16 v[46:49], v[148:151], v[208:211], v[46:49]
	v_mfma_f32_16x16x32_bf16 v[42:45], v[160:163], v[208:211], v[42:45]
	v_mfma_f32_16x16x32_bf16 v[30:33], v[148:151], v[216:219], v[30:33]
	v_mfma_f32_16x16x32_bf16 v[26:29], v[160:163], v[216:219], v[26:29]
	v_mfma_f32_16x16x32_bf16 v[14:17], v[148:151], v[230:233], v[14:17]
	v_mfma_f32_16x16x32_bf16 v[10:13], v[160:163], v[230:233], v[10:13]
	v_mfma_f32_16x16x32_bf16 v[54:57], v[164:167], v[180:183], v[54:57]
	v_mfma_f32_16x16x32_bf16 v[50:53], v[172:175], v[180:183], v[50:53]
	v_mfma_f32_16x16x32_bf16 v[38:41], v[164:167], v[204:207], v[38:41]
	v_mfma_f32_16x16x32_bf16 v[34:37], v[172:175], v[204:207], v[34:37]
	v_mfma_f32_16x16x32_bf16 v[22:25], v[164:167], v[212:215], v[22:25]
	v_mfma_f32_16x16x32_bf16 v[18:21], v[172:175], v[212:215], v[18:21]
	v_mfma_f32_16x16x32_bf16 v[6:9], v[164:167], v[226:229], v[6:9]
	v_mfma_f32_16x16x32_bf16 v[2:5], v[172:175], v[226:229], v[2:5]
	v_mfma_f32_16x16x32_bf16 v[54:57], v[168:171], v[200:203], v[54:57]
	v_mfma_f32_16x16x32_bf16 v[50:53], v[176:179], v[200:203], v[50:53]
	v_mfma_f32_16x16x32_bf16 v[38:41], v[168:171], v[208:211], v[38:41]
	v_mfma_f32_16x16x32_bf16 v[34:37], v[176:179], v[208:211], v[34:37]
	v_mfma_f32_16x16x32_bf16 v[22:25], v[168:171], v[216:219], v[22:25]
	v_mfma_f32_16x16x32_bf16 v[18:21], v[176:179], v[216:219], v[18:21]
	v_mfma_f32_16x16x32_bf16 v[6:9], v[168:171], v[230:233], v[6:9]
	v_mfma_f32_16x16x32_bf16 v[2:5], v[176:179], v[230:233], v[2:5]
	s_setprio 0
	s_barrier
	s_add_i32 s55, s55, 2
	s_add_u32 s53, s53, 0x100
	s_addc_u32 s54, s54, 0
	s_add_u32 s0, s0, 0x100
	s_addc_u32 s1, s1, 0
	s_cmp_gt_u32 s55, 13
	s_cbranch_scc0 .LBB0_796
	s_and_b64 vcc, exec, s[48:49]
	s_cbranch_vccz .LBB0_799
	s_barrier

.LBB0_2962:
	s_add_u32 s8, s0, 0xfffe0080
	s_addc_u32 s9, s1, -1
	s_add_i32 s52, 0, 0x10000
	s_cmp_eq_u32 s51, 4
	s_cselect_b32 s11, s12, s9
	s_cselect_b32 s10, s13, s8
	s_cselect_b32 s9, s37, s50
	s_cselect_b32 s8, s41, s43
	s_add_i32 s54, 0, 0x14000
	v_add_u32_e32 v142, s52, v181
	v_add_u32_e32 v168, s54, v181
	ds_read_b128 v[130:133], v142
	ds_read_b128 v[134:137], v142 offset:1024
	ds_read_b128 v[138:141], v142 offset:2048
	ds_read_b128 v[142:145], v142 offset:3072
	ds_read_b128 v[146:149], v168
	ds_read_b128 v[150:153], v168 offset:1024
	ds_read_b128 v[154:157], v168 offset:2048
	ds_read_b128 v[168:171], v168 offset:3072
	v_lshl_add_u64 v[184:185], s[0:1], 0, v[166:167]
	s_add_i32 m0, s20, 0xc000
	ds_read_b128 v[172:175], v183
	ds_read_b128 v[176:179], v183 offset:1024
	ds_read_b128 v[200:203], v183 offset:2048
	ds_read_b128 v[204:207], v183 offset:3072
	ds_read_b128 v[208:211], v183 offset:4096
	ds_read_b128 v[212:215], v183 offset:5120
	ds_read_b128 v[216:219], v183 offset:6144
	ds_read_b128 v[226:229], v183 offset:7168
	global_load_lds_dwordx4 v[184:185], off
	v_lshl_add_u64 v[184:185], s[0:1], 0, v[164:165]
	s_add_i32 m0, s20, 0xe000
	s_nop 0
	global_load_lds_dwordx4 v[184:185], off
	s_waitcnt vmcnt(8)
	s_waitcnt lgkmcnt(0)
	s_barrier
	s_setprio 1
	s_waitcnt lgkmcnt(0)
	v_mfma_f32_16x16x32_bf16 v[126:129], v[130:133], v[172:175], v[126:129]
	v_mfma_f32_16x16x32_bf16 v[122:125], v[138:141], v[172:175], v[122:125]
	v_mfma_f32_16x16x32_bf16 v[110:113], v[130:133], v[200:203], v[110:113]
	v_mfma_f32_16x16x32_bf16 v[106:109], v[138:141], v[200:203], v[106:109]
	v_mfma_f32_16x16x32_bf16 v[98:101], v[130:133], v[208:211], v[98:101]
	v_mfma_f32_16x16x32_bf16 v[90:93], v[138:141], v[208:211], v[90:93]
	v_mfma_f32_16x16x32_bf16 v[82:85], v[130:133], v[216:219], v[82:85]
	v_mfma_f32_16x16x32_bf16 v[74:77], v[138:141], v[216:219], v[74:77]
	v_mfma_f32_16x16x32_bf16 v[126:129], v[134:137], v[176:179], v[126:129]
	v_mfma_f32_16x16x32_bf16 v[122:125], v[142:145], v[176:179], v[122:125]
	v_mfma_f32_16x16x32_bf16 v[110:113], v[134:137], v[204:207], v[110:113]
	v_mfma_f32_16x16x32_bf16 v[106:109], v[142:145], v[204:207], v[106:109]
	v_mfma_f32_16x16x32_bf16 v[98:101], v[134:137], v[212:215], v[98:101]
	v_mfma_f32_16x16x32_bf16 v[90:93], v[142:145], v[212:215], v[90:93]
	v_mfma_f32_16x16x32_bf16 v[82:85], v[134:137], v[226:229], v[82:85]
	v_mfma_f32_16x16x32_bf16 v[74:77], v[142:145], v[226:229], v[74:77]
	v_mfma_f32_16x16x32_bf16 v[118:121], v[146:149], v[172:175], v[118:121]
	v_mfma_f32_16x16x32_bf16 v[114:117], v[154:157], v[172:175], v[114:117]
	v_mfma_f32_16x16x32_bf16 v[102:105], v[146:149], v[200:203], v[102:105]
	v_mfma_f32_16x16x32_bf16 v[94:97], v[154:157], v[200:203], v[94:97]
	v_mfma_f32_16x16x32_bf16 v[86:89], v[146:149], v[208:211], v[86:89]
	v_mfma_f32_16x16x32_bf16 v[78:81], v[154:157], v[208:211], v[78:81]
	v_mfma_f32_16x16x32_bf16 v[70:73], v[146:149], v[216:219], v[70:73]
	v_mfma_f32_16x16x32_bf16 v[66:69], v[154:157], v[216:219], v[66:69]
	v_mfma_f32_16x16x32_bf16 v[118:121], v[150:153], v[176:179], v[118:121]
	v_mfma_f32_16x16x32_bf16 v[114:117], v[168:171], v[176:179], v[114:117]
	v_mfma_f32_16x16x32_bf16 v[102:105], v[150:153], v[204:207], v[102:105]
	v_mfma_f32_16x16x32_bf16 v[94:97], v[168:171], v[204:207], v[94:97]
	v_mfma_f32_16x16x32_bf16 v[86:89], v[150:153], v[212:215], v[86:89]
	v_mfma_f32_16x16x32_bf16 v[78:81], v[168:171], v[212:215], v[78:81]
	v_mfma_f32_16x16x32_bf16 v[70:73], v[150:153], v[226:229], v[70:73]
	v_mfma_f32_16x16x32_bf16 v[66:69], v[168:171], v[226:229], v[66:69]
	s_setprio 0
	s_barrier
	s_add_i32 s52, s52, s19
	v_lshl_add_u64 v[184:185], s[8:9], 0, v[188:189]
	s_mov_b32 m0, s52
	ds_read_b128 v[172:175], v183 offset:16384
	ds_read_b128 v[176:179], v183 offset:17408
	ds_read_b128 v[200:203], v183 offset:18432
	ds_read_b128 v[204:207], v183 offset:19456
	ds_read_b128 v[208:211], v183 offset:20480
	ds_read_b128 v[212:215], v183 offset:21504
	ds_read_b128 v[216:219], v183 offset:22528
	ds_read_b128 v[226:229], v183 offset:23552
	global_load_lds_dwordx4 v[184:185], off
	s_add_i32 m0, s52, 0x2000
	s_add_u32 s52, s8, 0x20000
	v_lshl_add_u64 v[230:231], s[8:9], 0, v[158:159]
	s_addc_u32 s53, s9, 0
	s_add_i32 s54, s54, s19
	global_load_lds_dwordx4 v[230:231], off
	v_lshl_add_u64 v[232:233], s[52:53], 0, v[188:189]
	s_mov_b32 m0, s54
	v_lshl_add_u64 v[234:235], s[10:11], 0, v[160:161]
	global_load_lds_dwordx4 v[232:233], off
	v_lshl_add_u64 v[232:233], s[52:53], 0, v[158:159]
	s_add_i32 m0, s54, 0x2000
	s_nop 0
	global_load_lds_dwordx4 v[232:233], off
	v_lshl_add_u64 v[232:233], s[10:11], 0, v[162:163]
	s_mov_b32 m0, s20
	s_nop 0
	global_load_lds_dwordx4 v[232:233], off
	s_mov_b32 m0, s21
	s_nop 0
	global_load_lds_dwordx4 v[234:235], off
	s_waitcnt vmcnt(8)
	s_waitcnt lgkmcnt(0)
	s_barrier
	s_setprio 1
	s_waitcnt lgkmcnt(0)
	v_mfma_f32_16x16x32_bf16 v[62:65], v[130:133], v[172:175], v[62:65]
	v_mfma_f32_16x16x32_bf16 v[58:61], v[138:141], v[172:175], v[58:61]
	v_mfma_f32_16x16x32_bf16 v[50:53], v[130:133], v[200:203], v[50:53]
	v_mfma_f32_16x16x32_bf16 v[42:45], v[138:141], v[200:203], v[42:45]
	v_mfma_f32_16x16x32_bf16 v[34:37], v[130:133], v[208:211], v[34:37]
	v_mfma_f32_16x16x32_bf16 v[26:29], v[138:141], v[208:211], v[26:29]
	v_mfma_f32_16x16x32_bf16 v[18:21], v[130:133], v[216:219], v[18:21]
	v_mfma_f32_16x16x32_bf16 v[10:13], v[138:141], v[216:219], v[10:13]
	v_mfma_f32_16x16x32_bf16 v[62:65], v[134:137], v[176:179], v[62:65]
	v_mfma_f32_16x16x32_bf16 v[58:61], v[142:145], v[176:179], v[58:61]
	v_mfma_f32_16x16x32_bf16 v[50:53], v[134:137], v[204:207], v[50:53]
	v_mfma_f32_16x16x32_bf16 v[42:45], v[142:145], v[204:207], v[42:45]
	v_mfma_f32_16x16x32_bf16 v[34:37], v[134:137], v[212:215], v[34:37]
	v_mfma_f32_16x16x32_bf16 v[26:29], v[142:145], v[212:215], v[26:29]
	v_mfma_f32_16x16x32_bf16 v[18:21], v[134:137], v[226:229], v[18:21]
	v_mfma_f32_16x16x32_bf16 v[10:13], v[142:145], v[226:229], v[10:13]
	v_mfma_f32_16x16x32_bf16 v[54:57], v[146:149], v[172:175], v[54:57]
	v_mfma_f32_16x16x32_bf16 v[46:49], v[154:157], v[172:175], v[46:49]
	v_mfma_f32_16x16x32_bf16 v[38:41], v[146:149], v[200:203], v[38:41]
	v_mfma_f32_16x16x32_bf16 v[30:33], v[154:157], v[200:203], v[30:33]
	v_mfma_f32_16x16x32_bf16 v[22:25], v[146:149], v[208:211], v[22:25]
	v_mfma_f32_16x16x32_bf16 v[14:17], v[154:157], v[208:211], v[14:17]
	v_mfma_f32_16x16x32_bf16 v[6:9], v[146:149], v[216:219], v[6:9]
	v_mfma_f32_16x16x32_bf16 v[2:5], v[154:157], v[216:219], v[2:5]
	v_mfma_f32_16x16x32_bf16 v[54:57], v[150:153], v[176:179], v[54:57]
	v_mfma_f32_16x16x32_bf16 v[46:49], v[168:171], v[176:179], v[46:49]
	v_mfma_f32_16x16x32_bf16 v[38:41], v[150:153], v[204:207], v[38:41]
	v_mfma_f32_16x16x32_bf16 v[30:33], v[168:171], v[204:207], v[30:33]
	v_mfma_f32_16x16x32_bf16 v[22:25], v[150:153], v[212:215], v[22:25]
	v_mfma_f32_16x16x32_bf16 v[14:17], v[168:171], v[212:215], v[14:17]
	v_mfma_f32_16x16x32_bf16 v[6:9], v[150:153], v[226:229], v[6:9]
	v_mfma_f32_16x16x32_bf16 v[2:5], v[168:171], v[226:229], v[2:5]
	s_setprio 0
	s_barrier
	s_add_i32 s52, 0, 0x18000
	s_add_i32 s53, 0, 0x1c000
	v_add_u32_e32 v142, s52, v181
	v_add_u32_e32 v168, s53, v181
	ds_read_b128 v[130:133], v142
	ds_read_b128 v[134:137], v142 offset:1024
	ds_read_b128 v[138:141], v142 offset:2048
	ds_read_b128 v[142:145], v142 offset:3072
	ds_read_b128 v[146:149], v168
	ds_read_b128 v[150:153], v168 offset:1024
	ds_read_b128 v[154:157], v168 offset:2048
	ds_read_b128 v[168:171], v168 offset:3072
	s_add_u32 s10, s10, 0x20000
	s_addc_u32 s11, s11, 0
	s_mov_b32 m0, s24
	v_lshl_add_u64 v[236:237], s[10:11], 0, v[162:163]
	ds_read_b128 v[172:175], v183 offset:32768
	ds_read_b128 v[176:179], v183 offset:33792
	ds_read_b128 v[200:203], v183 offset:34816
	ds_read_b128 v[204:207], v183 offset:35840
	ds_read_b128 v[208:211], v183 offset:36864
	ds_read_b128 v[212:215], v183 offset:37888
	ds_read_b128 v[216:219], v183 offset:38912
	ds_read_b128 v[226:229], v183 offset:39936
	global_load_lds_dwordx4 v[236:237], off
	v_lshl_add_u64 v[236:237], s[10:11], 0, v[160:161]
	s_mov_b32 m0, s25
	s_nop 0
	global_load_lds_dwordx4 v[236:237], off
	s_waitcnt vmcnt(8)
	s_waitcnt lgkmcnt(0)
	s_barrier
	s_setprio 1
	s_waitcnt lgkmcnt(0)
	v_mfma_f32_16x16x32_bf16 v[126:129], v[130:133], v[172:175], v[126:129]
	v_mfma_f32_16x16x32_bf16 v[122:125], v[138:141], v[172:175], v[122:125]
	v_mfma_f32_16x16x32_bf16 v[110:113], v[130:133], v[200:203], v[110:113]
	v_mfma_f32_16x16x32_bf16 v[106:109], v[138:141], v[200:203], v[106:109]
	v_mfma_f32_16x16x32_bf16 v[98:101], v[130:133], v[208:211], v[98:101]
	v_mfma_f32_16x16x32_bf16 v[90:93], v[138:141], v[208:211], v[90:93]
	v_mfma_f32_16x16x32_bf16 v[82:85], v[130:133], v[216:219], v[82:85]
	v_mfma_f32_16x16x32_bf16 v[74:77], v[138:141], v[216:219], v[74:77]
	v_mfma_f32_16x16x32_bf16 v[126:129], v[134:137], v[176:179], v[126:129]
	v_mfma_f32_16x16x32_bf16 v[122:125], v[142:145], v[176:179], v[122:125]
	v_mfma_f32_16x16x32_bf16 v[110:113], v[134:137], v[204:207], v[110:113]
	v_mfma_f32_16x16x32_bf16 v[106:109], v[142:145], v[204:207], v[106:109]
	v_mfma_f32_16x16x32_bf16 v[98:101], v[134:137], v[212:215], v[98:101]
	v_mfma_f32_16x16x32_bf16 v[90:93], v[142:145], v[212:215], v[90:93]
	v_mfma_f32_16x16x32_bf16 v[82:85], v[134:137], v[226:229], v[82:85]
	v_mfma_f32_16x16x32_bf16 v[74:77], v[142:145], v[226:229], v[74:77]
	v_mfma_f32_16x16x32_bf16 v[118:121], v[146:149], v[172:175], v[118:121]
	v_mfma_f32_16x16x32_bf16 v[114:117], v[154:157], v[172:175], v[114:117]
	v_mfma_f32_16x16x32_bf16 v[102:105], v[146:149], v[200:203], v[102:105]
	v_mfma_f32_16x16x32_bf16 v[94:97], v[154:157], v[200:203], v[94:97]
	v_mfma_f32_16x16x32_bf16 v[86:89], v[146:149], v[208:211], v[86:89]
	v_mfma_f32_16x16x32_bf16 v[78:81], v[154:157], v[208:211], v[78:81]
	v_mfma_f32_16x16x32_bf16 v[70:73], v[146:149], v[216:219], v[70:73]
	v_mfma_f32_16x16x32_bf16 v[66:69], v[154:157], v[216:219], v[66:69]
	v_mfma_f32_16x16x32_bf16 v[118:121], v[150:153], v[176:179], v[118:121]
	v_mfma_f32_16x16x32_bf16 v[114:117], v[168:171], v[176:179], v[114:117]
	v_mfma_f32_16x16x32_bf16 v[102:105], v[150:153], v[204:207], v[102:105]
	v_mfma_f32_16x16x32_bf16 v[94:97], v[168:171], v[204:207], v[94:97]
	v_mfma_f32_16x16x32_bf16 v[86:89], v[150:153], v[212:215], v[86:89]
	v_mfma_f32_16x16x32_bf16 v[78:81], v[168:171], v[212:215], v[78:81]
	v_mfma_f32_16x16x32_bf16 v[70:73], v[150:153], v[226:229], v[70:73]
	v_mfma_f32_16x16x32_bf16 v[66:69], v[168:171], v[226:229], v[66:69]
	s_setprio 0
	s_barrier
	s_add_i32 s10, s52, s19
	v_lshl_add_u64 v[184:185], v[184:185], 0, s[4:5]
	s_mov_b32 m0, s10
	ds_read_b128 v[172:175], v183 offset:49152
	ds_read_b128 v[176:179], v183 offset:50176
	ds_read_b128 v[200:203], v183 offset:51200
	ds_read_b128 v[204:207], v183 offset:52224
	ds_read_b128 v[208:211], v183 offset:53248
	ds_read_b128 v[212:215], v183 offset:54272
	ds_read_b128 v[216:219], v183 offset:55296
	ds_read_b128 v[226:229], v183 offset:56320
	global_load_lds_dwordx4 v[184:185], off
	s_add_i32 m0, s10, 0x2000
	s_add_u32 s8, s8, 0x20080
	v_lshl_add_u64 v[184:185], v[230:231], 0, s[4:5]
	s_addc_u32 s9, s9, 0
	s_add_i32 s10, s53, s19
	global_load_lds_dwordx4 v[184:185], off
	v_lshl_add_u64 v[184:185], s[8:9], 0, v[188:189]
	s_mov_b32 m0, s10
	s_nop 0
	global_load_lds_dwordx4 v[184:185], off
	v_lshl_add_u64 v[184:185], s[8:9], 0, v[158:159]
	s_add_i32 m0, s10, 0x2000
	s_nop 0
	global_load_lds_dwordx4 v[184:185], off
	v_lshl_add_u64 v[184:185], v[232:233], 0, s[4:5]
	s_mov_b32 m0, s28
	s_nop 0
	global_load_lds_dwordx4 v[184:185], off
	v_lshl_add_u64 v[184:185], v[234:235], 0, s[4:5]
	s_mov_b32 m0, s29
	s_nop 0
	global_load_lds_dwordx4 v[184:185], off
	s_waitcnt vmcnt(8)
	s_waitcnt lgkmcnt(0)
	s_barrier
	s_setprio 1
	s_waitcnt lgkmcnt(0)
	v_mfma_f32_16x16x32_bf16 v[62:65], v[130:133], v[172:175], v[62:65]
	v_mfma_f32_16x16x32_bf16 v[58:61], v[138:141], v[172:175], v[58:61]
	v_mfma_f32_16x16x32_bf16 v[50:53], v[130:133], v[200:203], v[50:53]
	v_mfma_f32_16x16x32_bf16 v[42:45], v[138:141], v[200:203], v[42:45]
	v_mfma_f32_16x16x32_bf16 v[34:37], v[130:133], v[208:211], v[34:37]
	v_mfma_f32_16x16x32_bf16 v[26:29], v[138:141], v[208:211], v[26:29]
	v_mfma_f32_16x16x32_bf16 v[18:21], v[130:133], v[216:219], v[18:21]
	v_mfma_f32_16x16x32_bf16 v[10:13], v[138:141], v[216:219], v[10:13]
	v_mfma_f32_16x16x32_bf16 v[62:65], v[134:137], v[176:179], v[62:65]
	v_mfma_f32_16x16x32_bf16 v[58:61], v[142:145], v[176:179], v[58:61]
	v_mfma_f32_16x16x32_bf16 v[50:53], v[134:137], v[204:207], v[50:53]
	v_mfma_f32_16x16x32_bf16 v[42:45], v[142:145], v[204:207], v[42:45]
	v_mfma_f32_16x16x32_bf16 v[34:37], v[134:137], v[212:215], v[34:37]
	v_mfma_f32_16x16x32_bf16 v[26:29], v[142:145], v[212:215], v[26:29]
	v_mfma_f32_16x16x32_bf16 v[18:21], v[134:137], v[226:229], v[18:21]
	v_mfma_f32_16x16x32_bf16 v[10:13], v[142:145], v[226:229], v[10:13]
	v_mfma_f32_16x16x32_bf16 v[54:57], v[146:149], v[172:175], v[54:57]
	v_mfma_f32_16x16x32_bf16 v[46:49], v[154:157], v[172:175], v[46:49]
	v_mfma_f32_16x16x32_bf16 v[38:41], v[146:149], v[200:203], v[38:41]
	v_mfma_f32_16x16x32_bf16 v[30:33], v[154:157], v[200:203], v[30:33]
	v_mfma_f32_16x16x32_bf16 v[22:25], v[146:149], v[208:211], v[22:25]
	v_mfma_f32_16x16x32_bf16 v[14:17], v[154:157], v[208:211], v[14:17]
	v_mfma_f32_16x16x32_bf16 v[6:9], v[146:149], v[216:219], v[6:9]
	v_mfma_f32_16x16x32_bf16 v[2:5], v[154:157], v[216:219], v[2:5]
	v_mfma_f32_16x16x32_bf16 v[54:57], v[150:153], v[176:179], v[54:57]
	v_mfma_f32_16x16x32_bf16 v[46:49], v[168:171], v[176:179], v[46:49]
	v_mfma_f32_16x16x32_bf16 v[38:41], v[150:153], v[204:207], v[38:41]
	v_mfma_f32_16x16x32_bf16 v[30:33], v[168:171], v[204:207], v[30:33]
	v_mfma_f32_16x16x32_bf16 v[22:25], v[150:153], v[212:215], v[22:25]
	v_mfma_f32_16x16x32_bf16 v[14:17], v[168:171], v[212:215], v[14:17]
	v_mfma_f32_16x16x32_bf16 v[6:9], v[150:153], v[226:229], v[6:9]
	v_mfma_f32_16x16x32_bf16 v[2:5], v[168:171], v[226:229], v[2:5]
	s_setprio 0
	s_barrier
	s_add_i32 s51, s51, 2
	s_add_u32 s43, s43, 0x100
	s_addc_u32 s50, s50, 0
	s_add_u32 s0, s0, 0x100
	s_addc_u32 s1, s1, 0
	s_cmp_gt_u32 s51, 5
	s_cbranch_scc0 .LBB0_2962
	v_lshl_or_b32 v132, s35, 8, v182
	v_lshl_add_u32 v130, s36, 8, v180
	v_ashrrev_i32_e32 v133, 31, v132
	v_lshlrev_b64 v[168:169], 1, v[132:133]
	v_ashrrev_i32_e32 v131, 31, v130
	v_lshl_add_u64 v[170:171], s[6:7], 0, v[168:169]
	v_lshlrev_b64 v[172:173], 11, v[130:131]
	v_lshl_add_u64 v[132:133], v[170:171], 0, v[172:173]
	global_load_dwordx4 v[200:203], v[132:133], off
	global_load_dwordx4 v[154:157], v[132:133], off offset:256
	v_or_b32_e32 v132, 16, v130
	v_ashrrev_i32_e32 v133, 31, v132
	v_lshlrev_b64 v[178:179], 11, v[132:133]
	v_lshl_add_u64 v[132:133], v[170:171], 0, v[178:179]
	global_load_dwordx4 v[150:153], v[132:133], off
	global_load_dwordx4 v[146:149], v[132:133], off offset:256
	v_or_b32_e32 v132, 32, v130
	v_ashrrev_i32_e32 v133, 31, v132
	v_lshlrev_b64 v[176:177], 11, v[132:133]
	v_lshl_add_u64 v[132:133], v[170:171], 0, v[176:177]
	global_load_dwordx4 v[142:145], v[132:133], off
	global_load_dwordx4 v[134:137], v[132:133], off offset:256
	v_or_b32_e32 v130, 48, v130
	v_ashrrev_i32_e32 v131, 31, v130
	v_lshlrev_b64 v[174:175], 11, v[130:131]
	v_lshl_add_u64 v[130:131], v[170:171], 0, v[174:175]
	global_load_dwordx4 v[138:141], v[130:131], off
	s_nop 0
	global_load_dwordx4 v[130:133], v[130:131], off offset:256
	s_mov_b64 s[0:1], 0x40000
	s_and_b64 vcc, exec, s[38:39]
	s_mov_b32 s35, s40
	s_mov_b32 s36, s42
	s_mov_b64 s[8:9], s[44:45]
	s_waitcnt vmcnt(0)
	v_lshlrev_b32_e32 v184, 16, v200
	v_mul_f32_e32 v126, v126, v184
	v_and_b32_e32 v184, 0xffff0000, v200
	v_mul_f32_e32 v127, v127, v184
	v_lshlrev_b32_e32 v184, 16, v201
	v_mul_f32_e32 v128, v128, v184
	v_and_b32_e32 v184, 0xffff0000, v201
	v_mul_f32_e32 v129, v129, v184
	v_lshlrev_b32_e32 v184, 16, v202
	v_mul_f32_e32 v184, v122, v184
	v_and_b32_e32 v122, 0xffff0000, v202
	v_mul_f32_e32 v185, v123, v122
	v_lshlrev_b32_e32 v122, 16, v203
	v_mul_f32_e32 v200, v124, v122
	v_and_b32_e32 v122, 0xffff0000, v203
	v_mul_f32_e32 v125, v125, v122
	v_cvt_pk_bf16_f32 v122, v126, v127
	v_lshl_add_u64 v[126:127], s[6:7], 0, v[172:173]
	v_lshl_add_u64 v[126:127], v[126:127], 0, v[168:169]
	v_cvt_pk_bf16_f32 v123, v128, v129
	v_cvt_pk_bf16_f32 v124, v184, v185
	v_cvt_pk_bf16_f32 v125, v200, v125
	global_store_dwordx4 v[126:127], v[122:125], off
	s_nop 1
	v_lshlrev_b32_e32 v122, 16, v154
	v_mul_f32_e32 v118, v118, v122
	v_and_b32_e32 v122, 0xffff0000, v154
	v_mul_f32_e32 v119, v119, v122
	v_lshlrev_b32_e32 v122, 16, v155
	v_mul_f32_e32 v120, v120, v122
	v_and_b32_e32 v122, 0xffff0000, v155
	v_mul_f32_e32 v121, v121, v122
	v_lshlrev_b32_e32 v122, 16, v156
	v_mul_f32_e32 v122, v114, v122
	v_and_b32_e32 v114, 0xffff0000, v156
	v_mul_f32_e32 v123, v115, v114
	v_lshlrev_b32_e32 v114, 16, v157
	v_mul_f32_e32 v124, v116, v114
	v_and_b32_e32 v114, 0xffff0000, v157
	v_mul_f32_e32 v117, v117, v114
	v_cvt_pk_bf16_f32 v114, v118, v119
	v_cvt_pk_bf16_f32 v115, v120, v121
	v_cvt_pk_bf16_f32 v116, v122, v123
	v_cvt_pk_bf16_f32 v117, v124, v117
	global_store_dwordx4 v[126:127], v[114:117], off offset:256
	s_nop 1
	v_lshlrev_b32_e32 v114, 16, v150
	v_mul_f32_e32 v110, v110, v114
	v_and_b32_e32 v114, 0xffff0000, v150
	v_mul_f32_e32 v111, v111, v114
	v_lshlrev_b32_e32 v114, 16, v151
	v_mul_f32_e32 v112, v112, v114
	v_and_b32_e32 v114, 0xffff0000, v151
	v_mul_f32_e32 v113, v113, v114
	v_lshlrev_b32_e32 v114, 16, v152
	v_mul_f32_e32 v114, v106, v114
	v_and_b32_e32 v106, 0xffff0000, v152
	v_mul_f32_e32 v115, v107, v106
	v_lshlrev_b32_e32 v106, 16, v153
	v_mul_f32_e32 v116, v108, v106
	v_and_b32_e32 v106, 0xffff0000, v153
	v_mul_f32_e32 v109, v109, v106
	v_cvt_pk_bf16_f32 v106, v110, v111
	v_lshl_add_u64 v[110:111], s[6:7], 0, v[178:179]
	v_lshl_add_u64 v[110:111], v[110:111], 0, v[168:169]
	v_cvt_pk_bf16_f32 v107, v112, v113
	v_cvt_pk_bf16_f32 v108, v114, v115
	v_cvt_pk_bf16_f32 v109, v116, v109
	global_store_dwordx4 v[110:111], v[106:109], off
	s_nop 1
	v_lshlrev_b32_e32 v106, 16, v146
	v_mul_f32_e32 v102, v102, v106
	v_and_b32_e32 v106, 0xffff0000, v146
	v_mul_f32_e32 v103, v103, v106
	v_lshlrev_b32_e32 v106, 16, v147
	v_mul_f32_e32 v104, v104, v106
	v_and_b32_e32 v106, 0xffff0000, v147
	v_mul_f32_e32 v105, v105, v106
	v_lshlrev_b32_e32 v106, 16, v148
	v_mul_f32_e32 v106, v94, v106
	v_and_b32_e32 v94, 0xffff0000, v148
	v_mul_f32_e32 v107, v95, v94
	v_lshlrev_b32_e32 v94, 16, v149
	v_mul_f32_e32 v108, v96, v94
	v_and_b32_e32 v94, 0xffff0000, v149
	v_mul_f32_e32 v97, v97, v94
	v_cvt_pk_bf16_f32 v94, v102, v103
	v_cvt_pk_bf16_f32 v95, v104, v105
	v_cvt_pk_bf16_f32 v96, v106, v107
	v_cvt_pk_bf16_f32 v97, v108, v97
	global_store_dwordx4 v[110:111], v[94:97], off offset:256
	s_nop 1
	v_lshlrev_b32_e32 v94, 16, v142
	v_mul_f32_e32 v94, v98, v94
	v_lshlrev_b32_e32 v98, 16, v144
	v_and_b32_e32 v95, 0xffff0000, v142
	v_mul_f32_e32 v98, v90, v98
	v_and_b32_e32 v90, 0xffff0000, v144
	v_mul_f32_e32 v95, v99, v95
	v_lshlrev_b32_e32 v96, 16, v143
	v_mul_f32_e32 v99, v91, v90
	v_lshlrev_b32_e32 v90, 16, v145
	v_mul_f32_e32 v96, v100, v96
	v_mul_f32_e32 v100, v92, v90
	v_and_b32_e32 v90, 0xffff0000, v145
	v_mul_f32_e32 v93, v93, v90
	v_cvt_pk_bf16_f32 v90, v94, v95
	v_lshl_add_u64 v[94:95], s[6:7], 0, v[176:177]
	v_and_b32_e32 v97, 0xffff0000, v143
	v_lshl_add_u64 v[94:95], v[94:95], 0, v[168:169]
	v_mul_f32_e32 v97, v101, v97
	v_cvt_pk_bf16_f32 v91, v96, v97
	v_cvt_pk_bf16_f32 v92, v98, v99
	v_cvt_pk_bf16_f32 v93, v100, v93
	global_store_dwordx4 v[94:95], v[90:93], off
	v_lshl_add_u64 v[98:99], v[172:173], 0, s[0:1]
	s_mov_b64 s[0:1], 0x48000
	v_lshlrev_b32_e32 v90, 16, v134
	v_mul_f32_e32 v86, v86, v90
	v_and_b32_e32 v90, 0xffff0000, v134
	v_mul_f32_e32 v87, v87, v90
	v_lshlrev_b32_e32 v90, 16, v135
	v_mul_f32_e32 v88, v88, v90
	v_and_b32_e32 v90, 0xffff0000, v135
	v_mul_f32_e32 v89, v89, v90
	v_lshlrev_b32_e32 v90, 16, v136
	v_mul_f32_e32 v90, v78, v90
	v_and_b32_e32 v78, 0xffff0000, v136
	v_mul_f32_e32 v91, v79, v78
	v_lshlrev_b32_e32 v78, 16, v137
	v_mul_f32_e32 v92, v80, v78
	v_and_b32_e32 v78, 0xffff0000, v137
	v_mul_f32_e32 v81, v81, v78
	v_cvt_pk_bf16_f32 v78, v86, v87
	v_cvt_pk_bf16_f32 v79, v88, v89
	v_cvt_pk_bf16_f32 v80, v90, v91
	v_cvt_pk_bf16_f32 v81, v92, v81
	global_store_dwordx4 v[94:95], v[78:81], off offset:256
	v_lshl_add_u64 v[100:101], v[172:173], 0, s[0:1]
	s_mov_b64 s[0:1], 0x50000
	v_lshlrev_b32_e32 v78, 16, v138
	v_mul_f32_e32 v78, v82, v78
	v_lshlrev_b32_e32 v82, 16, v140
	v_and_b32_e32 v79, 0xffff0000, v138
	v_mul_f32_e32 v82, v74, v82
	v_and_b32_e32 v74, 0xffff0000, v140
	v_mul_f32_e32 v79, v83, v79
	v_lshlrev_b32_e32 v80, 16, v139
	v_mul_f32_e32 v83, v75, v74
	v_lshlrev_b32_e32 v74, 16, v141
	v_mul_f32_e32 v80, v84, v80
	v_mul_f32_e32 v84, v76, v74
	v_and_b32_e32 v74, 0xffff0000, v141
	v_mul_f32_e32 v77, v77, v74
	v_cvt_pk_bf16_f32 v74, v78, v79
	v_lshl_add_u64 v[78:79], s[6:7], 0, v[174:175]
	v_and_b32_e32 v81, 0xffff0000, v139
	v_lshl_add_u64 v[78:79], v[78:79], 0, v[168:169]
	v_mul_f32_e32 v81, v85, v81
	v_cvt_pk_bf16_f32 v75, v80, v81
	v_cvt_pk_bf16_f32 v76, v82, v83
	v_cvt_pk_bf16_f32 v77, v84, v77
	global_store_dwordx4 v[78:79], v[74:77], off
	v_lshl_add_u64 v[102:103], v[172:173], 0, s[0:1]
	v_lshl_add_u64 v[86:87], v[170:171], 0, v[102:103]
	v_lshlrev_b32_e32 v74, 16, v130
	v_mul_f32_e32 v70, v70, v74
	v_and_b32_e32 v74, 0xffff0000, v130
	v_mul_f32_e32 v71, v71, v74
	v_lshlrev_b32_e32 v74, 16, v131
	v_mul_f32_e32 v72, v72, v74
	v_and_b32_e32 v74, 0xffff0000, v131
	v_mul_f32_e32 v73, v73, v74
	v_lshlrev_b32_e32 v74, 16, v132
	v_mul_f32_e32 v74, v66, v74
	v_and_b32_e32 v66, 0xffff0000, v132
	v_mul_f32_e32 v75, v67, v66
	v_lshlrev_b32_e32 v66, 16, v133
	v_mul_f32_e32 v76, v68, v66
	v_and_b32_e32 v66, 0xffff0000, v133
	v_mul_f32_e32 v69, v69, v66
	v_cvt_pk_bf16_f32 v66, v70, v71
	v_cvt_pk_bf16_f32 v67, v72, v73
	v_cvt_pk_bf16_f32 v68, v74, v75
	v_cvt_pk_bf16_f32 v69, v76, v69
	global_store_dwordx4 v[78:79], v[66:69], off offset:256
	v_lshl_add_u64 v[70:71], v[170:171], 0, v[98:99]
	global_load_dwordx4 v[66:69], v[70:71], off
	s_nop 0
	global_load_dwordx4 v[70:73], v[70:71], off offset:256
	v_lshl_add_u64 v[78:79], v[170:171], 0, v[100:101]
	global_load_dwordx4 v[74:77], v[78:79], off
	s_nop 0
	global_load_dwordx4 v[78:81], v[78:79], off offset:256
	s_nop 0
	global_load_dwordx4 v[82:85], v[86:87], off
	s_nop 0
	global_load_dwordx4 v[86:89], v[86:87], off offset:256
	s_mov_b64 s[0:1], 0x58000
	v_lshl_add_u64 v[104:105], v[172:173], 0, s[0:1]
	v_lshl_add_u64 v[94:95], v[170:171], 0, v[104:105]
	global_load_dwordx4 v[90:93], v[94:95], off
	s_nop 0
	global_load_dwordx4 v[94:97], v[94:95], off offset:256
	s_mov_b64 s[0:1], s[48:49]
	s_waitcnt vmcnt(7)
	v_lshlrev_b32_e32 v106, 16, v66
	v_and_b32_e32 v66, 0xffff0000, v66
	v_mul_f32_e32 v63, v63, v66
	v_lshlrev_b32_e32 v66, 16, v67
	v_mul_f32_e32 v64, v64, v66
	v_and_b32_e32 v66, 0xffff0000, v67
	v_mul_f32_e32 v65, v65, v66
	v_lshlrev_b32_e32 v66, 16, v68
	v_mul_f32_e32 v66, v58, v66
	v_and_b32_e32 v58, 0xffff0000, v68
	v_mul_f32_e32 v67, v59, v58
	v_lshlrev_b32_e32 v58, 16, v69
	v_mul_f32_e32 v62, v62, v106
	v_mul_f32_e32 v68, v60, v58
	v_and_b32_e32 v58, 0xffff0000, v69
	v_mul_f32_e32 v61, v61, v58
	v_cvt_pk_bf16_f32 v58, v62, v63
	v_lshl_add_u64 v[62:63], s[6:7], 0, v[98:99]
	v_lshl_add_u64 v[62:63], v[62:63], 0, v[168:169]
	v_cvt_pk_bf16_f32 v59, v64, v65
	v_cvt_pk_bf16_f32 v60, v66, v67
	v_cvt_pk_bf16_f32 v61, v68, v61
	global_store_dwordx4 v[62:63], v[58:61], off
	s_waitcnt vmcnt(7)
	s_nop 0
	v_lshlrev_b32_e32 v58, 16, v70
	v_mul_f32_e32 v54, v54, v58
	v_and_b32_e32 v58, 0xffff0000, v70
	v_mul_f32_e32 v55, v55, v58
	v_lshlrev_b32_e32 v58, 16, v71
	v_mul_f32_e32 v56, v56, v58
	v_and_b32_e32 v58, 0xffff0000, v71
	v_mul_f32_e32 v57, v57, v58
	v_lshlrev_b32_e32 v58, 16, v72
	v_mul_f32_e32 v58, v46, v58
	v_and_b32_e32 v46, 0xffff0000, v72
	v_mul_f32_e32 v59, v47, v46
	v_lshlrev_b32_e32 v46, 16, v73
	v_mul_f32_e32 v60, v48, v46
	v_and_b32_e32 v46, 0xffff0000, v73
	v_mul_f32_e32 v49, v49, v46
	v_cvt_pk_bf16_f32 v46, v54, v55
	v_cvt_pk_bf16_f32 v47, v56, v57
	v_cvt_pk_bf16_f32 v48, v58, v59
	v_cvt_pk_bf16_f32 v49, v60, v49
	global_store_dwordx4 v[62:63], v[46:49], off offset:256
	s_waitcnt vmcnt(7)
	s_nop 0
	v_lshlrev_b32_e32 v46, 16, v74
	v_mul_f32_e32 v46, v50, v46
	v_lshlrev_b32_e32 v50, 16, v76
	v_and_b32_e32 v47, 0xffff0000, v74
	v_mul_f32_e32 v50, v42, v50
	v_and_b32_e32 v42, 0xffff0000, v76
	v_mul_f32_e32 v47, v51, v47
	v_lshlrev_b32_e32 v48, 16, v75
	v_mul_f32_e32 v51, v43, v42
	v_lshlrev_b32_e32 v42, 16, v77
	v_mul_f32_e32 v48, v52, v48
	v_mul_f32_e32 v52, v44, v42
	v_and_b32_e32 v42, 0xffff0000, v77
	v_mul_f32_e32 v45, v45, v42
	v_cvt_pk_bf16_f32 v42, v46, v47
	v_lshl_add_u64 v[46:47], s[6:7], 0, v[100:101]
	v_and_b32_e32 v49, 0xffff0000, v75
	v_lshl_add_u64 v[46:47], v[46:47], 0, v[168:169]
	v_mul_f32_e32 v49, v53, v49
	v_cvt_pk_bf16_f32 v43, v48, v49
	v_cvt_pk_bf16_f32 v44, v50, v51
	v_cvt_pk_bf16_f32 v45, v52, v45
	global_store_dwordx4 v[46:47], v[42:45], off
	s_waitcnt vmcnt(7)
	s_nop 0
	v_lshlrev_b32_e32 v42, 16, v78
	v_mul_f32_e32 v38, v38, v42
	v_and_b32_e32 v42, 0xffff0000, v78
	v_mul_f32_e32 v39, v39, v42
	v_lshlrev_b32_e32 v42, 16, v79
	v_mul_f32_e32 v40, v40, v42
	v_and_b32_e32 v42, 0xffff0000, v79
	v_mul_f32_e32 v41, v41, v42
	v_lshlrev_b32_e32 v42, 16, v80
	v_mul_f32_e32 v42, v30, v42
	v_and_b32_e32 v30, 0xffff0000, v80
	v_mul_f32_e32 v43, v31, v30
	v_lshlrev_b32_e32 v30, 16, v81
	v_mul_f32_e32 v44, v32, v30
	v_and_b32_e32 v30, 0xffff0000, v81
	v_mul_f32_e32 v33, v33, v30
	v_cvt_pk_bf16_f32 v30, v38, v39
	v_cvt_pk_bf16_f32 v31, v40, v41
	v_cvt_pk_bf16_f32 v32, v42, v43
	v_cvt_pk_bf16_f32 v33, v44, v33
	global_store_dwordx4 v[46:47], v[30:33], off offset:256
	s_waitcnt vmcnt(7)
	s_nop 0
	v_lshlrev_b32_e32 v30, 16, v82
	v_mul_f32_e32 v30, v34, v30
	v_lshlrev_b32_e32 v34, 16, v84
	v_and_b32_e32 v31, 0xffff0000, v82
	v_mul_f32_e32 v34, v26, v34
	v_and_b32_e32 v26, 0xffff0000, v84
	v_mul_f32_e32 v31, v35, v31
	v_lshlrev_b32_e32 v32, 16, v83
	v_mul_f32_e32 v35, v27, v26
	v_lshlrev_b32_e32 v26, 16, v85
	v_mul_f32_e32 v32, v36, v32
	v_mul_f32_e32 v36, v28, v26
	v_and_b32_e32 v26, 0xffff0000, v85
	v_mul_f32_e32 v29, v29, v26
	v_cvt_pk_bf16_f32 v26, v30, v31
	v_lshl_add_u64 v[30:31], s[6:7], 0, v[102:103]
	v_and_b32_e32 v33, 0xffff0000, v83
	v_lshl_add_u64 v[30:31], v[30:31], 0, v[168:169]
	v_mul_f32_e32 v33, v37, v33
	v_cvt_pk_bf16_f32 v27, v32, v33
	v_cvt_pk_bf16_f32 v28, v34, v35
	v_cvt_pk_bf16_f32 v29, v36, v29
	global_store_dwordx4 v[30:31], v[26:29], off
	s_waitcnt vmcnt(7)
	s_nop 0
	v_lshlrev_b32_e32 v26, 16, v86
	v_mul_f32_e32 v22, v22, v26
	v_and_b32_e32 v26, 0xffff0000, v86
	v_mul_f32_e32 v23, v23, v26
	v_lshlrev_b32_e32 v26, 16, v87
	v_mul_f32_e32 v24, v24, v26
	v_and_b32_e32 v26, 0xffff0000, v87
	v_mul_f32_e32 v25, v25, v26
	v_lshlrev_b32_e32 v26, 16, v88
	v_mul_f32_e32 v26, v14, v26
	v_and_b32_e32 v14, 0xffff0000, v88
	v_mul_f32_e32 v27, v15, v14
	v_lshlrev_b32_e32 v14, 16, v89
	v_mul_f32_e32 v28, v16, v14
	v_and_b32_e32 v14, 0xffff0000, v89
	v_mul_f32_e32 v17, v17, v14
	v_cvt_pk_bf16_f32 v14, v22, v23
	v_cvt_pk_bf16_f32 v15, v24, v25
	v_cvt_pk_bf16_f32 v16, v26, v27
	v_cvt_pk_bf16_f32 v17, v28, v17
	global_store_dwordx4 v[30:31], v[14:17], off offset:256
	s_waitcnt vmcnt(7)
	s_nop 0
	v_lshlrev_b32_e32 v14, 16, v90
	v_mul_f32_e32 v14, v18, v14
	v_lshlrev_b32_e32 v18, 16, v92
	v_and_b32_e32 v15, 0xffff0000, v90
	v_mul_f32_e32 v18, v10, v18
	v_and_b32_e32 v10, 0xffff0000, v92
	v_mul_f32_e32 v15, v19, v15
	v_lshlrev_b32_e32 v16, 16, v91
	v_mul_f32_e32 v19, v11, v10
	v_lshlrev_b32_e32 v10, 16, v93
	v_mul_f32_e32 v16, v20, v16
	v_mul_f32_e32 v20, v12, v10
	v_and_b32_e32 v10, 0xffff0000, v93
	v_mul_f32_e32 v13, v13, v10
	v_cvt_pk_bf16_f32 v10, v14, v15
	v_lshl_add_u64 v[14:15], s[6:7], 0, v[104:105]
	v_and_b32_e32 v17, 0xffff0000, v91
	v_lshl_add_u64 v[14:15], v[14:15], 0, v[168:169]
	v_mul_f32_e32 v17, v21, v17
	v_cvt_pk_bf16_f32 v11, v16, v17
	v_cvt_pk_bf16_f32 v12, v18, v19
	v_cvt_pk_bf16_f32 v13, v20, v13
	global_store_dwordx4 v[14:15], v[10:13], off
	s_waitcnt vmcnt(7)
	s_nop 0
	v_lshlrev_b32_e32 v10, 16, v94
	v_mul_f32_e32 v6, v6, v10
	v_and_b32_e32 v10, 0xffff0000, v94
	v_mul_f32_e32 v7, v7, v10
	v_lshlrev_b32_e32 v10, 16, v95
	v_mul_f32_e32 v8, v8, v10
	v_and_b32_e32 v10, 0xffff0000, v95
	v_mul_f32_e32 v9, v9, v10
	v_lshlrev_b32_e32 v10, 16, v96
	v_mul_f32_e32 v10, v2, v10
	v_and_b32_e32 v2, 0xffff0000, v96
	v_mul_f32_e32 v11, v3, v2
	v_lshlrev_b32_e32 v2, 16, v97
	v_mul_f32_e32 v12, v4, v2
	v_and_b32_e32 v2, 0xffff0000, v97
	v_mul_f32_e32 v5, v5, v2
	v_cvt_pk_bf16_f32 v2, v6, v7
	v_cvt_pk_bf16_f32 v3, v8, v9
	v_cvt_pk_bf16_f32 v4, v10, v11
	v_cvt_pk_bf16_f32 v5, v12, v5
	global_store_dwordx4 v[14:15], v[2:5], off offset:256
	s_cbranch_vccz .LBB0_2955
	s_waitcnt vmcnt(0)
	s_cmpk_gt_u32 s14, 0xff
	s_cbranch_scc1 .LBB0_2966
	s_barrier

.LBB0_3096:
	s_add_u32 s8, s0, 0xfffe0080
	s_addc_u32 s9, s1, -1
	s_add_i32 s52, 0, 0x10000
	s_cmp_eq_u32 s51, 4
	s_cselect_b32 s11, s12, s9
	s_cselect_b32 s10, s13, s8
	s_cselect_b32 s9, s37, s50
	s_cselect_b32 s8, s43, s45
	s_add_i32 s54, 0, 0x14000
	v_add_u32_e32 v142, s52, v227
	v_add_u32_e32 v158, s54, v227
	ds_read_b128 v[130:133], v142
	ds_read_b128 v[134:137], v142 offset:1024
	ds_read_b128 v[138:141], v142 offset:2048
	ds_read_b128 v[142:145], v142 offset:3072
	ds_read_b128 v[146:149], v158
	ds_read_b128 v[150:153], v158 offset:1024
	ds_read_b128 v[154:157], v158 offset:2048
	ds_read_b128 v[158:161], v158 offset:3072
	v_lshl_add_u64 v[218:219], s[0:1], 0, v[208:209]
	s_add_i32 m0, s20, 0xc000
	ds_read_b128 v[162:165], v229
	ds_read_b128 v[166:169], v229 offset:1024
	ds_read_b128 v[170:173], v229 offset:2048
	ds_read_b128 v[174:177], v229 offset:3072
	ds_read_b128 v[178:181], v229 offset:4096
	ds_read_b128 v[182:185], v229 offset:5120
	ds_read_b128 v[210:213], v229 offset:6144
	ds_read_b128 v[214:217], v229 offset:7168
	global_load_lds_dwordx4 v[218:219], off
	v_lshl_add_u64 v[218:219], s[0:1], 0, v[206:207]
	s_add_i32 m0, s20, 0xe000
	s_nop 0
	global_load_lds_dwordx4 v[218:219], off
	s_waitcnt vmcnt(8)
	s_waitcnt lgkmcnt(0)
	s_barrier
	s_setprio 1
	s_waitcnt lgkmcnt(0)
	v_mfma_f32_16x16x32_bf16 v[126:129], v[130:133], v[162:165], v[126:129]
	v_mfma_f32_16x16x32_bf16 v[122:125], v[138:141], v[162:165], v[122:125]
	v_mfma_f32_16x16x32_bf16 v[110:113], v[130:133], v[170:173], v[110:113]
	v_mfma_f32_16x16x32_bf16 v[106:109], v[138:141], v[170:173], v[106:109]
	v_mfma_f32_16x16x32_bf16 v[94:97], v[130:133], v[178:181], v[94:97]
	v_mfma_f32_16x16x32_bf16 v[90:93], v[138:141], v[178:181], v[90:93]
	v_mfma_f32_16x16x32_bf16 v[78:81], v[130:133], v[210:213], v[78:81]
	v_mfma_f32_16x16x32_bf16 v[74:77], v[138:141], v[210:213], v[74:77]
	v_mfma_f32_16x16x32_bf16 v[126:129], v[134:137], v[166:169], v[126:129]
	v_mfma_f32_16x16x32_bf16 v[122:125], v[142:145], v[166:169], v[122:125]
	v_mfma_f32_16x16x32_bf16 v[110:113], v[134:137], v[174:177], v[110:113]
	v_mfma_f32_16x16x32_bf16 v[106:109], v[142:145], v[174:177], v[106:109]
	v_mfma_f32_16x16x32_bf16 v[94:97], v[134:137], v[182:185], v[94:97]
	v_mfma_f32_16x16x32_bf16 v[90:93], v[142:145], v[182:185], v[90:93]
	v_mfma_f32_16x16x32_bf16 v[78:81], v[134:137], v[214:217], v[78:81]
	v_mfma_f32_16x16x32_bf16 v[74:77], v[142:145], v[214:217], v[74:77]
	v_mfma_f32_16x16x32_bf16 v[118:121], v[146:149], v[162:165], v[118:121]
	v_mfma_f32_16x16x32_bf16 v[114:117], v[154:157], v[162:165], v[114:117]
	v_mfma_f32_16x16x32_bf16 v[102:105], v[146:149], v[170:173], v[102:105]
	v_mfma_f32_16x16x32_bf16 v[98:101], v[154:157], v[170:173], v[98:101]
	v_mfma_f32_16x16x32_bf16 v[86:89], v[146:149], v[178:181], v[86:89]
	v_mfma_f32_16x16x32_bf16 v[82:85], v[154:157], v[178:181], v[82:85]
	v_mfma_f32_16x16x32_bf16 v[70:73], v[146:149], v[210:213], v[70:73]
	v_mfma_f32_16x16x32_bf16 v[66:69], v[154:157], v[210:213], v[66:69]
	v_mfma_f32_16x16x32_bf16 v[118:121], v[150:153], v[166:169], v[118:121]
	v_mfma_f32_16x16x32_bf16 v[114:117], v[158:161], v[166:169], v[114:117]
	v_mfma_f32_16x16x32_bf16 v[102:105], v[150:153], v[174:177], v[102:105]
	v_mfma_f32_16x16x32_bf16 v[98:101], v[158:161], v[174:177], v[98:101]
	v_mfma_f32_16x16x32_bf16 v[86:89], v[150:153], v[182:185], v[86:89]
	v_mfma_f32_16x16x32_bf16 v[82:85], v[158:161], v[182:185], v[82:85]
	v_mfma_f32_16x16x32_bf16 v[70:73], v[150:153], v[214:217], v[70:73]
	v_mfma_f32_16x16x32_bf16 v[66:69], v[158:161], v[214:217], v[66:69]
	s_setprio 0
	s_barrier
	s_add_i32 s52, s52, s19
	v_lshl_add_u64 v[218:219], s[8:9], 0, v[188:189]
	s_mov_b32 m0, s52
	ds_read_b128 v[162:165], v229 offset:16384
	ds_read_b128 v[166:169], v229 offset:17408
	ds_read_b128 v[170:173], v229 offset:18432
	ds_read_b128 v[174:177], v229 offset:19456
	ds_read_b128 v[178:181], v229 offset:20480
	ds_read_b128 v[182:185], v229 offset:21504
	ds_read_b128 v[210:213], v229 offset:22528
	ds_read_b128 v[214:217], v229 offset:23552
	global_load_lds_dwordx4 v[218:219], off
	s_add_i32 m0, s52, 0x2000
	s_add_u32 s52, s8, 0x20000
	v_lshl_add_u64 v[230:231], s[8:9], 0, v[200:201]
	s_addc_u32 s53, s9, 0
	s_add_i32 s54, s54, s19
	global_load_lds_dwordx4 v[230:231], off
	v_lshl_add_u64 v[232:233], s[52:53], 0, v[188:189]
	s_mov_b32 m0, s54
	v_lshl_add_u64 v[234:235], s[10:11], 0, v[202:203]
	global_load_lds_dwordx4 v[232:233], off
	v_lshl_add_u64 v[232:233], s[52:53], 0, v[200:201]
	s_add_i32 m0, s54, 0x2000
	s_nop 0
	global_load_lds_dwordx4 v[232:233], off
	v_lshl_add_u64 v[232:233], s[10:11], 0, v[204:205]
	s_mov_b32 m0, s20
	s_nop 0
	global_load_lds_dwordx4 v[232:233], off
	s_mov_b32 m0, s21
	s_nop 0
	global_load_lds_dwordx4 v[234:235], off
	s_waitcnt vmcnt(8)
	s_waitcnt lgkmcnt(0)
	s_barrier
	s_setprio 1
	s_waitcnt lgkmcnt(0)
	v_mfma_f32_16x16x32_bf16 v[62:65], v[130:133], v[162:165], v[62:65]
	v_mfma_f32_16x16x32_bf16 v[58:61], v[138:141], v[162:165], v[58:61]
	v_mfma_f32_16x16x32_bf16 v[46:49], v[130:133], v[170:173], v[46:49]
	v_mfma_f32_16x16x32_bf16 v[42:45], v[138:141], v[170:173], v[42:45]
	v_mfma_f32_16x16x32_bf16 v[30:33], v[130:133], v[178:181], v[30:33]
	v_mfma_f32_16x16x32_bf16 v[26:29], v[138:141], v[178:181], v[26:29]
	v_mfma_f32_16x16x32_bf16 v[14:17], v[130:133], v[210:213], v[14:17]
	v_mfma_f32_16x16x32_bf16 v[10:13], v[138:141], v[210:213], v[10:13]
	v_mfma_f32_16x16x32_bf16 v[62:65], v[134:137], v[166:169], v[62:65]
	v_mfma_f32_16x16x32_bf16 v[58:61], v[142:145], v[166:169], v[58:61]
	v_mfma_f32_16x16x32_bf16 v[46:49], v[134:137], v[174:177], v[46:49]
	v_mfma_f32_16x16x32_bf16 v[42:45], v[142:145], v[174:177], v[42:45]
	v_mfma_f32_16x16x32_bf16 v[30:33], v[134:137], v[182:185], v[30:33]
	v_mfma_f32_16x16x32_bf16 v[26:29], v[142:145], v[182:185], v[26:29]
	v_mfma_f32_16x16x32_bf16 v[14:17], v[134:137], v[214:217], v[14:17]
	v_mfma_f32_16x16x32_bf16 v[10:13], v[142:145], v[214:217], v[10:13]
	v_mfma_f32_16x16x32_bf16 v[54:57], v[146:149], v[162:165], v[54:57]
	v_mfma_f32_16x16x32_bf16 v[50:53], v[154:157], v[162:165], v[50:53]
	v_mfma_f32_16x16x32_bf16 v[38:41], v[146:149], v[170:173], v[38:41]
	v_mfma_f32_16x16x32_bf16 v[34:37], v[154:157], v[170:173], v[34:37]
	v_mfma_f32_16x16x32_bf16 v[22:25], v[146:149], v[178:181], v[22:25]
	v_mfma_f32_16x16x32_bf16 v[18:21], v[154:157], v[178:181], v[18:21]
	v_mfma_f32_16x16x32_bf16 v[6:9], v[146:149], v[210:213], v[6:9]
	v_mfma_f32_16x16x32_bf16 v[2:5], v[154:157], v[210:213], v[2:5]
	v_mfma_f32_16x16x32_bf16 v[54:57], v[150:153], v[166:169], v[54:57]
	v_mfma_f32_16x16x32_bf16 v[50:53], v[158:161], v[166:169], v[50:53]
	v_mfma_f32_16x16x32_bf16 v[38:41], v[150:153], v[174:177], v[38:41]
	v_mfma_f32_16x16x32_bf16 v[34:37], v[158:161], v[174:177], v[34:37]
	v_mfma_f32_16x16x32_bf16 v[22:25], v[150:153], v[182:185], v[22:25]
	v_mfma_f32_16x16x32_bf16 v[18:21], v[158:161], v[182:185], v[18:21]
	v_mfma_f32_16x16x32_bf16 v[6:9], v[150:153], v[214:217], v[6:9]
	v_mfma_f32_16x16x32_bf16 v[2:5], v[158:161], v[214:217], v[2:5]
	s_setprio 0
	s_barrier
	s_add_i32 s52, 0, 0x18000
	s_add_i32 s53, 0, 0x1c000
	v_add_u32_e32 v142, s52, v227
	v_add_u32_e32 v158, s53, v227
	ds_read_b128 v[130:133], v142
	ds_read_b128 v[134:137], v142 offset:1024
	ds_read_b128 v[138:141], v142 offset:2048
	ds_read_b128 v[142:145], v142 offset:3072
	ds_read_b128 v[146:149], v158
	ds_read_b128 v[150:153], v158 offset:1024
	ds_read_b128 v[154:157], v158 offset:2048
	ds_read_b128 v[158:161], v158 offset:3072
	s_add_u32 s10, s10, 0x20000
	s_addc_u32 s11, s11, 0
	s_mov_b32 m0, s24
	v_lshl_add_u64 v[236:237], s[10:11], 0, v[204:205]
	ds_read_b128 v[162:165], v229 offset:32768
	ds_read_b128 v[166:169], v229 offset:33792
	ds_read_b128 v[170:173], v229 offset:34816
	ds_read_b128 v[174:177], v229 offset:35840
	ds_read_b128 v[178:181], v229 offset:36864
	ds_read_b128 v[182:185], v229 offset:37888
	ds_read_b128 v[210:213], v229 offset:38912
	ds_read_b128 v[214:217], v229 offset:39936
	global_load_lds_dwordx4 v[236:237], off
	v_lshl_add_u64 v[236:237], s[10:11], 0, v[202:203]
	s_mov_b32 m0, s25
	s_nop 0
	global_load_lds_dwordx4 v[236:237], off
	s_waitcnt vmcnt(8)
	s_waitcnt lgkmcnt(0)
	s_barrier
	s_setprio 1
	s_waitcnt lgkmcnt(0)
	v_mfma_f32_16x16x32_bf16 v[126:129], v[130:133], v[162:165], v[126:129]
	v_mfma_f32_16x16x32_bf16 v[122:125], v[138:141], v[162:165], v[122:125]
	v_mfma_f32_16x16x32_bf16 v[110:113], v[130:133], v[170:173], v[110:113]
	v_mfma_f32_16x16x32_bf16 v[106:109], v[138:141], v[170:173], v[106:109]
	v_mfma_f32_16x16x32_bf16 v[94:97], v[130:133], v[178:181], v[94:97]
	v_mfma_f32_16x16x32_bf16 v[90:93], v[138:141], v[178:181], v[90:93]
	v_mfma_f32_16x16x32_bf16 v[78:81], v[130:133], v[210:213], v[78:81]
	v_mfma_f32_16x16x32_bf16 v[74:77], v[138:141], v[210:213], v[74:77]
	v_mfma_f32_16x16x32_bf16 v[126:129], v[134:137], v[166:169], v[126:129]
	v_mfma_f32_16x16x32_bf16 v[122:125], v[142:145], v[166:169], v[122:125]
	v_mfma_f32_16x16x32_bf16 v[110:113], v[134:137], v[174:177], v[110:113]
	v_mfma_f32_16x16x32_bf16 v[106:109], v[142:145], v[174:177], v[106:109]
	v_mfma_f32_16x16x32_bf16 v[94:97], v[134:137], v[182:185], v[94:97]
	v_mfma_f32_16x16x32_bf16 v[90:93], v[142:145], v[182:185], v[90:93]
	v_mfma_f32_16x16x32_bf16 v[78:81], v[134:137], v[214:217], v[78:81]
	v_mfma_f32_16x16x32_bf16 v[74:77], v[142:145], v[214:217], v[74:77]
	v_mfma_f32_16x16x32_bf16 v[118:121], v[146:149], v[162:165], v[118:121]
	v_mfma_f32_16x16x32_bf16 v[114:117], v[154:157], v[162:165], v[114:117]
	v_mfma_f32_16x16x32_bf16 v[102:105], v[146:149], v[170:173], v[102:105]
	v_mfma_f32_16x16x32_bf16 v[98:101], v[154:157], v[170:173], v[98:101]
	v_mfma_f32_16x16x32_bf16 v[86:89], v[146:149], v[178:181], v[86:89]
	v_mfma_f32_16x16x32_bf16 v[82:85], v[154:157], v[178:181], v[82:85]
	v_mfma_f32_16x16x32_bf16 v[70:73], v[146:149], v[210:213], v[70:73]
	v_mfma_f32_16x16x32_bf16 v[66:69], v[154:157], v[210:213], v[66:69]
	v_mfma_f32_16x16x32_bf16 v[118:121], v[150:153], v[166:169], v[118:121]
	v_mfma_f32_16x16x32_bf16 v[114:117], v[158:161], v[166:169], v[114:117]
	v_mfma_f32_16x16x32_bf16 v[102:105], v[150:153], v[174:177], v[102:105]
	v_mfma_f32_16x16x32_bf16 v[98:101], v[158:161], v[174:177], v[98:101]
	v_mfma_f32_16x16x32_bf16 v[86:89], v[150:153], v[182:185], v[86:89]
	v_mfma_f32_16x16x32_bf16 v[82:85], v[158:161], v[182:185], v[82:85]
	v_mfma_f32_16x16x32_bf16 v[70:73], v[150:153], v[214:217], v[70:73]
	v_mfma_f32_16x16x32_bf16 v[66:69], v[158:161], v[214:217], v[66:69]
	s_setprio 0
	s_barrier
	s_add_i32 s10, s52, s19
	v_lshl_add_u64 v[218:219], v[218:219], 0, s[4:5]
	s_mov_b32 m0, s10
	ds_read_b128 v[162:165], v229 offset:49152
	ds_read_b128 v[166:169], v229 offset:50176
	ds_read_b128 v[170:173], v229 offset:51200
	ds_read_b128 v[174:177], v229 offset:52224
	ds_read_b128 v[178:181], v229 offset:53248
	ds_read_b128 v[182:185], v229 offset:54272
	ds_read_b128 v[210:213], v229 offset:55296
	ds_read_b128 v[214:217], v229 offset:56320
	global_load_lds_dwordx4 v[218:219], off
	s_add_i32 m0, s10, 0x2000
	s_add_u32 s8, s8, 0x20080
	v_lshl_add_u64 v[218:219], v[230:231], 0, s[4:5]
	s_addc_u32 s9, s9, 0
	s_add_i32 s10, s53, s19
	global_load_lds_dwordx4 v[218:219], off
	v_lshl_add_u64 v[218:219], s[8:9], 0, v[188:189]
	s_mov_b32 m0, s10
	s_nop 0
	global_load_lds_dwordx4 v[218:219], off
	v_lshl_add_u64 v[218:219], s[8:9], 0, v[200:201]
	s_add_i32 m0, s10, 0x2000
	s_nop 0
	global_load_lds_dwordx4 v[218:219], off
	v_lshl_add_u64 v[218:219], v[232:233], 0, s[4:5]
	s_mov_b32 m0, s28
	s_nop 0
	global_load_lds_dwordx4 v[218:219], off
	v_lshl_add_u64 v[218:219], v[234:235], 0, s[4:5]
	s_mov_b32 m0, s29
	s_nop 0
	global_load_lds_dwordx4 v[218:219], off
	s_waitcnt vmcnt(8)
	s_waitcnt lgkmcnt(0)
	s_barrier
	s_setprio 1
	s_waitcnt lgkmcnt(0)
	v_mfma_f32_16x16x32_bf16 v[62:65], v[130:133], v[162:165], v[62:65]
	v_mfma_f32_16x16x32_bf16 v[58:61], v[138:141], v[162:165], v[58:61]
	v_mfma_f32_16x16x32_bf16 v[46:49], v[130:133], v[170:173], v[46:49]
	v_mfma_f32_16x16x32_bf16 v[42:45], v[138:141], v[170:173], v[42:45]
	v_mfma_f32_16x16x32_bf16 v[30:33], v[130:133], v[178:181], v[30:33]
	v_mfma_f32_16x16x32_bf16 v[26:29], v[138:141], v[178:181], v[26:29]
	v_mfma_f32_16x16x32_bf16 v[14:17], v[130:133], v[210:213], v[14:17]
	v_mfma_f32_16x16x32_bf16 v[10:13], v[138:141], v[210:213], v[10:13]
	v_mfma_f32_16x16x32_bf16 v[62:65], v[134:137], v[166:169], v[62:65]
	v_mfma_f32_16x16x32_bf16 v[58:61], v[142:145], v[166:169], v[58:61]
	v_mfma_f32_16x16x32_bf16 v[46:49], v[134:137], v[174:177], v[46:49]
	v_mfma_f32_16x16x32_bf16 v[42:45], v[142:145], v[174:177], v[42:45]
	v_mfma_f32_16x16x32_bf16 v[30:33], v[134:137], v[182:185], v[30:33]
	v_mfma_f32_16x16x32_bf16 v[26:29], v[142:145], v[182:185], v[26:29]
	v_mfma_f32_16x16x32_bf16 v[14:17], v[134:137], v[214:217], v[14:17]
	v_mfma_f32_16x16x32_bf16 v[10:13], v[142:145], v[214:217], v[10:13]
	v_mfma_f32_16x16x32_bf16 v[54:57], v[146:149], v[162:165], v[54:57]
	v_mfma_f32_16x16x32_bf16 v[50:53], v[154:157], v[162:165], v[50:53]
	v_mfma_f32_16x16x32_bf16 v[38:41], v[146:149], v[170:173], v[38:41]
	v_mfma_f32_16x16x32_bf16 v[34:37], v[154:157], v[170:173], v[34:37]
	v_mfma_f32_16x16x32_bf16 v[22:25], v[146:149], v[178:181], v[22:25]
	v_mfma_f32_16x16x32_bf16 v[18:21], v[154:157], v[178:181], v[18:21]
	v_mfma_f32_16x16x32_bf16 v[6:9], v[146:149], v[210:213], v[6:9]
	v_mfma_f32_16x16x32_bf16 v[2:5], v[154:157], v[210:213], v[2:5]
	v_mfma_f32_16x16x32_bf16 v[54:57], v[150:153], v[166:169], v[54:57]
	v_mfma_f32_16x16x32_bf16 v[50:53], v[158:161], v[166:169], v[50:53]
	v_mfma_f32_16x16x32_bf16 v[38:41], v[150:153], v[174:177], v[38:41]
	v_mfma_f32_16x16x32_bf16 v[34:37], v[158:161], v[174:177], v[34:37]
	v_mfma_f32_16x16x32_bf16 v[22:25], v[150:153], v[182:185], v[22:25]
	v_mfma_f32_16x16x32_bf16 v[18:21], v[158:161], v[182:185], v[18:21]
	v_mfma_f32_16x16x32_bf16 v[6:9], v[150:153], v[214:217], v[6:9]
	v_mfma_f32_16x16x32_bf16 v[2:5], v[158:161], v[214:217], v[2:5]
	s_setprio 0
	s_barrier
	s_add_i32 s51, s51, 2
	s_add_u32 s45, s45, 0x100
	s_addc_u32 s50, s50, 0
	s_add_u32 s0, s0, 0x100
	s_addc_u32 s1, s1, 0
	s_cmp_gt_u32 s51, 5
	s_cbranch_scc0 .LBB0_3096
	v_lshl_add_u32 v212, s36, 8, v226
	v_lshl_or_b32 v210, s35, 8, v228
	v_ashrrev_i32_e32 v213, 31, v212
	v_ashrrev_i32_e32 v211, 31, v210
	v_lshlrev_b64 v[130:131], 10, v[212:213]
	v_lshl_add_u64 v[130:131], v[130:131], 0, v[210:211]
	v_lshlrev_b64 v[130:131], 1, v[130:131]
	v_lshl_add_u64 v[132:133], s[6:7], 0, v[130:131]
	v_lshl_add_u64 v[130:131], s[40:41], 0, v[130:131]
	global_load_dwordx4 v[230:233], v[132:133], off
	global_load_dwordx4 v[234:237], v[130:131], off
	global_load_dwordx4 v[182:185], v[132:133], off offset:256
	global_load_dwordx4 v[178:181], v[130:131], off offset:256
	v_or_b32_e32 v218, 16, v212
	v_ashrrev_i32_e32 v219, 31, v218
	v_lshlrev_b64 v[130:131], 10, v[218:219]
	v_lshl_add_u64 v[130:131], v[130:131], 0, v[210:211]
	v_lshlrev_b64 v[130:131], 1, v[130:131]
	v_lshl_add_u64 v[132:133], s[6:7], 0, v[130:131]
	v_lshl_add_u64 v[130:131], s[40:41], 0, v[130:131]
	global_load_dwordx4 v[174:177], v[132:133], off
	global_load_dwordx4 v[170:173], v[130:131], off
	global_load_dwordx4 v[162:165], v[132:133], off offset:256
	global_load_dwordx4 v[150:153], v[130:131], off offset:256
	v_or_b32_e32 v216, 32, v212
	v_ashrrev_i32_e32 v217, 31, v216
	v_lshlrev_b64 v[130:131], 10, v[216:217]
	v_lshl_add_u64 v[130:131], v[130:131], 0, v[210:211]
	v_lshlrev_b64 v[130:131], 1, v[130:131]
	v_lshl_add_u64 v[132:133], s[6:7], 0, v[130:131]
	v_lshl_add_u64 v[130:131], s[40:41], 0, v[130:131]
	global_load_dwordx4 v[166:169], v[132:133], off
	global_load_dwordx4 v[158:161], v[130:131], off
	global_load_dwordx4 v[146:149], v[132:133], off offset:256
	global_load_dwordx4 v[138:141], v[130:131], off offset:256
	v_or_b32_e32 v214, 48, v212
	v_ashrrev_i32_e32 v215, 31, v214
	v_lshlrev_b64 v[130:131], 10, v[214:215]
	v_lshl_add_u64 v[130:131], v[130:131], 0, v[210:211]
	v_lshlrev_b64 v[130:131], 1, v[130:131]
	v_lshl_add_u64 v[132:133], s[6:7], 0, v[130:131]
	v_lshl_add_u64 v[130:131], s[40:41], 0, v[130:131]
	global_load_dwordx4 v[154:157], v[132:133], off
	global_load_dwordx4 v[142:145], v[130:131], off
	global_load_dwordx4 v[134:137], v[132:133], off offset:256
	s_nop 0
	global_load_dwordx4 v[130:133], v[130:131], off offset:256
	s_and_b64 vcc, exec, s[38:39]
	s_mov_b32 s35, s42
	s_mov_b32 s36, s44
	s_mov_b64 s[0:1], s[48:49]
	s_mov_b64 s[8:9], s[46:47]
	s_waitcnt vmcnt(0)
	v_lshlrev_b32_e32 v238, 16, v230
	v_lshlrev_b32_e32 v242, 16, v234
	v_and_b32_e32 v230, 0xffff0000, v230
	v_fmac_f32_e32 v242, v126, v238
	v_and_b32_e32 v126, 0xffff0000, v234
	v_lshlrev_b32_e32 v239, 16, v231
	v_fmac_f32_e32 v126, v127, v230
	v_lshlrev_b32_e32 v127, 16, v235
	v_and_b32_e32 v231, 0xffff0000, v231
	v_fmac_f32_e32 v127, v128, v239
	v_and_b32_e32 v128, 0xffff0000, v235
	v_lshlrev_b32_e32 v240, 16, v232
	v_fmac_f32_e32 v128, v129, v231
	v_lshlrev_b32_e32 v129, 16, v236
	v_and_b32_e32 v232, 0xffff0000, v232
	v_fmac_f32_e32 v129, v122, v240
	v_and_b32_e32 v122, 0xffff0000, v236
	v_lshlrev_b32_e32 v241, 16, v233
	v_fmac_f32_e32 v122, v123, v232
	v_lshlrev_b32_e32 v123, 16, v237
	v_and_b32_e32 v233, 0xffff0000, v233
	v_fmac_f32_e32 v123, v124, v241
	v_and_b32_e32 v230, 0xffff0000, v237
	v_fmac_f32_e32 v230, v125, v233
	v_cvt_pk_bf16_f32 v124, v242, v126
	v_cvt_pk_bf16_f32 v125, v127, v128
	v_cvt_pk_bf16_f32 v126, v129, v122
	v_cvt_pk_bf16_f32 v127, v123, v230
	v_lshlrev_b64 v[122:123], 11, v[212:213]
	v_lshl_add_u64 v[128:129], s[6:7], 0, v[122:123]
	v_lshlrev_b64 v[122:123], 1, v[210:211]
	v_lshl_add_u64 v[128:129], v[128:129], 0, v[122:123]
	global_store_dwordx4 v[128:129], v[124:127], off
	v_lshlrev_b32_e32 v213, 16, v178
	s_nop 0
	v_lshlrev_b32_e32 v124, 16, v182
	v_and_b32_e32 v125, 0xffff0000, v182
	v_fmac_f32_e32 v213, v118, v124
	v_and_b32_e32 v118, 0xffff0000, v178
	v_lshlrev_b32_e32 v126, 16, v183
	v_fmac_f32_e32 v118, v119, v125
	v_lshlrev_b32_e32 v119, 16, v179
	v_and_b32_e32 v127, 0xffff0000, v183
	v_fmac_f32_e32 v119, v120, v126
	v_and_b32_e32 v120, 0xffff0000, v179
	v_lshlrev_b32_e32 v182, 16, v184
	v_and_b32_e32 v183, 0xffff0000, v184
	v_fmac_f32_e32 v120, v121, v127
	v_lshlrev_b32_e32 v121, 16, v180
	v_and_b32_e32 v124, 0xffff0000, v180
	v_lshlrev_b32_e32 v184, 16, v185
	v_and_b32_e32 v185, 0xffff0000, v185
	v_fmac_f32_e32 v121, v114, v182
	v_fmac_f32_e32 v124, v115, v183
	v_lshlrev_b32_e32 v125, 16, v181
	v_and_b32_e32 v126, 0xffff0000, v181
	v_cvt_pk_bf16_f32 v114, v213, v118
	v_fmac_f32_e32 v125, v116, v184
	v_fmac_f32_e32 v126, v117, v185
	v_cvt_pk_bf16_f32 v115, v119, v120
	v_cvt_pk_bf16_f32 v116, v121, v124
	v_cvt_pk_bf16_f32 v117, v125, v126
	global_store_dwordx4 v[128:129], v[114:117], off offset:256
	v_lshlrev_b32_e32 v124, 16, v170
	v_lshlrev_b32_e32 v118, 16, v176
	v_lshlrev_b32_e32 v114, 16, v174
	v_and_b32_e32 v115, 0xffff0000, v174
	v_fmac_f32_e32 v124, v110, v114
	v_and_b32_e32 v110, 0xffff0000, v170
	v_lshlrev_b32_e32 v116, 16, v175
	v_fmac_f32_e32 v110, v111, v115
	v_lshlrev_b32_e32 v111, 16, v171
	v_and_b32_e32 v117, 0xffff0000, v175
	v_fmac_f32_e32 v111, v112, v116
	v_and_b32_e32 v112, 0xffff0000, v171
	v_and_b32_e32 v119, 0xffff0000, v176
	v_fmac_f32_e32 v112, v113, v117
	v_lshlrev_b32_e32 v113, 16, v172
	v_and_b32_e32 v114, 0xffff0000, v172
	v_fmac_f32_e32 v113, v106, v118
	v_fmac_f32_e32 v114, v107, v119
	v_cvt_pk_bf16_f32 v106, v124, v110
	v_cvt_pk_bf16_f32 v107, v111, v112
	v_lshlrev_b64 v[110:111], 11, v[218:219]
	v_and_b32_e32 v121, 0xffff0000, v177
	v_and_b32_e32 v116, 0xffff0000, v173
	v_lshl_add_u64 v[110:111], s[6:7], 0, v[110:111]
	v_lshlrev_b32_e32 v120, 16, v177
	v_lshlrev_b32_e32 v115, 16, v173
	v_fmac_f32_e32 v116, v109, v121
	v_lshl_add_u64 v[110:111], v[110:111], 0, v[122:123]
	v_fmac_f32_e32 v115, v108, v120
	v_cvt_pk_bf16_f32 v108, v113, v114
	v_cvt_pk_bf16_f32 v109, v115, v116
	global_store_dwordx4 v[110:111], v[106:109], off
	v_lshlrev_b32_e32 v116, 16, v150
	v_lshlrev_b32_e32 v112, 16, v164
	v_lshlrev_b32_e32 v106, 16, v162
	v_and_b32_e32 v107, 0xffff0000, v162
	v_fmac_f32_e32 v116, v102, v106
	v_and_b32_e32 v102, 0xffff0000, v150
	v_lshlrev_b32_e32 v108, 16, v163
	v_fmac_f32_e32 v102, v103, v107
	v_lshlrev_b32_e32 v103, 16, v151
	v_and_b32_e32 v109, 0xffff0000, v163
	v_fmac_f32_e32 v103, v104, v108
	v_and_b32_e32 v104, 0xffff0000, v151
	v_and_b32_e32 v113, 0xffff0000, v164
	v_fmac_f32_e32 v104, v105, v109
	v_lshlrev_b32_e32 v105, 16, v152
	v_and_b32_e32 v106, 0xffff0000, v152
	v_lshlrev_b32_e32 v114, 16, v165
	v_and_b32_e32 v115, 0xffff0000, v165
	v_fmac_f32_e32 v105, v98, v112
	v_fmac_f32_e32 v106, v99, v113
	v_lshlrev_b32_e32 v107, 16, v153
	v_and_b32_e32 v108, 0xffff0000, v153
	v_cvt_pk_bf16_f32 v98, v116, v102
	v_fmac_f32_e32 v107, v100, v114
	v_fmac_f32_e32 v108, v101, v115
	v_cvt_pk_bf16_f32 v99, v103, v104
	v_cvt_pk_bf16_f32 v100, v105, v106
	v_cvt_pk_bf16_f32 v101, v107, v108
	global_store_dwordx4 v[110:111], v[98:101], off offset:256
	v_lshlrev_b32_e32 v106, 16, v158
	v_lshlrev_b32_e32 v102, 16, v168
	v_lshlrev_b32_e32 v98, 16, v166
	v_and_b32_e32 v99, 0xffff0000, v166
	v_fmac_f32_e32 v106, v94, v98
	v_and_b32_e32 v94, 0xffff0000, v158
	v_lshlrev_b32_e32 v100, 16, v167
	v_fmac_f32_e32 v94, v95, v99
	v_lshlrev_b32_e32 v95, 16, v159
	v_and_b32_e32 v101, 0xffff0000, v167
	v_fmac_f32_e32 v95, v96, v100
	v_and_b32_e32 v96, 0xffff0000, v159
	v_and_b32_e32 v103, 0xffff0000, v168
	v_fmac_f32_e32 v96, v97, v101
	v_lshlrev_b32_e32 v97, 16, v160
	v_and_b32_e32 v98, 0xffff0000, v160
	v_fmac_f32_e32 v97, v90, v102
	v_fmac_f32_e32 v98, v91, v103
	v_cvt_pk_bf16_f32 v90, v106, v94
	v_cvt_pk_bf16_f32 v91, v95, v96
	v_lshlrev_b64 v[94:95], 11, v[216:217]
	v_and_b32_e32 v105, 0xffff0000, v169
	v_and_b32_e32 v100, 0xffff0000, v161
	v_lshl_add_u64 v[94:95], s[6:7], 0, v[94:95]
	v_lshlrev_b32_e32 v104, 16, v169
	v_lshlrev_b32_e32 v99, 16, v161
	v_fmac_f32_e32 v100, v93, v105
	v_lshl_add_u64 v[94:95], v[94:95], 0, v[122:123]
	v_fmac_f32_e32 v99, v92, v104
	v_cvt_pk_bf16_f32 v92, v97, v98
	v_cvt_pk_bf16_f32 v93, v99, v100
	global_store_dwordx4 v[94:95], v[90:93], off
	v_lshlrev_b32_e32 v100, 16, v138
	v_lshlrev_b32_e32 v96, 16, v148
	v_lshlrev_b32_e32 v90, 16, v146
	v_and_b32_e32 v91, 0xffff0000, v146
	v_fmac_f32_e32 v100, v86, v90
	v_and_b32_e32 v86, 0xffff0000, v138
	v_lshlrev_b32_e32 v92, 16, v147
	v_fmac_f32_e32 v86, v87, v91
	v_lshlrev_b32_e32 v87, 16, v139
	v_and_b32_e32 v93, 0xffff0000, v147
	v_fmac_f32_e32 v87, v88, v92
	v_and_b32_e32 v88, 0xffff0000, v139
	v_and_b32_e32 v97, 0xffff0000, v148
	v_fmac_f32_e32 v88, v89, v93
	v_lshlrev_b32_e32 v89, 16, v140
	v_and_b32_e32 v90, 0xffff0000, v140
	v_lshlrev_b32_e32 v98, 16, v149
	v_and_b32_e32 v99, 0xffff0000, v149
	v_fmac_f32_e32 v89, v82, v96
	v_fmac_f32_e32 v90, v83, v97
	v_lshlrev_b32_e32 v91, 16, v141
	v_and_b32_e32 v92, 0xffff0000, v141
	v_cvt_pk_bf16_f32 v82, v100, v86
	v_fmac_f32_e32 v91, v84, v98
	v_fmac_f32_e32 v92, v85, v99
	v_cvt_pk_bf16_f32 v83, v87, v88
	v_cvt_pk_bf16_f32 v84, v89, v90
	v_cvt_pk_bf16_f32 v85, v91, v92
	global_store_dwordx4 v[94:95], v[82:85], off offset:256
	v_lshlrev_b32_e32 v90, 16, v142
	v_lshlrev_b32_e32 v86, 16, v156
	v_lshlrev_b32_e32 v82, 16, v154
	v_and_b32_e32 v83, 0xffff0000, v154
	v_fmac_f32_e32 v90, v78, v82
	v_and_b32_e32 v78, 0xffff0000, v142
	v_lshlrev_b32_e32 v84, 16, v155
	v_fmac_f32_e32 v78, v79, v83
	v_lshlrev_b32_e32 v79, 16, v143
	v_and_b32_e32 v85, 0xffff0000, v155
	v_fmac_f32_e32 v79, v80, v84
	v_and_b32_e32 v80, 0xffff0000, v143
	v_and_b32_e32 v87, 0xffff0000, v156
	v_fmac_f32_e32 v80, v81, v85
	v_lshlrev_b32_e32 v81, 16, v144
	v_and_b32_e32 v82, 0xffff0000, v144
	v_fmac_f32_e32 v81, v74, v86
	v_fmac_f32_e32 v82, v75, v87
	v_cvt_pk_bf16_f32 v74, v90, v78
	v_cvt_pk_bf16_f32 v75, v79, v80
	v_lshlrev_b64 v[78:79], 11, v[214:215]
	v_and_b32_e32 v89, 0xffff0000, v157
	v_and_b32_e32 v84, 0xffff0000, v145
	v_lshl_add_u64 v[78:79], s[6:7], 0, v[78:79]
	v_lshlrev_b32_e32 v88, 16, v157
	v_lshlrev_b32_e32 v83, 16, v145
	v_fmac_f32_e32 v84, v77, v89
	v_lshl_add_u64 v[78:79], v[78:79], 0, v[122:123]
	v_fmac_f32_e32 v83, v76, v88
	v_cvt_pk_bf16_f32 v76, v81, v82
	v_cvt_pk_bf16_f32 v77, v83, v84
	global_store_dwordx4 v[78:79], v[74:77], off
	v_lshlrev_b32_e32 v84, 16, v130
	v_lshlrev_b32_e32 v80, 16, v136
	v_lshlrev_b32_e32 v74, 16, v134
	v_and_b32_e32 v75, 0xffff0000, v134
	v_fmac_f32_e32 v84, v70, v74
	v_and_b32_e32 v70, 0xffff0000, v130
	v_lshlrev_b32_e32 v76, 16, v135
	v_fmac_f32_e32 v70, v71, v75
	v_lshlrev_b32_e32 v71, 16, v131
	v_and_b32_e32 v77, 0xffff0000, v135
	v_fmac_f32_e32 v71, v72, v76
	v_and_b32_e32 v72, 0xffff0000, v131
	v_and_b32_e32 v81, 0xffff0000, v136
	v_fmac_f32_e32 v72, v73, v77
	v_lshlrev_b32_e32 v73, 16, v132
	v_and_b32_e32 v74, 0xffff0000, v132
	v_add_u32_e32 v120, 0x80, v212
	v_lshlrev_b32_e32 v82, 16, v137
	v_and_b32_e32 v83, 0xffff0000, v137
	v_fmac_f32_e32 v73, v66, v80
	v_fmac_f32_e32 v74, v67, v81
	v_lshlrev_b32_e32 v75, 16, v133
	v_and_b32_e32 v76, 0xffff0000, v133
	v_cvt_pk_bf16_f32 v66, v84, v70
	v_cvt_pk_bf16_f32 v67, v71, v72
	v_ashrrev_i32_e32 v121, 31, v120
	v_fmac_f32_e32 v75, v68, v82
	v_fmac_f32_e32 v76, v69, v83
	v_cvt_pk_bf16_f32 v68, v73, v74
	v_cvt_pk_bf16_f32 v69, v75, v76
	global_store_dwordx4 v[78:79], v[66:69], off offset:256
	v_add_u32_e32 v136, 0x90, v212
	v_ashrrev_i32_e32 v137, 31, v136
	v_lshlrev_b64 v[66:67], 10, v[120:121]
	v_lshl_add_u64 v[66:67], v[66:67], 0, v[210:211]
	v_lshlrev_b64 v[66:67], 1, v[66:67]
	v_lshl_add_u64 v[68:69], s[6:7], 0, v[66:67]
	v_lshl_add_u64 v[66:67], s[40:41], 0, v[66:67]
	global_load_dwordx4 v[88:91], v[68:69], off
	global_load_dwordx4 v[92:95], v[66:67], off
	global_load_dwordx4 v[96:99], v[68:69], off offset:256
	global_load_dwordx4 v[100:103], v[66:67], off offset:256
	v_lshlrev_b64 v[66:67], 10, v[136:137]
	v_lshl_add_u64 v[66:67], v[66:67], 0, v[210:211]
	v_lshlrev_b64 v[66:67], 1, v[66:67]
	v_lshl_add_u64 v[68:69], s[6:7], 0, v[66:67]
	v_lshl_add_u64 v[66:67], s[40:41], 0, v[66:67]
	global_load_dwordx4 v[104:107], v[68:69], off
	global_load_dwordx4 v[108:111], v[66:67], off
	global_load_dwordx4 v[112:115], v[68:69], off offset:256
	global_load_dwordx4 v[116:119], v[66:67], off offset:256
	v_add_u32_e32 v138, 0xa0, v212
	v_ashrrev_i32_e32 v139, 31, v138
	v_lshlrev_b64 v[66:67], 10, v[138:139]
	v_lshl_add_u64 v[66:67], v[66:67], 0, v[210:211]
	v_lshlrev_b64 v[66:67], 1, v[66:67]
	v_lshl_add_u64 v[68:69], s[6:7], 0, v[66:67]
	v_lshl_add_u64 v[66:67], s[40:41], 0, v[66:67]
	global_load_dwordx4 v[124:127], v[68:69], off
	global_load_dwordx4 v[128:131], v[66:67], off
	global_load_dwordx4 v[132:135], v[68:69], off offset:256
	global_load_dwordx4 v[82:85], v[66:67], off offset:256
	v_add_u32_e32 v86, 0xb0, v212
	v_ashrrev_i32_e32 v87, 31, v86
	v_lshlrev_b64 v[66:67], 10, v[86:87]
	v_lshl_add_u64 v[66:67], v[66:67], 0, v[210:211]
	v_lshlrev_b64 v[66:67], 1, v[66:67]
	v_lshl_add_u64 v[68:69], s[6:7], 0, v[66:67]
	v_lshl_add_u64 v[66:67], s[40:41], 0, v[66:67]
	global_load_dwordx4 v[78:81], v[68:69], off
	global_load_dwordx4 v[74:77], v[66:67], off
	global_load_dwordx4 v[70:73], v[68:69], off offset:256
	s_nop 0
	global_load_dwordx4 v[66:69], v[66:67], off offset:256
	s_waitcnt vmcnt(15)
	v_lshlrev_b32_e32 v140, 16, v88
	s_waitcnt vmcnt(14)
	v_lshlrev_b32_e32 v144, 16, v92
	v_and_b32_e32 v88, 0xffff0000, v88
	v_fmac_f32_e32 v144, v62, v140
	v_and_b32_e32 v62, 0xffff0000, v92
	v_lshlrev_b32_e32 v141, 16, v89
	v_fmac_f32_e32 v62, v63, v88
	v_lshlrev_b32_e32 v63, 16, v93
	v_and_b32_e32 v89, 0xffff0000, v89
	v_fmac_f32_e32 v63, v64, v141
	v_and_b32_e32 v64, 0xffff0000, v93
	v_lshlrev_b32_e32 v142, 16, v90
	v_and_b32_e32 v90, 0xffff0000, v90
	v_fmac_f32_e32 v64, v65, v89
	v_lshlrev_b32_e32 v65, 16, v94
	v_and_b32_e32 v88, 0xffff0000, v94
	v_fmac_f32_e32 v65, v58, v142
	v_fmac_f32_e32 v88, v59, v90
	v_cvt_pk_bf16_f32 v58, v144, v62
	v_cvt_pk_bf16_f32 v59, v63, v64
	v_lshlrev_b64 v[62:63], 11, v[120:121]
	v_lshlrev_b32_e32 v143, 16, v91
	v_and_b32_e32 v91, 0xffff0000, v91
	v_and_b32_e32 v90, 0xffff0000, v95
	v_lshl_add_u64 v[62:63], s[6:7], 0, v[62:63]
	v_lshlrev_b32_e32 v89, 16, v95
	v_fmac_f32_e32 v90, v61, v91
	v_lshl_add_u64 v[62:63], v[62:63], 0, v[122:123]
	v_fmac_f32_e32 v89, v60, v143
	v_cvt_pk_bf16_f32 v60, v65, v88
	v_cvt_pk_bf16_f32 v61, v89, v90
	global_store_dwordx4 v[62:63], v[58:61], off
	s_waitcnt vmcnt(13)
	v_lshlrev_b32_e32 v90, 16, v100
	v_lshlrev_b32_e32 v64, 16, v98
	v_lshlrev_b32_e32 v58, 16, v96
	v_and_b32_e32 v59, 0xffff0000, v96
	v_fmac_f32_e32 v90, v54, v58
	v_and_b32_e32 v54, 0xffff0000, v100
	v_lshlrev_b32_e32 v60, 16, v97
	v_fmac_f32_e32 v54, v55, v59
	v_lshlrev_b32_e32 v55, 16, v101
	v_and_b32_e32 v61, 0xffff0000, v97
	v_fmac_f32_e32 v55, v56, v60
	v_and_b32_e32 v56, 0xffff0000, v101
	v_and_b32_e32 v65, 0xffff0000, v98
	v_fmac_f32_e32 v56, v57, v61
	v_lshlrev_b32_e32 v57, 16, v102
	v_and_b32_e32 v58, 0xffff0000, v102
	v_lshlrev_b32_e32 v88, 16, v99
	v_and_b32_e32 v89, 0xffff0000, v99
	v_fmac_f32_e32 v57, v50, v64
	v_fmac_f32_e32 v58, v51, v65
	v_lshlrev_b32_e32 v59, 16, v103
	v_and_b32_e32 v60, 0xffff0000, v103
	v_cvt_pk_bf16_f32 v50, v90, v54
	v_fmac_f32_e32 v59, v52, v88
	v_fmac_f32_e32 v60, v53, v89
	v_cvt_pk_bf16_f32 v51, v55, v56
	v_cvt_pk_bf16_f32 v52, v57, v58
	v_cvt_pk_bf16_f32 v53, v59, v60
	global_store_dwordx4 v[62:63], v[50:53], off offset:256
	s_waitcnt vmcnt(12)
	v_lshlrev_b32_e32 v58, 16, v108
	v_lshlrev_b32_e32 v54, 16, v106
	v_lshlrev_b32_e32 v50, 16, v104
	v_and_b32_e32 v51, 0xffff0000, v104
	v_fmac_f32_e32 v58, v46, v50
	v_and_b32_e32 v46, 0xffff0000, v108
	v_lshlrev_b32_e32 v52, 16, v105
	v_fmac_f32_e32 v46, v47, v51
	v_lshlrev_b32_e32 v47, 16, v109
	v_and_b32_e32 v53, 0xffff0000, v105
	v_fmac_f32_e32 v47, v48, v52
	v_and_b32_e32 v48, 0xffff0000, v109
	v_and_b32_e32 v55, 0xffff0000, v106
	v_fmac_f32_e32 v48, v49, v53
	v_lshlrev_b32_e32 v49, 16, v110
	v_and_b32_e32 v50, 0xffff0000, v110
	v_fmac_f32_e32 v49, v42, v54
	v_fmac_f32_e32 v50, v43, v55
	v_cvt_pk_bf16_f32 v42, v58, v46
	v_cvt_pk_bf16_f32 v43, v47, v48
	v_lshlrev_b64 v[46:47], 11, v[136:137]
	v_and_b32_e32 v57, 0xffff0000, v107
	v_and_b32_e32 v52, 0xffff0000, v111
	v_lshl_add_u64 v[46:47], s[6:7], 0, v[46:47]
	v_lshlrev_b32_e32 v56, 16, v107
	v_lshlrev_b32_e32 v51, 16, v111
	v_fmac_f32_e32 v52, v45, v57
	v_lshl_add_u64 v[46:47], v[46:47], 0, v[122:123]
	v_fmac_f32_e32 v51, v44, v56
	v_cvt_pk_bf16_f32 v44, v49, v50
	v_cvt_pk_bf16_f32 v45, v51, v52
	global_store_dwordx4 v[46:47], v[42:45], off
	s_waitcnt vmcnt(11)
	v_lshlrev_b32_e32 v52, 16, v116
	v_lshlrev_b32_e32 v48, 16, v114
	v_lshlrev_b32_e32 v42, 16, v112
	v_and_b32_e32 v43, 0xffff0000, v112
	v_fmac_f32_e32 v52, v38, v42
	v_and_b32_e32 v38, 0xffff0000, v116
	v_lshlrev_b32_e32 v44, 16, v113
	v_fmac_f32_e32 v38, v39, v43
	v_lshlrev_b32_e32 v39, 16, v117
	v_and_b32_e32 v45, 0xffff0000, v113
	v_fmac_f32_e32 v39, v40, v44
	v_and_b32_e32 v40, 0xffff0000, v117
	v_and_b32_e32 v49, 0xffff0000, v114
	v_fmac_f32_e32 v40, v41, v45
	v_lshlrev_b32_e32 v41, 16, v118
	v_and_b32_e32 v42, 0xffff0000, v118
	v_lshlrev_b32_e32 v50, 16, v115
	v_and_b32_e32 v51, 0xffff0000, v115
	v_fmac_f32_e32 v41, v34, v48
	v_fmac_f32_e32 v42, v35, v49
	v_lshlrev_b32_e32 v43, 16, v119
	v_and_b32_e32 v44, 0xffff0000, v119
	v_cvt_pk_bf16_f32 v34, v52, v38
	v_fmac_f32_e32 v43, v36, v50
	v_fmac_f32_e32 v44, v37, v51
	v_cvt_pk_bf16_f32 v35, v39, v40
	v_cvt_pk_bf16_f32 v36, v41, v42
	v_cvt_pk_bf16_f32 v37, v43, v44
	global_store_dwordx4 v[46:47], v[34:37], off offset:256
	s_waitcnt vmcnt(10)
	v_lshlrev_b32_e32 v42, 16, v128
	v_lshlrev_b32_e32 v38, 16, v126
	v_lshlrev_b32_e32 v34, 16, v124
	v_and_b32_e32 v35, 0xffff0000, v124
	v_fmac_f32_e32 v42, v30, v34
	v_and_b32_e32 v30, 0xffff0000, v128
	v_lshlrev_b32_e32 v36, 16, v125
	v_fmac_f32_e32 v30, v31, v35
	v_lshlrev_b32_e32 v31, 16, v129
	v_and_b32_e32 v37, 0xffff0000, v125
	v_fmac_f32_e32 v31, v32, v36
	v_and_b32_e32 v32, 0xffff0000, v129
	v_and_b32_e32 v39, 0xffff0000, v126
	v_fmac_f32_e32 v32, v33, v37
	v_lshlrev_b32_e32 v33, 16, v130
	v_and_b32_e32 v34, 0xffff0000, v130
	v_fmac_f32_e32 v33, v26, v38
	v_fmac_f32_e32 v34, v27, v39
	v_cvt_pk_bf16_f32 v26, v42, v30
	v_cvt_pk_bf16_f32 v27, v31, v32
	v_lshlrev_b64 v[30:31], 11, v[138:139]
	v_and_b32_e32 v41, 0xffff0000, v127
	v_and_b32_e32 v36, 0xffff0000, v131
	v_lshl_add_u64 v[30:31], s[6:7], 0, v[30:31]
	v_lshlrev_b32_e32 v40, 16, v127
	v_lshlrev_b32_e32 v35, 16, v131
	v_fmac_f32_e32 v36, v29, v41
	v_lshl_add_u64 v[30:31], v[30:31], 0, v[122:123]
	v_fmac_f32_e32 v35, v28, v40
	v_cvt_pk_bf16_f32 v28, v33, v34
	v_cvt_pk_bf16_f32 v29, v35, v36
	global_store_dwordx4 v[30:31], v[26:29], off
	s_waitcnt vmcnt(9)
	v_lshlrev_b32_e32 v36, 16, v82
	v_lshlrev_b32_e32 v32, 16, v134
	v_lshlrev_b32_e32 v26, 16, v132
	v_and_b32_e32 v27, 0xffff0000, v132
	v_fmac_f32_e32 v36, v22, v26
	v_and_b32_e32 v22, 0xffff0000, v82
	v_lshlrev_b32_e32 v28, 16, v133
	v_fmac_f32_e32 v22, v23, v27
	v_lshlrev_b32_e32 v23, 16, v83
	v_and_b32_e32 v29, 0xffff0000, v133
	v_fmac_f32_e32 v23, v24, v28
	v_and_b32_e32 v24, 0xffff0000, v83
	v_and_b32_e32 v33, 0xffff0000, v134
	v_fmac_f32_e32 v24, v25, v29
	v_lshlrev_b32_e32 v25, 16, v84
	v_and_b32_e32 v26, 0xffff0000, v84
	v_lshlrev_b32_e32 v34, 16, v135
	v_and_b32_e32 v35, 0xffff0000, v135
	v_fmac_f32_e32 v25, v18, v32
	v_fmac_f32_e32 v26, v19, v33
	v_lshlrev_b32_e32 v27, 16, v85
	v_and_b32_e32 v28, 0xffff0000, v85
	v_cvt_pk_bf16_f32 v18, v36, v22
	v_fmac_f32_e32 v27, v20, v34
	v_fmac_f32_e32 v28, v21, v35
	v_cvt_pk_bf16_f32 v19, v23, v24
	v_cvt_pk_bf16_f32 v20, v25, v26
	v_cvt_pk_bf16_f32 v21, v27, v28
	global_store_dwordx4 v[30:31], v[18:21], off offset:256
	s_waitcnt vmcnt(8)
	v_lshlrev_b32_e32 v26, 16, v74
	v_lshlrev_b32_e32 v22, 16, v80
	v_lshlrev_b32_e32 v18, 16, v78
	v_and_b32_e32 v19, 0xffff0000, v78
	v_fmac_f32_e32 v26, v14, v18
	v_and_b32_e32 v14, 0xffff0000, v74
	v_lshlrev_b32_e32 v20, 16, v79
	v_fmac_f32_e32 v14, v15, v19
	v_lshlrev_b32_e32 v15, 16, v75
	v_and_b32_e32 v21, 0xffff0000, v79
	v_fmac_f32_e32 v15, v16, v20
	v_and_b32_e32 v16, 0xffff0000, v75
	v_and_b32_e32 v23, 0xffff0000, v80
	v_fmac_f32_e32 v16, v17, v21
	v_lshlrev_b32_e32 v17, 16, v76
	v_and_b32_e32 v18, 0xffff0000, v76
	v_fmac_f32_e32 v17, v10, v22
	v_fmac_f32_e32 v18, v11, v23
	v_cvt_pk_bf16_f32 v10, v26, v14
	v_cvt_pk_bf16_f32 v11, v15, v16
	v_lshlrev_b64 v[14:15], 11, v[86:87]
	v_and_b32_e32 v25, 0xffff0000, v81
	v_and_b32_e32 v20, 0xffff0000, v77
	v_lshl_add_u64 v[14:15], s[6:7], 0, v[14:15]
	v_lshlrev_b32_e32 v24, 16, v81
	v_lshlrev_b32_e32 v19, 16, v77
	v_fmac_f32_e32 v20, v13, v25
	v_lshl_add_u64 v[14:15], v[14:15], 0, v[122:123]
	v_fmac_f32_e32 v19, v12, v24
	v_cvt_pk_bf16_f32 v12, v17, v18
	v_cvt_pk_bf16_f32 v13, v19, v20
	global_store_dwordx4 v[14:15], v[10:13], off
	s_waitcnt vmcnt(7)
	v_lshlrev_b32_e32 v20, 16, v66
	v_lshlrev_b32_e32 v16, 16, v72
	v_lshlrev_b32_e32 v10, 16, v70
	v_and_b32_e32 v11, 0xffff0000, v70
	v_fmac_f32_e32 v20, v6, v10
	v_and_b32_e32 v6, 0xffff0000, v66
	v_lshlrev_b32_e32 v12, 16, v71
	v_fmac_f32_e32 v6, v7, v11
	v_lshlrev_b32_e32 v7, 16, v67
	v_and_b32_e32 v13, 0xffff0000, v71
	v_fmac_f32_e32 v7, v8, v12
	v_and_b32_e32 v8, 0xffff0000, v67
	v_and_b32_e32 v17, 0xffff0000, v72
	v_lshlrev_b32_e32 v18, 16, v73
	v_and_b32_e32 v19, 0xffff0000, v73
	v_fmac_f32_e32 v8, v9, v13
	v_lshlrev_b32_e32 v9, 16, v68
	v_and_b32_e32 v10, 0xffff0000, v68
	v_lshlrev_b32_e32 v11, 16, v69
	v_and_b32_e32 v12, 0xffff0000, v69
	v_fmac_f32_e32 v9, v2, v16
	v_fmac_f32_e32 v10, v3, v17
	v_fmac_f32_e32 v11, v4, v18
	v_fmac_f32_e32 v12, v5, v19
	v_cvt_pk_bf16_f32 v2, v20, v6
	v_cvt_pk_bf16_f32 v3, v7, v8
	v_cvt_pk_bf16_f32 v4, v9, v10
	v_cvt_pk_bf16_f32 v5, v11, v12
	global_store_dwordx4 v[14:15], v[2:5], off offset:256
	s_cbranch_vccz .LBB0_3089
	s_waitcnt vmcnt(0)
	s_cmpk_gt_u32 s14, 0xff
	s_cbranch_scc1 .LBB0_3100
	s_barrier

.LBB0_3228:
	s_add_u32 s10, s52, s8
	s_addc_u32 s11, s53, s9
	s_add_u32 s10, s10, 0x100
	s_addc_u32 s11, s11, 0
	s_add_u32 s71, s63, s8
	s_addc_u32 s77, s64, s9
	s_add_i32 s78, 0, 0x10000
	s_cmpk_eq_i32 s8, 0x700
	s_cselect_b32 s13, s59, s11
	s_cselect_b32 s12, s65, s10
	s_cselect_b32 s11, s57, s77
	s_cselect_b32 s10, s68, s71
	s_add_i32 s71, 0, 0x14000
	v_add_u32_e32 v154, s78, v140
	v_add_u32_e32 v169, s71, v140
	ds_read_b128 v[142:145], v154
	ds_read_b128 v[146:149], v154 offset:1024
	ds_read_b128 v[150:153], v154 offset:2048
	ds_read_b128 v[154:157], v154 offset:3072
	ds_read_b128 v[158:161], v169
	ds_read_b128 v[162:165], v169 offset:1024
	ds_read_b128 v[170:173], v169 offset:2048
	ds_read_b128 v[174:177], v169 offset:3072
	v_lshl_add_u64 v[230:231], v[138:139], 0, s[8:9]
	s_add_i32 m0, s29, 0xc000
	ds_read_b128 v[178:181], v141
	ds_read_b128 v[182:185], v141 offset:1024
	ds_read_b128 v[200:203], v141 offset:2048
	ds_read_b128 v[204:207], v141 offset:3072
	ds_read_b128 v[208:211], v141 offset:4096
	ds_read_b128 v[212:215], v141 offset:5120
	ds_read_b128 v[216:219], v141 offset:6144
	ds_read_b128 v[226:229], v141 offset:7168
	global_load_lds_dwordx4 v[230:231], off
	v_lshl_add_u64 v[230:231], v[136:137], 0, s[8:9]
	s_add_i32 m0, s29, 0xe000
	s_nop 0
	global_load_lds_dwordx4 v[230:231], off
	s_waitcnt vmcnt(8)
	s_waitcnt lgkmcnt(0)
	s_barrier
	s_setprio 1
	s_waitcnt lgkmcnt(0)
	v_mfma_f32_16x16x32_bf16 v[126:129], v[142:145], v[178:181], v[126:129]
	v_mfma_f32_16x16x32_bf16 v[66:69], v[150:153], v[178:181], v[66:69]
	v_mfma_f32_16x16x32_bf16 v[122:125], v[142:145], v[200:203], v[122:125]
	v_mfma_f32_16x16x32_bf16 v[70:73], v[150:153], v[200:203], v[70:73]
	v_mfma_f32_16x16x32_bf16 v[118:121], v[142:145], v[208:211], v[118:121]
	v_mfma_f32_16x16x32_bf16 v[74:77], v[150:153], v[208:211], v[74:77]
	v_mfma_f32_16x16x32_bf16 v[114:117], v[142:145], v[216:219], v[114:117]
	v_mfma_f32_16x16x32_bf16 v[78:81], v[150:153], v[216:219], v[78:81]
	v_mfma_f32_16x16x32_bf16 v[126:129], v[146:149], v[182:185], v[126:129]
	v_mfma_f32_16x16x32_bf16 v[66:69], v[154:157], v[182:185], v[66:69]
	v_mfma_f32_16x16x32_bf16 v[122:125], v[146:149], v[204:207], v[122:125]
	v_mfma_f32_16x16x32_bf16 v[70:73], v[154:157], v[204:207], v[70:73]
	v_mfma_f32_16x16x32_bf16 v[118:121], v[146:149], v[212:215], v[118:121]
	v_mfma_f32_16x16x32_bf16 v[74:77], v[154:157], v[212:215], v[74:77]
	v_mfma_f32_16x16x32_bf16 v[114:117], v[146:149], v[226:229], v[114:117]
	v_mfma_f32_16x16x32_bf16 v[78:81], v[154:157], v[226:229], v[78:81]
	v_mfma_f32_16x16x32_bf16 v[34:37], v[158:161], v[178:181], v[34:37]
	v_mfma_f32_16x16x32_bf16 v[2:5], v[170:173], v[178:181], v[2:5]
	v_mfma_f32_16x16x32_bf16 v[38:41], v[158:161], v[200:203], v[38:41]
	v_mfma_f32_16x16x32_bf16 v[6:9], v[170:173], v[200:203], v[6:9]
	v_mfma_f32_16x16x32_bf16 v[42:45], v[158:161], v[208:211], v[42:45]
	v_mfma_f32_16x16x32_bf16 v[10:13], v[170:173], v[208:211], v[10:13]
	v_mfma_f32_16x16x32_bf16 v[46:49], v[158:161], v[216:219], v[46:49]
	v_mfma_f32_16x16x32_bf16 v[14:17], v[170:173], v[216:219], v[14:17]
	v_mfma_f32_16x16x32_bf16 v[34:37], v[162:165], v[182:185], v[34:37]
	v_mfma_f32_16x16x32_bf16 v[2:5], v[174:177], v[182:185], v[2:5]
	v_mfma_f32_16x16x32_bf16 v[38:41], v[162:165], v[204:207], v[38:41]
	v_mfma_f32_16x16x32_bf16 v[6:9], v[174:177], v[204:207], v[6:9]
	v_mfma_f32_16x16x32_bf16 v[42:45], v[162:165], v[212:215], v[42:45]
	v_mfma_f32_16x16x32_bf16 v[10:13], v[174:177], v[212:215], v[10:13]
	v_mfma_f32_16x16x32_bf16 v[46:49], v[162:165], v[226:229], v[46:49]
	v_mfma_f32_16x16x32_bf16 v[14:17], v[174:177], v[226:229], v[14:17]
	s_setprio 0
	s_barrier
	s_add_i32 s77, s78, s19
	v_lshl_add_u64 v[230:231], s[10:11], 0, v[188:189]
	s_mov_b32 m0, s77
	ds_read_b128 v[178:181], v141 offset:16384
	ds_read_b128 v[182:185], v141 offset:17408
	ds_read_b128 v[200:203], v141 offset:18432
	ds_read_b128 v[204:207], v141 offset:19456
	ds_read_b128 v[208:211], v141 offset:20480
	ds_read_b128 v[212:215], v141 offset:21504
	ds_read_b128 v[216:219], v141 offset:22528
	ds_read_b128 v[226:229], v141 offset:23552
	global_load_lds_dwordx4 v[230:231], off
	s_add_i32 m0, s77, 0x2000
	s_add_u32 s78, s10, 0x40000
	v_lshl_add_u64 v[232:233], s[10:11], 0, v[130:131]
	s_addc_u32 s79, s11, 0
	s_add_i32 s71, s71, s19
	global_load_lds_dwordx4 v[232:233], off
	v_lshl_add_u64 v[234:235], s[78:79], 0, v[188:189]
	s_mov_b32 m0, s71
	v_lshl_add_u64 v[236:237], s[12:13], 0, v[130:131]
	global_load_lds_dwordx4 v[234:235], off
	v_lshl_add_u64 v[234:235], s[78:79], 0, v[130:131]
	s_add_i32 m0, s71, 0x2000
	s_nop 0
	global_load_lds_dwordx4 v[234:235], off
	v_lshl_add_u64 v[234:235], s[12:13], 0, v[188:189]
	s_mov_b32 m0, s29
	s_nop 0
	global_load_lds_dwordx4 v[234:235], off
	s_mov_b32 m0, s34
	s_nop 0
	global_load_lds_dwordx4 v[236:237], off
	s_waitcnt vmcnt(8)
	s_waitcnt lgkmcnt(0)
	s_barrier
	s_setprio 1
	s_waitcnt lgkmcnt(0)
	v_mfma_f32_16x16x32_bf16 v[106:109], v[142:145], v[178:181], v[106:109]
	v_mfma_f32_16x16x32_bf16 v[82:85], v[150:153], v[178:181], v[82:85]
	v_mfma_f32_16x16x32_bf16 v[110:113], v[142:145], v[200:203], v[110:113]
	v_mfma_f32_16x16x32_bf16 v[86:89], v[150:153], v[200:203], v[86:89]
	v_mfma_f32_16x16x32_bf16 v[102:105], v[142:145], v[208:211], v[102:105]
	v_mfma_f32_16x16x32_bf16 v[90:93], v[150:153], v[208:211], v[90:93]
	v_mfma_f32_16x16x32_bf16 v[98:101], v[142:145], v[216:219], v[98:101]
	v_mfma_f32_16x16x32_bf16 v[94:97], v[150:153], v[216:219], v[94:97]
	v_mfma_f32_16x16x32_bf16 v[106:109], v[146:149], v[182:185], v[106:109]
	v_mfma_f32_16x16x32_bf16 v[82:85], v[154:157], v[182:185], v[82:85]
	v_mfma_f32_16x16x32_bf16 v[110:113], v[146:149], v[204:207], v[110:113]
	v_mfma_f32_16x16x32_bf16 v[86:89], v[154:157], v[204:207], v[86:89]
	v_mfma_f32_16x16x32_bf16 v[102:105], v[146:149], v[212:215], v[102:105]
	v_mfma_f32_16x16x32_bf16 v[90:93], v[154:157], v[212:215], v[90:93]
	v_mfma_f32_16x16x32_bf16 v[98:101], v[146:149], v[226:229], v[98:101]
	v_mfma_f32_16x16x32_bf16 v[94:97], v[154:157], v[226:229], v[94:97]
	v_mfma_f32_16x16x32_bf16 v[50:53], v[158:161], v[178:181], v[50:53]
	v_mfma_f32_16x16x32_bf16 v[18:21], v[170:173], v[178:181], v[18:21]
	v_mfma_f32_16x16x32_bf16 v[54:57], v[158:161], v[200:203], v[54:57]
	v_mfma_f32_16x16x32_bf16 v[22:25], v[170:173], v[200:203], v[22:25]
	v_mfma_f32_16x16x32_bf16 v[58:61], v[158:161], v[208:211], v[58:61]
	v_mfma_f32_16x16x32_bf16 v[26:29], v[170:173], v[208:211], v[26:29]
	v_mfma_f32_16x16x32_bf16 v[62:65], v[158:161], v[216:219], v[62:65]
	v_mfma_f32_16x16x32_bf16 v[30:33], v[170:173], v[216:219], v[30:33]
	v_mfma_f32_16x16x32_bf16 v[50:53], v[162:165], v[182:185], v[50:53]
	v_mfma_f32_16x16x32_bf16 v[18:21], v[174:177], v[182:185], v[18:21]
	v_mfma_f32_16x16x32_bf16 v[54:57], v[162:165], v[204:207], v[54:57]
	v_mfma_f32_16x16x32_bf16 v[22:25], v[174:177], v[204:207], v[22:25]
	v_mfma_f32_16x16x32_bf16 v[58:61], v[162:165], v[212:215], v[58:61]
	v_mfma_f32_16x16x32_bf16 v[26:29], v[174:177], v[212:215], v[26:29]
	v_mfma_f32_16x16x32_bf16 v[62:65], v[162:165], v[226:229], v[62:65]
	v_mfma_f32_16x16x32_bf16 v[30:33], v[174:177], v[226:229], v[30:33]
	s_setprio 0
	s_barrier
	s_add_i32 s71, 0, 0x18000
	s_add_i32 s77, 0, 0x1c000
	v_add_u32_e32 v154, s71, v140
	v_add_u32_e32 v169, s77, v140
	ds_read_b128 v[142:145], v154
	ds_read_b128 v[146:149], v154 offset:1024
	ds_read_b128 v[150:153], v154 offset:2048
	ds_read_b128 v[154:157], v154 offset:3072
	ds_read_b128 v[158:161], v169
	ds_read_b128 v[162:165], v169 offset:1024
	ds_read_b128 v[170:173], v169 offset:2048
	ds_read_b128 v[174:177], v169 offset:3072
	s_add_u32 s12, s12, 0x40000
	s_addc_u32 s13, s13, 0
	s_mov_b32 m0, s35
	v_lshl_add_u64 v[238:239], s[12:13], 0, v[188:189]
	ds_read_b128 v[178:181], v141 offset:32768
	ds_read_b128 v[182:185], v141 offset:33792
	ds_read_b128 v[200:203], v141 offset:34816
	ds_read_b128 v[204:207], v141 offset:35840
	ds_read_b128 v[208:211], v141 offset:36864
	ds_read_b128 v[212:215], v141 offset:37888
	ds_read_b128 v[216:219], v141 offset:38912
	ds_read_b128 v[226:229], v141 offset:39936
	global_load_lds_dwordx4 v[238:239], off
	v_lshl_add_u64 v[238:239], s[12:13], 0, v[130:131]
	s_mov_b32 m0, s36
	s_nop 0
	global_load_lds_dwordx4 v[238:239], off
	s_waitcnt vmcnt(8)
	s_waitcnt lgkmcnt(0)
	s_barrier
	s_setprio 1
	s_waitcnt lgkmcnt(0)
	v_mfma_f32_16x16x32_bf16 v[126:129], v[142:145], v[178:181], v[126:129]
	v_mfma_f32_16x16x32_bf16 v[66:69], v[150:153], v[178:181], v[66:69]
	v_mfma_f32_16x16x32_bf16 v[122:125], v[142:145], v[200:203], v[122:125]
	v_mfma_f32_16x16x32_bf16 v[70:73], v[150:153], v[200:203], v[70:73]
	v_mfma_f32_16x16x32_bf16 v[118:121], v[142:145], v[208:211], v[118:121]
	v_mfma_f32_16x16x32_bf16 v[74:77], v[150:153], v[208:211], v[74:77]
	v_mfma_f32_16x16x32_bf16 v[114:117], v[142:145], v[216:219], v[114:117]
	v_mfma_f32_16x16x32_bf16 v[78:81], v[150:153], v[216:219], v[78:81]
	v_mfma_f32_16x16x32_bf16 v[126:129], v[146:149], v[182:185], v[126:129]
	v_mfma_f32_16x16x32_bf16 v[66:69], v[154:157], v[182:185], v[66:69]
	v_mfma_f32_16x16x32_bf16 v[122:125], v[146:149], v[204:207], v[122:125]
	v_mfma_f32_16x16x32_bf16 v[70:73], v[154:157], v[204:207], v[70:73]
	v_mfma_f32_16x16x32_bf16 v[118:121], v[146:149], v[212:215], v[118:121]
	v_mfma_f32_16x16x32_bf16 v[74:77], v[154:157], v[212:215], v[74:77]
	v_mfma_f32_16x16x32_bf16 v[114:117], v[146:149], v[226:229], v[114:117]
	v_mfma_f32_16x16x32_bf16 v[78:81], v[154:157], v[226:229], v[78:81]
	v_mfma_f32_16x16x32_bf16 v[34:37], v[158:161], v[178:181], v[34:37]
	v_mfma_f32_16x16x32_bf16 v[2:5], v[170:173], v[178:181], v[2:5]
	v_mfma_f32_16x16x32_bf16 v[38:41], v[158:161], v[200:203], v[38:41]
	v_mfma_f32_16x16x32_bf16 v[6:9], v[170:173], v[200:203], v[6:9]
	v_mfma_f32_16x16x32_bf16 v[42:45], v[158:161], v[208:211], v[42:45]
	v_mfma_f32_16x16x32_bf16 v[10:13], v[170:173], v[208:211], v[10:13]
	v_mfma_f32_16x16x32_bf16 v[46:49], v[158:161], v[216:219], v[46:49]
	v_mfma_f32_16x16x32_bf16 v[14:17], v[170:173], v[216:219], v[14:17]
	v_mfma_f32_16x16x32_bf16 v[34:37], v[162:165], v[182:185], v[34:37]
	v_mfma_f32_16x16x32_bf16 v[2:5], v[174:177], v[182:185], v[2:5]
	v_mfma_f32_16x16x32_bf16 v[38:41], v[162:165], v[204:207], v[38:41]
	v_mfma_f32_16x16x32_bf16 v[6:9], v[174:177], v[204:207], v[6:9]
	v_mfma_f32_16x16x32_bf16 v[42:45], v[162:165], v[212:215], v[42:45]
	v_mfma_f32_16x16x32_bf16 v[10:13], v[174:177], v[212:215], v[10:13]
	v_mfma_f32_16x16x32_bf16 v[46:49], v[162:165], v[226:229], v[46:49]
	v_mfma_f32_16x16x32_bf16 v[14:17], v[174:177], v[226:229], v[14:17]
	s_setprio 0
	s_barrier
	s_add_i32 s12, s71, s19
	v_lshl_add_u64 v[230:231], v[230:231], 0, s[4:5]
	s_mov_b32 m0, s12
	ds_read_b128 v[178:181], v141 offset:49152
	ds_read_b128 v[182:185], v141 offset:50176
	ds_read_b128 v[200:203], v141 offset:51200
	ds_read_b128 v[204:207], v141 offset:52224
	ds_read_b128 v[208:211], v141 offset:53248
	ds_read_b128 v[212:215], v141 offset:54272
	ds_read_b128 v[216:219], v141 offset:55296
	ds_read_b128 v[226:229], v141 offset:56320
	global_load_lds_dwordx4 v[230:231], off
	s_add_i32 m0, s12, 0x2000
	s_add_u32 s10, s10, 0x40080
	v_lshl_add_u64 v[230:231], v[232:233], 0, s[4:5]
	s_addc_u32 s11, s11, 0
	s_add_i32 s12, s77, s19
	global_load_lds_dwordx4 v[230:231], off
	v_lshl_add_u64 v[230:231], s[10:11], 0, v[188:189]
	s_mov_b32 m0, s12
	s_nop 0
	global_load_lds_dwordx4 v[230:231], off
	v_lshl_add_u64 v[230:231], s[10:11], 0, v[130:131]
	s_add_i32 m0, s12, 0x2000
	s_nop 0
	global_load_lds_dwordx4 v[230:231], off
	v_lshl_add_u64 v[230:231], v[234:235], 0, s[4:5]
	s_mov_b32 m0, s37
	s_nop 0
	global_load_lds_dwordx4 v[230:231], off
	v_lshl_add_u64 v[230:231], v[236:237], 0, s[4:5]
	s_mov_b32 m0, s43
	s_nop 0
	global_load_lds_dwordx4 v[230:231], off
	s_waitcnt vmcnt(8)
	s_waitcnt lgkmcnt(0)
	s_barrier
	s_setprio 1
	s_waitcnt lgkmcnt(0)
	v_mfma_f32_16x16x32_bf16 v[106:109], v[142:145], v[178:181], v[106:109]
	v_mfma_f32_16x16x32_bf16 v[82:85], v[150:153], v[178:181], v[82:85]
	v_mfma_f32_16x16x32_bf16 v[110:113], v[142:145], v[200:203], v[110:113]
	v_mfma_f32_16x16x32_bf16 v[86:89], v[150:153], v[200:203], v[86:89]
	v_mfma_f32_16x16x32_bf16 v[102:105], v[142:145], v[208:211], v[102:105]
	v_mfma_f32_16x16x32_bf16 v[90:93], v[150:153], v[208:211], v[90:93]
	v_mfma_f32_16x16x32_bf16 v[98:101], v[142:145], v[216:219], v[98:101]
	v_mfma_f32_16x16x32_bf16 v[94:97], v[150:153], v[216:219], v[94:97]
	v_mfma_f32_16x16x32_bf16 v[106:109], v[146:149], v[182:185], v[106:109]
	v_mfma_f32_16x16x32_bf16 v[82:85], v[154:157], v[182:185], v[82:85]
	v_mfma_f32_16x16x32_bf16 v[110:113], v[146:149], v[204:207], v[110:113]
	v_mfma_f32_16x16x32_bf16 v[86:89], v[154:157], v[204:207], v[86:89]
	v_mfma_f32_16x16x32_bf16 v[102:105], v[146:149], v[212:215], v[102:105]
	v_mfma_f32_16x16x32_bf16 v[90:93], v[154:157], v[212:215], v[90:93]
	v_mfma_f32_16x16x32_bf16 v[98:101], v[146:149], v[226:229], v[98:101]
	v_mfma_f32_16x16x32_bf16 v[94:97], v[154:157], v[226:229], v[94:97]
	v_mfma_f32_16x16x32_bf16 v[50:53], v[158:161], v[178:181], v[50:53]
	v_mfma_f32_16x16x32_bf16 v[18:21], v[170:173], v[178:181], v[18:21]
	v_mfma_f32_16x16x32_bf16 v[54:57], v[158:161], v[200:203], v[54:57]
	v_mfma_f32_16x16x32_bf16 v[22:25], v[170:173], v[200:203], v[22:25]
	v_mfma_f32_16x16x32_bf16 v[58:61], v[158:161], v[208:211], v[58:61]
	v_mfma_f32_16x16x32_bf16 v[26:29], v[170:173], v[208:211], v[26:29]
	v_mfma_f32_16x16x32_bf16 v[62:65], v[158:161], v[216:219], v[62:65]
	v_mfma_f32_16x16x32_bf16 v[30:33], v[170:173], v[216:219], v[30:33]
	v_mfma_f32_16x16x32_bf16 v[50:53], v[162:165], v[182:185], v[50:53]
	v_mfma_f32_16x16x32_bf16 v[18:21], v[174:177], v[182:185], v[18:21]
	v_mfma_f32_16x16x32_bf16 v[54:57], v[162:165], v[204:207], v[54:57]
	v_mfma_f32_16x16x32_bf16 v[22:25], v[174:177], v[204:207], v[22:25]
	v_mfma_f32_16x16x32_bf16 v[58:61], v[162:165], v[212:215], v[58:61]
	v_mfma_f32_16x16x32_bf16 v[26:29], v[174:177], v[212:215], v[26:29]
	v_mfma_f32_16x16x32_bf16 v[62:65], v[162:165], v[226:229], v[62:65]
	v_mfma_f32_16x16x32_bf16 v[30:33], v[174:177], v[226:229], v[30:33]
	s_setprio 0
	s_barrier
	s_add_i32 s70, s70, 2
	s_add_u32 s8, s8, 0x100
	s_addc_u32 s9, s9, 0
	s_cmp_gt_u32 s70, 13
	s_cbranch_scc0 .LBB0_3228
	s_add_u32 s8, s63, 0xffffff00
	s_addc_u32 s9, s64, -1
	s_andn2_b64 vcc, exec, s[40:41]
	s_cbranch_vccnz .LBB0_3219
	v_mov_b32_e32 v30, 0
	s_mov_b32 s42, s56
	s_mov_b32 s16, s58
	s_mov_b64 s[52:53], s[0:1]
	s_mov_b32 s55, s62
	v_mov_b32_e32 v31, v30
	v_mov_b32_e32 v32, v30
	v_mov_b32_e32 v33, v30
	v_mov_b32_e32 v62, v30
	v_mov_b32_e32 v63, v30
	v_mov_b32_e32 v64, v30
	v_mov_b32_e32 v65, v30
	v_mov_b32_e32 v26, v30
	v_mov_b32_e32 v27, v30
	v_mov_b32_e32 v28, v30
	v_mov_b32_e32 v29, v30
	v_mov_b32_e32 v58, v30
	v_mov_b32_e32 v59, v30
	v_mov_b32_e32 v60, v30
	v_mov_b32_e32 v61, v30
	v_mov_b32_e32 v22, v30
	v_mov_b32_e32 v23, v30
	v_mov_b32_e32 v24, v30
	v_mov_b32_e32 v25, v30
	v_mov_b32_e32 v54, v30
	v_mov_b32_e32 v55, v30
	v_mov_b32_e32 v56, v30
	v_mov_b32_e32 v57, v30
	v_mov_b32_e32 v18, v30
	v_mov_b32_e32 v19, v30
	v_mov_b32_e32 v20, v30
	v_mov_b32_e32 v21, v30
	v_mov_b32_e32 v50, v30
	v_mov_b32_e32 v51, v30
	v_mov_b32_e32 v52, v30
	v_mov_b32_e32 v53, v30
	v_mov_b32_e32 v94, v30
	v_mov_b32_e32 v95, v30
	v_mov_b32_e32 v96, v30
	v_mov_b32_e32 v97, v30
	v_mov_b32_e32 v98, v30
	v_mov_b32_e32 v99, v30
	v_mov_b32_e32 v100, v30
	v_mov_b32_e32 v101, v30
	v_mov_b32_e32 v90, v30
	v_mov_b32_e32 v91, v30
	v_mov_b32_e32 v92, v30
	v_mov_b32_e32 v93, v30
	v_mov_b32_e32 v102, v30
	v_mov_b32_e32 v103, v30
	v_mov_b32_e32 v104, v30
	v_mov_b32_e32 v105, v30
	v_mov_b32_e32 v86, v30
	v_mov_b32_e32 v87, v30
	v_mov_b32_e32 v88, v30
	v_mov_b32_e32 v89, v30
	v_mov_b32_e32 v110, v30
	v_mov_b32_e32 v111, v30
	v_mov_b32_e32 v112, v30
	v_mov_b32_e32 v113, v30
	v_mov_b32_e32 v82, v30
	v_mov_b32_e32 v83, v30
	v_mov_b32_e32 v84, v30
	v_mov_b32_e32 v85, v30
	v_mov_b32_e32 v106, v30
	v_mov_b32_e32 v107, v30
	v_mov_b32_e32 v108, v30
	v_mov_b32_e32 v109, v30
	v_mov_b32_e32 v14, v30
	v_mov_b32_e32 v15, v30
	v_mov_b32_e32 v16, v30
	v_mov_b32_e32 v17, v30
	v_mov_b32_e32 v46, v30
	v_mov_b32_e32 v47, v30
	v_mov_b32_e32 v48, v30
	v_mov_b32_e32 v49, v30
	v_mov_b32_e32 v10, v30
	v_mov_b32_e32 v11, v30
	v_mov_b32_e32 v12, v30
	v_mov_b32_e32 v13, v30
	v_mov_b32_e32 v42, v30
	v_mov_b32_e32 v43, v30
	v_mov_b32_e32 v44, v30
	v_mov_b32_e32 v45, v30
	v_mov_b32_e32 v6, v30
	v_mov_b32_e32 v7, v30
	v_mov_b32_e32 v8, v30
	v_mov_b32_e32 v9, v30
	v_mov_b32_e32 v38, v30
	v_mov_b32_e32 v39, v30
	v_mov_b32_e32 v40, v30
	v_mov_b32_e32 v41, v30
	v_mov_b32_e32 v2, v30
	v_mov_b32_e32 v3, v30
	v_mov_b32_e32 v4, v30
	v_mov_b32_e32 v5, v30
	v_mov_b32_e32 v34, v30
	v_mov_b32_e32 v35, v30
	v_mov_b32_e32 v36, v30
	v_mov_b32_e32 v37, v30
	v_mov_b32_e32 v78, v30
	v_mov_b32_e32 v79, v30
	v_mov_b32_e32 v80, v30
	v_mov_b32_e32 v81, v30
	v_mov_b32_e32 v114, v30
	v_mov_b32_e32 v115, v30
	v_mov_b32_e32 v116, v30
	v_mov_b32_e32 v117, v30
	v_mov_b32_e32 v74, v30
	v_mov_b32_e32 v75, v30
	v_mov_b32_e32 v76, v30
	v_mov_b32_e32 v77, v30
	v_mov_b32_e32 v118, v30
	v_mov_b32_e32 v119, v30
	v_mov_b32_e32 v120, v30
	v_mov_b32_e32 v121, v30
	v_mov_b32_e32 v70, v30
	v_mov_b32_e32 v71, v30
	v_mov_b32_e32 v72, v30
	v_mov_b32_e32 v73, v30
	v_mov_b32_e32 v122, v30
	v_mov_b32_e32 v123, v30
	v_mov_b32_e32 v124, v30
	v_mov_b32_e32 v125, v30
	v_mov_b32_e32 v66, v30
	v_mov_b32_e32 v67, v30
	v_mov_b32_e32 v68, v30
	v_mov_b32_e32 v69, v30
	v_mov_b32_e32 v126, v30
	v_mov_b32_e32 v127, v30
	v_mov_b32_e32 v128, v30
	v_mov_b32_e32 v129, v30
	s_mov_b64 s[70:71], 0x20000
	s_andn2_b64 vcc, exec, s[38:39]
	s_cbranch_vccnz .LBB0_3220
